# speedup vs baseline: 1.0504x; 1.0073x over previous
;   #define WAIT_V(n) asm volatile("s_waitcnt vmcnt(" #n ")":::"memory")
;   #define BAR __builtin_amdgcn_s_barrier()
; template <class Pre, class Fin, class Epi> ...
;     ...
;   if(wr==1)BAR;
;   if (pf && pfE == 16)      { WAIT_V(26); BAR; WAIT_V(22); BAR; }
;   else if (pf && pfE == 32) { WAIT_V(42); BAR; WAIT_V(38); BAR; }
;   else                      { WAIT_V(10); BAR; WAIT_V(6); BAR; }
.LBB0_227:
	s_or_b64 exec, exec, s[28:29]
	s_cmp_lg_u32 s30, 16
	s_cselect_b64 s[60:61], -1, 0
	s_or_b64 s[60:61], s[6:7], s[60:61]
	s_mov_b64 s[28:29], -1
	s_and_b64 vcc, exec, s[60:61]
	s_cbranch_vccz .LBB0_233
	s_cmp_lg_u32 s30, 32
	s_cselect_b64 s[60:61], -1, 0
	s_or_b64 s[6:7], s[6:7], s[60:61]
	s_and_b64 vcc, exec, s[6:7]
	s_cbranch_vccz .LBB0_230
	s_waitcnt vmcnt(10)
	s_barrier
	s_waitcnt vmcnt(6)
	s_barrier
	s_mov_b64 s[28:29], 0
.LBB0_230:
	s_andn2_b64 vcc, exec, s[28:29]
	s_cbranch_vccnz .LBB0_232
	s_waitcnt vmcnt(26)
	s_barrier
	s_waitcnt vmcnt(22)
	s_barrier
.LBB0_232:
	s_mov_b64 s[28:29], 0
.LBB0_233:
	s_andn2_b64 vcc, exec, s[28:29]
	s_cbranch_vccnz .LBB0_235
	s_waitcnt vmcnt(18)
	s_barrier
	s_waitcnt vmcnt(14)
	s_barrier

; #define p_rope W_(float2, OFF_ROPE)
; __device__ __forceinline__ u32x2 pack4(float a, float b, float c, float d) { return u32x2{cvtpk(a, b), cvtpk(c, d)}; }
; __device__ __forceinline__ u32x2 pack4(const f32x4& v) { return u32x2{cvtpk(v[0], v[1]), cvtpk(v[2], v[3])}; }
; #define SBAR() __builtin_amdgcn_sched_barrier(0)
; __global__ void __launch_bounds__(512) fwd_megakernel(Params p) {
;     ...
;           if (wc == 0) {
;             #pragma unroll
;             for (int ai = 0; ai < 2; ++ai) { SBAR();
;               f32x4 csa[4], csb[4];
;               #pragma unroll
;               for (int m = 0; m < 4; ++m) {
;                 int pos = (brow + ai * 128 + wr * 64 + m * 16 + fr) % LTOK;
;                 csa[m] = *reinterpret_cast<const f32x4*>(p_rope + pos * 16 + fq * 4); csb[m] = *reinterpret_cast<const f32x4*>(p_rope + pos * 16 + fq * 4 + 2);
;               }
;               SBAR();
;               #pragma unroll
;               for (int m = 0; m < 4; ++m) {
;                 int lrow = ai * 128 + wr * 64 + m * 16 + fr, row = brow + lrow; float rs = xl[lrow];
;                 int b = row / LTOK, pos = row - b * LTOK;
;                 const float cs_c[4] = {csa[m][0], csa[m][2], csb[m][0], csb[m][2]}, cs_s[4] = {csa[m][1], csa[m][3], csb[m][1], csb[m][3]};
;                 float o1[4], o2[4];
;                 #pragma unroll
;                 for (int j = 0; j < 4; ++j) { float x1 = acc[ai][0][m][0][j] * rs, x2 = acc[ai][0][m][1][j] * rs;
;                   o1[j] = x1 * cs_c[j] - x2 * cs_s[j]; o2[j] = x2 * cs_c[j] + x1 * cs_s[j]; }
;                 const u32x2 w1 = pack4(o1[0], o1[1], o1[2], o1[3]), w2 = pack4(o2[0], o2[1], o2[2], o2[3]);
;                 int key = pos < NMETA ? SEQ + pos : pos - NMETA;
;                 bf16* kd = p_Kb + ((long)(b * NH) * KPAD + key) * DQK + 64 + fq * 4;
;                 #pragma unroll
;                 for (int h = 0; h < NH; ++h) { *reinterpret_cast<u32x2*>(kd + (long)h * KPAD * DQK) = w1; *reinterpret_cast<u32x2*>(kd + (long)h * KPAD * DQK + 16) = w2; }
.LBB0_278:
	s_waitcnt lgkmcnt(0)
	v_mov_b32_e32 v128, v252
	s_cmp_lt_i32 s76, 4
	s_barrier
	s_cselect_b64 s[2:3], -1, 0
	v_ashrrev_i32_e32 v152, 8, v128
	v_bfe_u32 v151, v128, 6, 2
	v_and_b32_e32 v153, 15, v128
	v_bfe_u32 v150, v128, 4, 2
	s_cmp_gt_i32 s76, 3
	s_mov_b64 s[0:1], -1
	s_cbranch_scc0 .LBB0_304
	s_cmp_gt_u32 s76, 5
	s_cbranch_scc0 .LBB0_283
	v_cmp_eq_u32_e32 vcc, 0, v151
	s_and_saveexec_b64 s[0:1], vcc
	s_cbranch_execz .LBB0_282
	s_waitcnt lgkmcnt(0)
	v_lshl_or_b32 v176, v152, 6, v153
	v_add_u32_e32 v155, s80, v176
	v_mul_hi_i32 v128, v155, s16
	v_lshrrev_b32_e32 v129, 31, v128
	v_ashrrev_i32_e32 v128, 7, v128
	v_add_u32_e32 v177, v128, v129
	v_mul_i32_i24_e32 v128, 0x810, v177
	v_sub_u32_e32 v128, v155, v128
	v_readlane_b32 s4, v254, 29
	v_lshlrev_b32_e32 v128, 4, v128
	v_lshlrev_b32_e32 v194, 5, v150
	v_readlane_b32 s5, v254, 30
	v_ashrrev_i32_e32 v129, 31, v128
	v_lshl_add_u64 v[146:147], s[34:35], 0, v[194:195]
	v_lshl_add_u64 v[148:149], s[4:5], 0, v[194:195]
	v_lshlrev_b64 v[128:129], 3, v[128:129]
	v_lshl_add_u64 v[130:131], v[148:149], 0, v[128:129]
	v_lshl_add_u64 v[128:129], v[146:147], 0, v[128:129]
	v_add_co_u32_e32 v128, vcc, s21, v128
	s_nop 1
	v_addc_co_u32_e32 v129, vcc, 0, v129, vcc
	global_load_dwordx4 v[156:159], v[130:131], off
	global_load_dwordx4 v[160:163], v[128:129], off offset:1040
	v_or_b32_e32 v128, 16, v155
	v_mul_hi_i32 v129, v128, s16
	v_lshrrev_b32_e32 v130, 31, v129
	v_ashrrev_i32_e32 v129, 7, v129
	v_add_u32_e32 v129, v129, v130
	v_mul_lo_u32 v129, v129, s20
	v_sub_u32_e32 v128, v128, v129
	v_lshlrev_b32_e32 v128, 4, v128
	v_ashrrev_i32_e32 v129, 31, v128
	v_lshlrev_b64 v[128:129], 3, v[128:129]
	v_lshl_add_u64 v[130:131], v[148:149], 0, v[128:129]
	v_lshl_add_u64 v[128:129], v[146:147], 0, v[128:129]
	v_add_co_u32_e32 v128, vcc, s21, v128
	s_nop 1
	v_addc_co_u32_e32 v129, vcc, 0, v129, vcc
	global_load_dwordx4 v[164:167], v[130:131], off
	global_load_dwordx4 v[168:171], v[128:129], off offset:1040
	v_or_b32_e32 v128, 32, v155
	v_mul_hi_i32 v129, v128, s16
	v_lshrrev_b32_e32 v130, 31, v129
	v_ashrrev_i32_e32 v129, 7, v129
	v_add_u32_e32 v129, v129, v130
	v_mul_lo_u32 v129, v129, s20
	v_sub_u32_e32 v128, v128, v129
	v_lshlrev_b32_e32 v128, 4, v128
	v_ashrrev_i32_e32 v129, 31, v128
	v_lshlrev_b64 v[128:129], 3, v[128:129]
	v_lshl_add_u64 v[130:131], v[148:149], 0, v[128:129]
	v_lshl_add_u64 v[128:129], v[146:147], 0, v[128:129]
	v_add_co_u32_e32 v128, vcc, s21, v128
	s_nop 1
	v_addc_co_u32_e32 v129, vcc, 0, v129, vcc
	global_load_dwordx4 v[140:143], v[130:131], off
	global_load_dwordx4 v[136:139], v[128:129], off offset:1040
	v_or_b32_e32 v128, 48, v155
	v_mul_hi_i32 v129, v128, s16
	v_lshrrev_b32_e32 v130, 31, v129
	v_ashrrev_i32_e32 v129, 7, v129
	v_add_u32_e32 v129, v129, v130
	v_mul_lo_u32 v129, v129, s20
	v_sub_u32_e32 v128, v128, v129
	v_lshlrev_b32_e32 v128, 4, v128
	v_ashrrev_i32_e32 v129, 31, v128
	v_lshlrev_b64 v[128:129], 3, v[128:129]
	v_lshl_add_u64 v[130:131], v[148:149], 0, v[128:129]
	v_lshl_add_u64 v[128:129], v[146:147], 0, v[128:129]
	v_add_co_u32_e32 v128, vcc, s21, v128
	s_nop 1
	v_addc_co_u32_e32 v129, vcc, 0, v129, vcc
	global_load_dwordx4 v[132:135], v[130:131], off
	s_nop 0
	global_load_dwordx4 v[128:131], v[128:129], off offset:1040
	v_lshl_add_u32 v154, v176, 2, s67
	ds_read_b32 v144, v154
	v_mov_b32_e32 v172, v112
	v_mov_b32_e32 v173, v120
	v_lshlrev_b32_e32 v194, 3, v150
	s_mov_b32 s6, 0x930f000
	s_waitcnt lgkmcnt(0)
	v_pk_mul_f32 v[172:173], v[172:173], v[144:145] op_sel_hi:[1,0]
	s_mov_b32 s7, 0x9372000
	s_waitcnt vmcnt(0)
	v_pk_mul_f32 v[174:175], v[156:157], v[172:173] op_sel:[0,1] op_sel_hi:[1,0]
	v_pk_mul_f32 v[156:157], v[156:157], v[172:173]
	v_sub_f32_e32 v174, v174, v175
	v_add_f32_e32 v175, v157, v156
	v_mov_b32_e32 v156, v113
	v_mov_b32_e32 v157, v121
	v_pk_mul_f32 v[156:157], v[156:157], v[144:145] op_sel_hi:[1,0]
	s_mov_b32 s28, 0x93d5000
	v_pk_mul_f32 v[172:173], v[158:159], v[156:157] op_sel:[0,1] op_sel_hi:[1,0]
	v_pk_mul_f32 v[156:157], v[158:159], v[156:157]
	v_sub_f32_e32 v172, v172, v173
	v_add_f32_e32 v173, v157, v156
	v_mov_b32_e32 v156, v114
	v_mov_b32_e32 v157, v122
	v_pk_mul_f32 v[156:157], v[156:157], v[144:145] op_sel_hi:[1,0]
	s_nop 0
	v_pk_mul_f32 v[158:159], v[160:161], v[156:157] op_sel:[0,1] op_sel_hi:[1,0]
	v_pk_mul_f32 v[156:157], v[160:161], v[156:157]
	v_sub_f32_e32 v158, v158, v159
	v_add_f32_e32 v159, v157, v156
	v_mov_b32_e32 v156, v115
	v_mov_b32_e32 v157, v123
	v_pk_mul_f32 v[144:145], v[156:157], v[144:145] op_sel_hi:[1,0]
	s_nop 0
	v_pk_mul_f32 v[156:157], v[162:163], v[144:145] op_sel:[0,1] op_sel_hi:[1,0]
	v_pk_mul_f32 v[144:145], v[162:163], v[144:145]
	v_sub_f32_e32 v157, v156, v157
	v_add_f32_e32 v144, v145, v144
	v_mad_i32_i24 v145, v177, s22, v155
	v_cmp_gt_i32_e32 vcc, 16, v145
	v_cvt_pk_bf16_f32 v156, v174, v172
	v_cvt_pk_bf16_f32 v157, v158, v157
	v_cvt_pk_bf16_f32 v158, v175, v173
	v_cvt_pk_bf16_f32 v159, v159, v144
	s_nop 1
	v_cndmask_b32_e32 v144, -16, v204, vcc
	v_add_u32_e32 v144, v144, v145
	v_lshlrev_b32_e32 v145, 3, v177
	v_mul_hi_i32_i24_e32 v161, 0x840, v145
	v_mul_i32_i24_e32 v160, 0x840, v145
	v_ashrrev_i32_e32 v145, 31, v144
	v_lshl_add_u64 v[160:161], v[160:161], 0, v[144:145]
	v_mov_b64_e32 v[144:145], s[34:35]
	v_mad_u64_u32 v[162:163], s[4:5], v160, s9, v[144:145]
	v_mov_b32_e32 v160, v163
	v_mad_u64_u32 v[160:161], s[4:5], v161, s9, v[160:161]
	v_mov_b32_e32 v163, v160
	v_lshl_add_u64 v[160:161], v[162:163], 0, v[194:195]
	v_add_co_u32_e32 v172, vcc, s23, v160
	v_lshl_add_u64 v[162:163], v[160:161], 0, s[24:25]
	s_nop 0
	v_addc_co_u32_e32 v173, vcc, 0, v161, vcc
; __device__ __forceinline__ u32x2 pack4(float a, float b, float c, float d) { return u32x2{cvtpk(a, b), cvtpk(c, d)}; }
; __device__ __forceinline__ u32x2 pack4(const f32x4& v) { return u32x2{cvtpk(v[0], v[1]), cvtpk(v[2], v[3])}; }
; __global__ void __launch_bounds__(512) fwd_megakernel(Params p) {
;     ...
;               for (int m = 0; m < 4; ++m) {
;                 int lrow = ai * 128 + wr * 64 + m * 16 + fr, row = brow + lrow; float rs = xl[lrow];
;                 int b = row / LTOK, pos = row - b * LTOK;
;                 const float cs_c[4] = {csa[m][0], csa[m][2], csb[m][0], csb[m][2]}, cs_s[4] = {csa[m][1], csa[m][3], csb[m][1], csb[m][3]};
;                 float o1[4], o2[4];
;                 #pragma unroll
;                 for (int j = 0; j < 4; ++j) { float x1 = acc[ai][0][m][0][j] * rs, x2 = acc[ai][0][m][1][j] * rs;
;                   o1[j] = x1 * cs_c[j] - x2 * cs_s[j]; o2[j] = x2 * cs_c[j] + x1 * cs_s[j]; }
;                 const u32x2 w1 = pack4(o1[0], o1[1], o1[2], o1[3]), w2 = pack4(o2[0], o2[1], o2[2], o2[3]);
;                 int key = pos < NMETA ? SEQ + pos : pos - NMETA;
;                 bf16* kd = p_Kb + ((long)(b * NH) * KPAD + key) * DQK + 64 + fq * 4;
;                 #pragma unroll
;                 for (int h = 0; h < NH; ++h) { *reinterpret_cast<u32x2*>(kd + (long)h * KPAD * DQK) = w1; *reinterpret_cast<u32x2*>(kd + (long)h * KPAD * DQK + 16) = w2; }
	global_store_dwordx2 v[172:173], v[156:157], off offset:128
	global_store_dwordx2 v[162:163], v[158:159], off offset:32
	v_add_co_u32_e32 v162, vcc, s66, v160
	s_nop 1
	v_addc_co_u32_e32 v163, vcc, 0, v161, vcc
	v_mov_b32_e32 v184, v156
	v_mov_b32_e32 v185, v157
	v_mov_b32_e32 v186, v158
	v_mov_b32_e32 v187, v159
	v_bfe_u32 v188, v252, 4, 1
	v_mul_u32_u24_e32 v188, 24, v188
	v_mov_b32_e32 v189, 0
	v_lshl_add_u64 v[182:183], v[162:163], 0, v[188:189]
	v_permlane16_swap_b32_e32 v184, v186
	v_permlane16_swap_b32_e32 v185, v187
	global_store_dwordx4 v[182:183], v[184:187], off offset:128
	s_nop 1
	v_add_co_u32_e32 v162, vcc, s64, v160
	s_nop 1
	v_addc_co_u32_e32 v163, vcc, 0, v161, vcc
	v_mov_b32_e32 v184, v156
	v_mov_b32_e32 v185, v157
	v_mov_b32_e32 v186, v158
	v_mov_b32_e32 v187, v159
	v_bfe_u32 v188, v252, 4, 1
	v_mul_u32_u24_e32 v188, 24, v188
	v_mov_b32_e32 v189, 0
	v_lshl_add_u64 v[182:183], v[162:163], 0, v[188:189]
	v_permlane16_swap_b32_e32 v184, v186
	v_permlane16_swap_b32_e32 v185, v187
	global_store_dwordx4 v[182:183], v[184:187], off offset:128
	s_nop 1
	v_add_co_u32_e32 v162, vcc, s68, v160
	s_nop 1
	v_addc_co_u32_e32 v163, vcc, 0, v161, vcc
	v_mov_b32_e32 v184, v156
	v_mov_b32_e32 v185, v157
	v_mov_b32_e32 v186, v158
	v_mov_b32_e32 v187, v159
	v_bfe_u32 v188, v252, 4, 1
	v_mul_u32_u24_e32 v188, 24, v188
	v_mov_b32_e32 v189, 0
	v_lshl_add_u64 v[182:183], v[162:163], 0, v[188:189]
	v_permlane16_swap_b32_e32 v184, v186
	v_permlane16_swap_b32_e32 v185, v187
	global_store_dwordx4 v[182:183], v[184:187], off offset:128
	s_nop 1
	v_add_co_u32_e32 v162, vcc, s69, v160
	s_nop 1
	v_addc_co_u32_e32 v163, vcc, 0, v161, vcc
	v_mov_b32_e32 v184, v156
	v_mov_b32_e32 v185, v157
	v_mov_b32_e32 v186, v158
	v_mov_b32_e32 v187, v159
	v_bfe_u32 v188, v252, 4, 1
	v_mul_u32_u24_e32 v188, 24, v188
	v_mov_b32_e32 v189, 0
	v_lshl_add_u64 v[182:183], v[162:163], 0, v[188:189]
	v_permlane16_swap_b32_e32 v184, v186
	v_permlane16_swap_b32_e32 v185, v187
	global_store_dwordx4 v[182:183], v[184:187], off offset:128
	s_nop 1
	v_add_co_u32_e32 v162, vcc, s6, v160
	s_nop 1
	v_addc_co_u32_e32 v163, vcc, 0, v161, vcc
	v_mov_b32_e32 v184, v156
	v_mov_b32_e32 v185, v157
	v_mov_b32_e32 v186, v158
	v_mov_b32_e32 v187, v159
	v_bfe_u32 v188, v252, 4, 1
	v_mul_u32_u24_e32 v188, 24, v188
	v_mov_b32_e32 v189, 0
	v_lshl_add_u64 v[182:183], v[162:163], 0, v[188:189]
	v_permlane16_swap_b32_e32 v184, v186
	v_permlane16_swap_b32_e32 v185, v187
	global_store_dwordx4 v[182:183], v[184:187], off offset:128
	s_nop 1
	v_add_co_u32_e32 v162, vcc, s7, v160
	s_nop 1
	v_addc_co_u32_e32 v163, vcc, 0, v161, vcc
	v_add_co_u32_e32 v160, vcc, s28, v160
	v_mov_b32_e32 v184, v156
	v_mov_b32_e32 v185, v157
	v_mov_b32_e32 v186, v158
	v_mov_b32_e32 v187, v159
	v_bfe_u32 v188, v252, 4, 1
	v_mul_u32_u24_e32 v188, 24, v188
	v_mov_b32_e32 v189, 0
	v_lshl_add_u64 v[182:183], v[162:163], 0, v[188:189]
	v_permlane16_swap_b32_e32 v184, v186
	v_permlane16_swap_b32_e32 v185, v187
	global_store_dwordx4 v[182:183], v[184:187], off offset:128
	s_nop 1
	v_addc_co_u32_e32 v161, vcc, 0, v161, vcc
	v_mov_b32_e32 v184, v156
	v_mov_b32_e32 v185, v157
	v_mov_b32_e32 v186, v158
	v_mov_b32_e32 v187, v159
	v_bfe_u32 v188, v252, 4, 1
	v_mul_u32_u24_e32 v188, 24, v188
	v_mov_b32_e32 v189, 0
	v_lshl_add_u64 v[182:183], v[160:161], 0, v[188:189]
	v_permlane16_swap_b32_e32 v184, v186
	v_permlane16_swap_b32_e32 v185, v187
	global_store_dwordx4 v[182:183], v[184:187], off offset:128
	s_nop 1
	v_or_b32_e32 v156, 16, v176
	v_add_u32_e32 v162, s80, v156
	v_lshl_add_u32 v156, v156, 2, s67
	ds_read_b32 v156, v156
	v_mul_hi_i32 v157, v162, s16
	v_lshrrev_b32_e32 v158, 31, v157
	v_ashrrev_i32_e32 v157, 7, v157
	v_add_u32_e32 v163, v157, v158
	v_mov_b32_e32 v158, v96
	v_mov_b32_e32 v159, v104
	s_waitcnt lgkmcnt(0)
	v_pk_mul_f32 v[158:159], v[158:159], v[156:157] op_sel_hi:[1,0]
	v_mad_i32_i24 v162, v163, s22, v162
	v_pk_mul_f32 v[160:161], v[164:165], v[158:159] op_sel:[0,1] op_sel_hi:[1,0]
	v_pk_mul_f32 v[158:159], v[164:165], v[158:159]
	v_sub_f32_e32 v172, v160, v161
	v_add_f32_e32 v164, v159, v158
	v_mov_b32_e32 v158, v97
	v_mov_b32_e32 v159, v105
	v_pk_mul_f32 v[158:159], v[158:159], v[156:157] op_sel_hi:[1,0]
	v_cmp_gt_i32_e32 vcc, 16, v162
	v_pk_mul_f32 v[160:161], v[166:167], v[158:159] op_sel:[0,1] op_sel_hi:[1,0]
	v_pk_mul_f32 v[158:159], v[166:167], v[158:159]
	v_sub_f32_e32 v165, v160, v161
	v_add_f32_e32 v166, v159, v158
	v_mov_b32_e32 v158, v98
	v_mov_b32_e32 v159, v106
	v_pk_mul_f32 v[158:159], v[158:159], v[156:157] op_sel_hi:[1,0]
	s_nop 0
	v_pk_mul_f32 v[160:161], v[168:169], v[158:159] op_sel:[0,1] op_sel_hi:[1,0]
	v_pk_mul_f32 v[158:159], v[168:169], v[158:159]
	v_sub_f32_e32 v160, v160, v161
	v_add_f32_e32 v161, v159, v158
	v_mov_b32_e32 v158, v99
	v_mov_b32_e32 v159, v107
	v_pk_mul_f32 v[156:157], v[158:159], v[156:157] op_sel_hi:[1,0]
	s_nop 0
	v_pk_mul_f32 v[158:159], v[170:171], v[156:157] op_sel:[0,1] op_sel_hi:[1,0]
	v_pk_mul_f32 v[156:157], v[170:171], v[156:157]
	v_sub_f32_e32 v158, v158, v159
	v_add_f32_e32 v159, v157, v156
	v_cvt_pk_bf16_f32 v156, v172, v165
	v_cvt_pk_bf16_f32 v157, v160, v158
	v_cndmask_b32_e32 v160, -16, v204, vcc
	v_cvt_pk_bf16_f32 v158, v164, v166
	v_cvt_pk_bf16_f32 v159, v161, v159
	v_add_u32_e32 v160, v160, v162
	v_lshlrev_b32_e32 v161, 3, v163
	v_mul_hi_i32_i24_e32 v163, 0x840, v161
	v_mul_i32_i24_e32 v162, 0x840, v161
	v_ashrrev_i32_e32 v161, 31, v160
	v_lshl_add_u64 v[160:161], v[162:163], 0, v[160:161]
	v_mad_u64_u32 v[162:163], s[4:5], v160, s9, v[144:145]
	v_mov_b32_e32 v160, v163
	v_mad_u64_u32 v[160:161], s[4:5], v161, s9, v[160:161]
	v_mov_b32_e32 v163, v160
; #define p_rope W_(float2, OFF_ROPE)
; __device__ __forceinline__ u32x2 pack4(float a, float b, float c, float d) { return u32x2{cvtpk(a, b), cvtpk(c, d)}; }
; __device__ __forceinline__ u32x2 pack4(const f32x4& v) { return u32x2{cvtpk(v[0], v[1]), cvtpk(v[2], v[3])}; }
; #define SBAR() __builtin_amdgcn_sched_barrier(0)
; __global__ void __launch_bounds__(512) fwd_megakernel(Params p) {
;     ...
;                 int pos = (brow + ai * 128 + wr * 64 + m * 16 + fr) % LTOK;
;                 csa[m] = *reinterpret_cast<const f32x4*>(p_rope + pos * 16 + fq * 4); csb[m] = *reinterpret_cast<const f32x4*>(p_rope + pos * 16 + fq * 4 + 2);
;               }
;               SBAR();
;               #pragma unroll
;               for (int m = 0; m < 4; ++m) {
;                 int lrow = ai * 128 + wr * 64 + m * 16 + fr, row = brow + lrow; float rs = xl[lrow];
;                 int b = row / LTOK, pos = row - b * LTOK;
;                 const float cs_c[4] = {csa[m][0], csa[m][2], csb[m][0], csb[m][2]}, cs_s[4] = {csa[m][1], csa[m][3], csb[m][1], csb[m][3]};
;                 float o1[4], o2[4];
;                 #pragma unroll
;                 for (int j = 0; j < 4; ++j) { float x1 = acc[ai][0][m][0][j] * rs, x2 = acc[ai][0][m][1][j] * rs;
;                   o1[j] = x1 * cs_c[j] - x2 * cs_s[j]; o2[j] = x2 * cs_c[j] + x1 * cs_s[j]; }
;                 const u32x2 w1 = pack4(o1[0], o1[1], o1[2], o1[3]), w2 = pack4(o2[0], o2[1], o2[2], o2[3]);
;                 int key = pos < NMETA ? SEQ + pos : pos - NMETA;
;                 bf16* kd = p_Kb + ((long)(b * NH) * KPAD + key) * DQK + 64 + fq * 4;
;                 #pragma unroll
;                 for (int h = 0; h < NH; ++h) { *reinterpret_cast<u32x2*>(kd + (long)h * KPAD * DQK) = w1; *reinterpret_cast<u32x2*>(kd + (long)h * KPAD * DQK + 16) = w2; }
	v_lshl_add_u64 v[160:161], v[162:163], 0, v[194:195]
	v_add_co_u32_e32 v164, vcc, s23, v160
	v_lshl_add_u64 v[162:163], v[160:161], 0, s[24:25]
	s_nop 0
	v_addc_co_u32_e32 v165, vcc, 0, v161, vcc
	global_store_dwordx2 v[164:165], v[156:157], off offset:128
	global_store_dwordx2 v[162:163], v[158:159], off offset:32
	v_add_co_u32_e32 v162, vcc, s66, v160
	s_nop 1
	v_addc_co_u32_e32 v163, vcc, 0, v161, vcc
	v_mov_b32_e32 v184, v156
	v_mov_b32_e32 v185, v157
	v_mov_b32_e32 v186, v158
	v_mov_b32_e32 v187, v159
	v_bfe_u32 v188, v252, 4, 1
	v_mul_u32_u24_e32 v188, 24, v188
	v_mov_b32_e32 v189, 0
	v_lshl_add_u64 v[182:183], v[162:163], 0, v[188:189]
	v_permlane16_swap_b32_e32 v184, v186
	v_permlane16_swap_b32_e32 v185, v187
	global_store_dwordx4 v[182:183], v[184:187], off offset:128
	s_nop 1
	v_add_co_u32_e32 v162, vcc, s64, v160
	s_nop 1
	v_addc_co_u32_e32 v163, vcc, 0, v161, vcc
	v_mov_b32_e32 v184, v156
	v_mov_b32_e32 v185, v157
	v_mov_b32_e32 v186, v158
	v_mov_b32_e32 v187, v159
	v_bfe_u32 v188, v252, 4, 1
	v_mul_u32_u24_e32 v188, 24, v188
	v_mov_b32_e32 v189, 0
	v_lshl_add_u64 v[182:183], v[162:163], 0, v[188:189]
	v_permlane16_swap_b32_e32 v184, v186
	v_permlane16_swap_b32_e32 v185, v187
	global_store_dwordx4 v[182:183], v[184:187], off offset:128
	s_nop 1
	v_add_co_u32_e32 v162, vcc, s68, v160
	s_nop 1
	v_addc_co_u32_e32 v163, vcc, 0, v161, vcc
	v_mov_b32_e32 v184, v156
	v_mov_b32_e32 v185, v157
	v_mov_b32_e32 v186, v158
	v_mov_b32_e32 v187, v159
	v_bfe_u32 v188, v252, 4, 1
	v_mul_u32_u24_e32 v188, 24, v188
	v_mov_b32_e32 v189, 0
	v_lshl_add_u64 v[182:183], v[162:163], 0, v[188:189]
	v_permlane16_swap_b32_e32 v184, v186
	v_permlane16_swap_b32_e32 v185, v187
	global_store_dwordx4 v[182:183], v[184:187], off offset:128
	s_nop 1
	v_add_co_u32_e32 v162, vcc, s69, v160
	s_nop 1
	v_addc_co_u32_e32 v163, vcc, 0, v161, vcc
	v_mov_b32_e32 v184, v156
	v_mov_b32_e32 v185, v157
	v_mov_b32_e32 v186, v158
	v_mov_b32_e32 v187, v159
	v_bfe_u32 v188, v252, 4, 1
	v_mul_u32_u24_e32 v188, 24, v188
	v_mov_b32_e32 v189, 0
	v_lshl_add_u64 v[182:183], v[162:163], 0, v[188:189]
	v_permlane16_swap_b32_e32 v184, v186
	v_permlane16_swap_b32_e32 v185, v187
	global_store_dwordx4 v[182:183], v[184:187], off offset:128
	s_nop 1
	v_add_co_u32_e32 v162, vcc, s6, v160
	s_nop 1
	v_addc_co_u32_e32 v163, vcc, 0, v161, vcc
	v_mov_b32_e32 v184, v156
	v_mov_b32_e32 v185, v157
	v_mov_b32_e32 v186, v158
	v_mov_b32_e32 v187, v159
	v_bfe_u32 v188, v252, 4, 1
	v_mul_u32_u24_e32 v188, 24, v188
	v_mov_b32_e32 v189, 0
	v_lshl_add_u64 v[182:183], v[162:163], 0, v[188:189]
	v_permlane16_swap_b32_e32 v184, v186
	v_permlane16_swap_b32_e32 v185, v187
	global_store_dwordx4 v[182:183], v[184:187], off offset:128
	s_nop 1
	v_add_co_u32_e32 v162, vcc, s7, v160
	s_nop 1
	v_addc_co_u32_e32 v163, vcc, 0, v161, vcc
	v_add_co_u32_e32 v160, vcc, s28, v160
	v_mov_b32_e32 v184, v156
	v_mov_b32_e32 v185, v157
	v_mov_b32_e32 v186, v158
	v_mov_b32_e32 v187, v159
	v_bfe_u32 v188, v252, 4, 1
	v_mul_u32_u24_e32 v188, 24, v188
	v_mov_b32_e32 v189, 0
	v_lshl_add_u64 v[182:183], v[162:163], 0, v[188:189]
	v_permlane16_swap_b32_e32 v184, v186
	v_permlane16_swap_b32_e32 v185, v187
	global_store_dwordx4 v[182:183], v[184:187], off offset:128
	s_nop 1
	v_addc_co_u32_e32 v161, vcc, 0, v161, vcc
	v_mov_b32_e32 v184, v156
	v_mov_b32_e32 v185, v157
	v_mov_b32_e32 v186, v158
	v_mov_b32_e32 v187, v159
	v_bfe_u32 v188, v252, 4, 1
	v_mul_u32_u24_e32 v188, 24, v188
	v_mov_b32_e32 v189, 0
	v_lshl_add_u64 v[182:183], v[160:161], 0, v[188:189]
	v_permlane16_swap_b32_e32 v184, v186
	v_permlane16_swap_b32_e32 v185, v187
	global_store_dwordx4 v[182:183], v[184:187], off offset:128
	s_nop 1
	v_or_b32_e32 v156, 32, v176
	v_add_u32_e32 v157, s80, v156
	v_lshl_add_u32 v156, v156, 2, s67
	ds_read_b32 v156, v156
	v_mul_hi_i32 v158, v157, s16
	v_lshrrev_b32_e32 v159, 31, v158
	v_ashrrev_i32_e32 v158, 7, v158
	v_add_u32_e32 v162, v158, v159
	v_mov_b32_e32 v158, v80
	v_mov_b32_e32 v159, v88
	s_waitcnt lgkmcnt(0)
	v_pk_mul_f32 v[158:159], v[158:159], v[156:157] op_sel_hi:[1,0]
	s_nop 0
	v_pk_mul_f32 v[160:161], v[140:141], v[158:159] op_sel:[0,1] op_sel_hi:[1,0]
	v_pk_mul_f32 v[140:141], v[140:141], v[158:159]
	v_sub_f32_e32 v160, v160, v161
	v_add_f32_e32 v161, v141, v140
	v_mov_b32_e32 v140, v81
	v_mov_b32_e32 v141, v89
	v_pk_mul_f32 v[140:141], v[140:141], v[156:157] op_sel_hi:[1,0]
	s_nop 0
	v_pk_mul_f32 v[158:159], v[142:143], v[140:141] op_sel:[0,1] op_sel_hi:[1,0]
	v_pk_mul_f32 v[140:141], v[142:143], v[140:141]
	v_sub_f32_e32 v158, v158, v159
	v_add_f32_e32 v159, v141, v140
	v_mov_b32_e32 v140, v82
	v_mov_b32_e32 v141, v90
	v_pk_mul_f32 v[140:141], v[140:141], v[156:157] op_sel_hi:[1,0]
	s_nop 0
	v_pk_mul_f32 v[142:143], v[136:137], v[140:141] op_sel:[0,1] op_sel_hi:[1,0]
	v_pk_mul_f32 v[136:137], v[136:137], v[140:141]
	v_sub_f32_e32 v142, v142, v143
	v_add_f32_e32 v143, v137, v136
	v_mov_b32_e32 v136, v83
	v_mov_b32_e32 v137, v91
	v_pk_mul_f32 v[136:137], v[136:137], v[156:157] op_sel_hi:[1,0]
	s_nop 0
	v_pk_mul_f32 v[140:141], v[138:139], v[136:137] op_sel:[0,1] op_sel_hi:[1,0]
	v_pk_mul_f32 v[136:137], v[138:139], v[136:137]
	v_sub_f32_e32 v140, v140, v141
	v_mad_i32_i24 v141, v162, s22, v157
	v_cmp_gt_i32_e32 vcc, 16, v141
	v_add_f32_e32 v139, v137, v136
	v_cvt_pk_bf16_f32 v136, v160, v158
	v_cvt_pk_bf16_f32 v137, v142, v140
	v_cvt_pk_bf16_f32 v138, v161, v159
	v_cvt_pk_bf16_f32 v139, v143, v139
	s_nop 0
	v_cndmask_b32_e32 v140, -16, v204, vcc
	v_add_u32_e32 v140, v140, v141
	v_lshlrev_b32_e32 v141, 3, v162
	v_mul_hi_i32_i24_e32 v143, 0x840, v141
	v_mul_i32_i24_e32 v142, 0x840, v141
	v_ashrrev_i32_e32 v141, 31, v140
; #define p_rope W_(float2, OFF_ROPE)
; __device__ __forceinline__ u32x2 pack4(float a, float b, float c, float d) { return u32x2{cvtpk(a, b), cvtpk(c, d)}; }
; __device__ __forceinline__ u32x2 pack4(const f32x4& v) { return u32x2{cvtpk(v[0], v[1]), cvtpk(v[2], v[3])}; }
; #define SBAR() __builtin_amdgcn_sched_barrier(0)
; __global__ void __launch_bounds__(512) fwd_megakernel(Params p) {
;     ...
;                 int pos = (brow + ai * 128 + wr * 64 + m * 16 + fr) % LTOK;
;                 csa[m] = *reinterpret_cast<const f32x4*>(p_rope + pos * 16 + fq * 4); csb[m] = *reinterpret_cast<const f32x4*>(p_rope + pos * 16 + fq * 4 + 2);
;               }
;               SBAR();
;               #pragma unroll
;               for (int m = 0; m < 4; ++m) {
;                 int lrow = ai * 128 + wr * 64 + m * 16 + fr, row = brow + lrow; float rs = xl[lrow];
;                 int b = row / LTOK, pos = row - b * LTOK;
;                 const float cs_c[4] = {csa[m][0], csa[m][2], csb[m][0], csb[m][2]}, cs_s[4] = {csa[m][1], csa[m][3], csb[m][1], csb[m][3]};
;                 float o1[4], o2[4];
;                 #pragma unroll
;                 for (int j = 0; j < 4; ++j) { float x1 = acc[ai][0][m][0][j] * rs, x2 = acc[ai][0][m][1][j] * rs;
;                   o1[j] = x1 * cs_c[j] - x2 * cs_s[j]; o2[j] = x2 * cs_c[j] + x1 * cs_s[j]; }
;                 const u32x2 w1 = pack4(o1[0], o1[1], o1[2], o1[3]), w2 = pack4(o2[0], o2[1], o2[2], o2[3]);
;                 int key = pos < NMETA ? SEQ + pos : pos - NMETA;
;                 bf16* kd = p_Kb + ((long)(b * NH) * KPAD + key) * DQK + 64 + fq * 4;
;                 #pragma unroll
;                 for (int h = 0; h < NH; ++h) { *reinterpret_cast<u32x2*>(kd + (long)h * KPAD * DQK) = w1; *reinterpret_cast<u32x2*>(kd + (long)h * KPAD * DQK + 16) = w2; }
	v_lshl_add_u64 v[140:141], v[142:143], 0, v[140:141]
	v_mad_u64_u32 v[142:143], s[4:5], v140, s9, v[144:145]
	v_mov_b32_e32 v140, v143
	v_mad_u64_u32 v[140:141], s[4:5], v141, s9, v[140:141]
	v_mov_b32_e32 v143, v140
	v_lshl_add_u64 v[140:141], v[142:143], 0, v[194:195]
	v_add_co_u32_e32 v156, vcc, s23, v140
	v_lshl_add_u64 v[142:143], v[140:141], 0, s[24:25]
	s_nop 0
	v_addc_co_u32_e32 v157, vcc, 0, v141, vcc
	global_store_dwordx2 v[156:157], v[136:137], off offset:128
	global_store_dwordx2 v[142:143], v[138:139], off offset:32
	v_add_co_u32_e32 v142, vcc, s66, v140
	s_nop 1
	v_addc_co_u32_e32 v143, vcc, 0, v141, vcc
	v_mov_b32_e32 v184, v136
	v_mov_b32_e32 v185, v137
	v_mov_b32_e32 v186, v138
	v_mov_b32_e32 v187, v139
	v_bfe_u32 v188, v252, 4, 1
	v_mul_u32_u24_e32 v188, 24, v188
	v_mov_b32_e32 v189, 0
	v_lshl_add_u64 v[182:183], v[142:143], 0, v[188:189]
	v_permlane16_swap_b32_e32 v184, v186
	v_permlane16_swap_b32_e32 v185, v187
	global_store_dwordx4 v[182:183], v[184:187], off offset:128
	s_nop 1
	v_add_co_u32_e32 v142, vcc, s64, v140
	s_nop 1
	v_addc_co_u32_e32 v143, vcc, 0, v141, vcc
	v_mov_b32_e32 v184, v136
	v_mov_b32_e32 v185, v137
	v_mov_b32_e32 v186, v138
	v_mov_b32_e32 v187, v139
	v_bfe_u32 v188, v252, 4, 1
	v_mul_u32_u24_e32 v188, 24, v188
	v_mov_b32_e32 v189, 0
	v_lshl_add_u64 v[182:183], v[142:143], 0, v[188:189]
	v_permlane16_swap_b32_e32 v184, v186
	v_permlane16_swap_b32_e32 v185, v187
	global_store_dwordx4 v[182:183], v[184:187], off offset:128
	s_nop 1
	v_add_co_u32_e32 v142, vcc, s68, v140
	s_nop 1
	v_addc_co_u32_e32 v143, vcc, 0, v141, vcc
	v_mov_b32_e32 v184, v136
	v_mov_b32_e32 v185, v137
	v_mov_b32_e32 v186, v138
	v_mov_b32_e32 v187, v139
	v_bfe_u32 v188, v252, 4, 1
	v_mul_u32_u24_e32 v188, 24, v188
	v_mov_b32_e32 v189, 0
	v_lshl_add_u64 v[182:183], v[142:143], 0, v[188:189]
	v_permlane16_swap_b32_e32 v184, v186
	v_permlane16_swap_b32_e32 v185, v187
	global_store_dwordx4 v[182:183], v[184:187], off offset:128
	s_nop 1
	v_add_co_u32_e32 v142, vcc, s69, v140
	s_nop 1
	v_addc_co_u32_e32 v143, vcc, 0, v141, vcc
	v_mov_b32_e32 v184, v136
	v_mov_b32_e32 v185, v137
	v_mov_b32_e32 v186, v138
	v_mov_b32_e32 v187, v139
	v_bfe_u32 v188, v252, 4, 1
	v_mul_u32_u24_e32 v188, 24, v188
	v_mov_b32_e32 v189, 0
	v_lshl_add_u64 v[182:183], v[142:143], 0, v[188:189]
	v_permlane16_swap_b32_e32 v184, v186
	v_permlane16_swap_b32_e32 v185, v187
	global_store_dwordx4 v[182:183], v[184:187], off offset:128
	s_nop 1
	v_add_co_u32_e32 v142, vcc, s6, v140
	s_nop 1
	v_addc_co_u32_e32 v143, vcc, 0, v141, vcc
	v_mov_b32_e32 v184, v136
	v_mov_b32_e32 v185, v137
	v_mov_b32_e32 v186, v138
	v_mov_b32_e32 v187, v139
	v_bfe_u32 v188, v252, 4, 1
	v_mul_u32_u24_e32 v188, 24, v188
	v_mov_b32_e32 v189, 0
	v_lshl_add_u64 v[182:183], v[142:143], 0, v[188:189]
	v_permlane16_swap_b32_e32 v184, v186
	v_permlane16_swap_b32_e32 v185, v187
	global_store_dwordx4 v[182:183], v[184:187], off offset:128
	s_nop 1
	v_add_co_u32_e32 v142, vcc, s7, v140
	s_nop 1
	v_addc_co_u32_e32 v143, vcc, 0, v141, vcc
	v_add_co_u32_e32 v140, vcc, s28, v140
	v_mov_b32_e32 v184, v136
	v_mov_b32_e32 v185, v137
	v_mov_b32_e32 v186, v138
	v_mov_b32_e32 v187, v139
	v_bfe_u32 v188, v252, 4, 1
	v_mul_u32_u24_e32 v188, 24, v188
	v_mov_b32_e32 v189, 0
	v_lshl_add_u64 v[182:183], v[142:143], 0, v[188:189]
	v_permlane16_swap_b32_e32 v184, v186
	v_permlane16_swap_b32_e32 v185, v187
	global_store_dwordx4 v[182:183], v[184:187], off offset:128
	s_nop 1
	v_addc_co_u32_e32 v141, vcc, 0, v141, vcc
	v_mov_b32_e32 v184, v136
	v_mov_b32_e32 v185, v137
	v_mov_b32_e32 v186, v138
	v_mov_b32_e32 v187, v139
	v_bfe_u32 v188, v252, 4, 1
	v_mul_u32_u24_e32 v188, 24, v188
	v_mov_b32_e32 v189, 0
	v_lshl_add_u64 v[182:183], v[140:141], 0, v[188:189]
	v_permlane16_swap_b32_e32 v184, v186
	v_permlane16_swap_b32_e32 v185, v187
	global_store_dwordx4 v[182:183], v[184:187], off offset:128
	s_nop 1
	v_or_b32_e32 v136, 48, v176
	v_add_u32_e32 v137, s80, v136
	v_lshl_add_u32 v136, v136, 2, s67
	ds_read_b32 v136, v136
	v_mul_hi_i32 v138, v137, s16
	v_lshrrev_b32_e32 v139, 31, v138
	v_ashrrev_i32_e32 v138, 7, v138
	v_add_u32_e32 v142, v138, v139
	v_mov_b32_e32 v138, v64
	v_mov_b32_e32 v139, v72
	s_waitcnt lgkmcnt(0)
	v_pk_mul_f32 v[138:139], v[138:139], v[136:137] op_sel_hi:[1,0]
	s_nop 0
	v_pk_mul_f32 v[140:141], v[132:133], v[138:139] op_sel:[0,1] op_sel_hi:[1,0]
	v_pk_mul_f32 v[132:133], v[132:133], v[138:139]
	v_sub_f32_e32 v140, v140, v141
	v_add_f32_e32 v141, v133, v132
	v_mov_b32_e32 v132, v65
	v_mov_b32_e32 v133, v73
	v_pk_mul_f32 v[132:133], v[132:133], v[136:137] op_sel_hi:[1,0]
	s_nop 0
	v_pk_mul_f32 v[138:139], v[134:135], v[132:133] op_sel:[0,1] op_sel_hi:[1,0]
	v_pk_mul_f32 v[132:133], v[134:135], v[132:133]
	v_sub_f32_e32 v138, v138, v139
	v_add_f32_e32 v139, v133, v132
	v_mov_b32_e32 v132, v66
	v_mov_b32_e32 v133, v74
	v_pk_mul_f32 v[132:133], v[132:133], v[136:137] op_sel_hi:[1,0]
	s_nop 0
	v_pk_mul_f32 v[134:135], v[128:129], v[132:133] op_sel:[0,1] op_sel_hi:[1,0]
	v_pk_mul_f32 v[128:129], v[128:129], v[132:133]
	v_sub_f32_e32 v134, v134, v135
	v_add_f32_e32 v135, v129, v128
	v_mov_b32_e32 v128, v67
	v_mov_b32_e32 v129, v75
	v_pk_mul_f32 v[128:129], v[128:129], v[136:137] op_sel_hi:[1,0]
	s_nop 0
	v_pk_mul_f32 v[132:133], v[130:131], v[128:129] op_sel:[0,1] op_sel_hi:[1,0]
	v_pk_mul_f32 v[128:129], v[130:131], v[128:129]
	v_sub_f32_e32 v132, v132, v133
	v_mad_i32_i24 v133, v142, s22, v137
	v_cmp_gt_i32_e32 vcc, 16, v133
	v_add_f32_e32 v131, v129, v128
	v_cvt_pk_bf16_f32 v128, v140, v138
	v_cvt_pk_bf16_f32 v129, v134, v132
	v_cvt_pk_bf16_f32 v130, v141, v139
	v_cvt_pk_bf16_f32 v131, v135, v131
	s_nop 0
; #define p_rope W_(float2, OFF_ROPE)
; __device__ __forceinline__ u32x2 pack4(float a, float b, float c, float d) { return u32x2{cvtpk(a, b), cvtpk(c, d)}; }
; __device__ __forceinline__ u32x2 pack4(const f32x4& v) { return u32x2{cvtpk(v[0], v[1]), cvtpk(v[2], v[3])}; }
; #define SBAR() __builtin_amdgcn_sched_barrier(0)
; __global__ void __launch_bounds__(512) fwd_megakernel(Params p) {
;     ...
;                 int pos = (brow + ai * 128 + wr * 64 + m * 16 + fr) % LTOK;
;                 csa[m] = *reinterpret_cast<const f32x4*>(p_rope + pos * 16 + fq * 4); csb[m] = *reinterpret_cast<const f32x4*>(p_rope + pos * 16 + fq * 4 + 2);
;               }
;               SBAR();
;               #pragma unroll
;               for (int m = 0; m < 4; ++m) {
;                 int lrow = ai * 128 + wr * 64 + m * 16 + fr, row = brow + lrow; float rs = xl[lrow];
;                 int b = row / LTOK, pos = row - b * LTOK;
;                 const float cs_c[4] = {csa[m][0], csa[m][2], csb[m][0], csb[m][2]}, cs_s[4] = {csa[m][1], csa[m][3], csb[m][1], csb[m][3]};
;                 float o1[4], o2[4];
;                 #pragma unroll
;                 for (int j = 0; j < 4; ++j) { float x1 = acc[ai][0][m][0][j] * rs, x2 = acc[ai][0][m][1][j] * rs;
;                   o1[j] = x1 * cs_c[j] - x2 * cs_s[j]; o2[j] = x2 * cs_c[j] + x1 * cs_s[j]; }
;                 const u32x2 w1 = pack4(o1[0], o1[1], o1[2], o1[3]), w2 = pack4(o2[0], o2[1], o2[2], o2[3]);
;                 int key = pos < NMETA ? SEQ + pos : pos - NMETA;
;                 bf16* kd = p_Kb + ((long)(b * NH) * KPAD + key) * DQK + 64 + fq * 4;
;                 #pragma unroll
;                 for (int h = 0; h < NH; ++h) { *reinterpret_cast<u32x2*>(kd + (long)h * KPAD * DQK) = w1; *reinterpret_cast<u32x2*>(kd + (long)h * KPAD * DQK + 16) = w2; }
	v_cndmask_b32_e32 v132, -16, v204, vcc
	v_add_u32_e32 v132, v132, v133
	v_lshlrev_b32_e32 v133, 3, v142
	v_mul_hi_i32_i24_e32 v135, 0x840, v133
	v_mul_i32_i24_e32 v134, 0x840, v133
	v_ashrrev_i32_e32 v133, 31, v132
	v_lshl_add_u64 v[132:133], v[134:135], 0, v[132:133]
	v_mad_u64_u32 v[134:135], s[4:5], v132, s9, v[144:145]
	v_mov_b32_e32 v132, v135
	v_mad_u64_u32 v[132:133], s[4:5], v133, s9, v[132:133]
	v_mov_b32_e32 v135, v132
	v_lshl_add_u64 v[132:133], v[134:135], 0, v[194:195]
	v_add_co_u32_e32 v136, vcc, s23, v132
	v_lshl_add_u64 v[134:135], v[132:133], 0, s[24:25]
	s_nop 0
	v_addc_co_u32_e32 v137, vcc, 0, v133, vcc
	global_store_dwordx2 v[136:137], v[128:129], off offset:128
	global_store_dwordx2 v[134:135], v[130:131], off offset:32
	v_add_co_u32_e32 v134, vcc, s66, v132
	s_nop 1
	v_addc_co_u32_e32 v135, vcc, 0, v133, vcc
	v_mov_b32_e32 v184, v128
	v_mov_b32_e32 v185, v129
	v_mov_b32_e32 v186, v130
	v_mov_b32_e32 v187, v131
	v_bfe_u32 v188, v252, 4, 1
	v_mul_u32_u24_e32 v188, 24, v188
	v_mov_b32_e32 v189, 0
	v_lshl_add_u64 v[182:183], v[134:135], 0, v[188:189]
	v_permlane16_swap_b32_e32 v184, v186
	v_permlane16_swap_b32_e32 v185, v187
	global_store_dwordx4 v[182:183], v[184:187], off offset:128
	s_nop 1
	v_add_co_u32_e32 v134, vcc, s64, v132
	s_nop 1
	v_addc_co_u32_e32 v135, vcc, 0, v133, vcc
	v_mov_b32_e32 v184, v128
	v_mov_b32_e32 v185, v129
	v_mov_b32_e32 v186, v130
	v_mov_b32_e32 v187, v131
	v_bfe_u32 v188, v252, 4, 1
	v_mul_u32_u24_e32 v188, 24, v188
	v_mov_b32_e32 v189, 0
	v_lshl_add_u64 v[182:183], v[134:135], 0, v[188:189]
	v_permlane16_swap_b32_e32 v184, v186
	v_permlane16_swap_b32_e32 v185, v187
	global_store_dwordx4 v[182:183], v[184:187], off offset:128
	s_nop 1
	v_add_co_u32_e32 v134, vcc, s68, v132
	s_nop 1
	v_addc_co_u32_e32 v135, vcc, 0, v133, vcc
	v_mov_b32_e32 v184, v128
	v_mov_b32_e32 v185, v129
	v_mov_b32_e32 v186, v130
	v_mov_b32_e32 v187, v131
	v_bfe_u32 v188, v252, 4, 1
	v_mul_u32_u24_e32 v188, 24, v188
	v_mov_b32_e32 v189, 0
	v_lshl_add_u64 v[182:183], v[134:135], 0, v[188:189]
	v_permlane16_swap_b32_e32 v184, v186
	v_permlane16_swap_b32_e32 v185, v187
	global_store_dwordx4 v[182:183], v[184:187], off offset:128
	s_nop 1
	v_add_co_u32_e32 v134, vcc, s69, v132
	s_nop 1
	v_addc_co_u32_e32 v135, vcc, 0, v133, vcc
	v_mov_b32_e32 v184, v128
	v_mov_b32_e32 v185, v129
	v_mov_b32_e32 v186, v130
	v_mov_b32_e32 v187, v131
	v_bfe_u32 v188, v252, 4, 1
	v_mul_u32_u24_e32 v188, 24, v188
	v_mov_b32_e32 v189, 0
	v_lshl_add_u64 v[182:183], v[134:135], 0, v[188:189]
	v_permlane16_swap_b32_e32 v184, v186
	v_permlane16_swap_b32_e32 v185, v187
	global_store_dwordx4 v[182:183], v[184:187], off offset:128
	s_nop 1
	v_add_co_u32_e32 v134, vcc, s6, v132
	s_nop 1
	v_addc_co_u32_e32 v135, vcc, 0, v133, vcc
	v_mov_b32_e32 v184, v128
	v_mov_b32_e32 v185, v129
	v_mov_b32_e32 v186, v130
	v_mov_b32_e32 v187, v131
	v_bfe_u32 v188, v252, 4, 1
	v_mul_u32_u24_e32 v188, 24, v188
	v_mov_b32_e32 v189, 0
	v_lshl_add_u64 v[182:183], v[134:135], 0, v[188:189]
	v_permlane16_swap_b32_e32 v184, v186
	v_permlane16_swap_b32_e32 v185, v187
	global_store_dwordx4 v[182:183], v[184:187], off offset:128
	s_nop 1
	v_add_co_u32_e32 v134, vcc, s7, v132
	s_nop 1
	v_addc_co_u32_e32 v135, vcc, 0, v133, vcc
	v_add_co_u32_e32 v132, vcc, s28, v132
	v_mov_b32_e32 v184, v128
	v_mov_b32_e32 v185, v129
	v_mov_b32_e32 v186, v130
	v_mov_b32_e32 v187, v131
	v_bfe_u32 v188, v252, 4, 1
	v_mul_u32_u24_e32 v188, 24, v188
	v_mov_b32_e32 v189, 0
	v_lshl_add_u64 v[182:183], v[134:135], 0, v[188:189]
	v_permlane16_swap_b32_e32 v184, v186
	v_permlane16_swap_b32_e32 v185, v187
	global_store_dwordx4 v[182:183], v[184:187], off offset:128
	s_nop 1
	v_addc_co_u32_e32 v133, vcc, 0, v133, vcc
	v_mov_b32_e32 v184, v128
	v_mov_b32_e32 v185, v129
	v_mov_b32_e32 v186, v130
	v_mov_b32_e32 v187, v131
	v_bfe_u32 v188, v252, 4, 1
	v_mul_u32_u24_e32 v188, 24, v188
	v_mov_b32_e32 v189, 0
	v_lshl_add_u64 v[182:183], v[132:133], 0, v[188:189]
	v_permlane16_swap_b32_e32 v184, v186
	v_permlane16_swap_b32_e32 v185, v187
	global_store_dwordx4 v[182:183], v[184:187], off offset:128
	s_nop 1
	v_add_u32_e32 v174, 0x80, v155
	v_mul_hi_i32 v128, v174, s16
	v_lshrrev_b32_e32 v129, 31, v128
	v_ashrrev_i32_e32 v128, 7, v128
	v_add_u32_e32 v175, v128, v129
	v_mul_i32_i24_e32 v128, 0x810, v175
	v_sub_u32_e32 v128, v174, v128
	v_lshlrev_b32_e32 v128, 4, v128
	v_ashrrev_i32_e32 v129, 31, v128
	v_lshlrev_b64 v[128:129], 3, v[128:129]
	v_lshl_add_u64 v[130:131], v[148:149], 0, v[128:129]
	v_lshl_add_u64 v[128:129], v[146:147], 0, v[128:129]
	v_add_co_u32_e32 v128, vcc, s21, v128
	v_add_u32_e32 v176, 0x90, v155
	s_nop 0
	v_addc_co_u32_e32 v129, vcc, 0, v129, vcc
	global_load_dwordx4 v[156:159], v[130:131], off
	global_load_dwordx4 v[160:163], v[128:129], off offset:1040
	v_mul_hi_i32 v128, v176, s16
	v_lshrrev_b32_e32 v129, 31, v128
	v_ashrrev_i32_e32 v128, 7, v128
	v_add_u32_e32 v177, v128, v129
	v_mul_lo_u32 v128, v177, s20
	v_sub_u32_e32 v128, v176, v128
	v_lshlrev_b32_e32 v128, 4, v128
	v_ashrrev_i32_e32 v129, 31, v128
	v_lshlrev_b64 v[128:129], 3, v[128:129]
	v_lshl_add_u64 v[130:131], v[148:149], 0, v[128:129]
	v_lshl_add_u64 v[128:129], v[146:147], 0, v[128:129]
	v_add_co_u32_e32 v128, vcc, s21, v128
	v_add_u32_e32 v178, 0xa0, v155
	s_nop 0
	v_addc_co_u32_e32 v129, vcc, 0, v129, vcc
	global_load_dwordx4 v[164:167], v[130:131], off
	global_load_dwordx4 v[168:171], v[128:129], off offset:1040
	v_mul_hi_i32 v128, v178, s16
	v_lshrrev_b32_e32 v129, 31, v128
	v_ashrrev_i32_e32 v128, 7, v128
	v_add_u32_e32 v179, v128, v129
	v_mul_lo_u32 v128, v179, s20
	v_sub_u32_e32 v128, v178, v128
	v_lshlrev_b32_e32 v128, 4, v128
	v_ashrrev_i32_e32 v129, 31, v128
	v_lshlrev_b64 v[128:129], 3, v[128:129]
	v_lshl_add_u64 v[130:131], v[148:149], 0, v[128:129]
	v_lshl_add_u64 v[128:129], v[146:147], 0, v[128:129]
	v_add_co_u32_e32 v128, vcc, s21, v128
	v_add_u32_e32 v155, 0xb0, v155
	s_nop 0
	v_addc_co_u32_e32 v129, vcc, 0, v129, vcc
	global_load_dwordx4 v[140:143], v[130:131], off
	global_load_dwordx4 v[136:139], v[128:129], off offset:1040
	v_mul_hi_i32 v128, v155, s16
	v_lshrrev_b32_e32 v129, 31, v128
	v_ashrrev_i32_e32 v128, 7, v128
	v_add_u32_e32 v180, v128, v129
	v_mul_lo_u32 v128, v180, s20
	v_sub_u32_e32 v128, v155, v128
	v_lshlrev_b32_e32 v128, 4, v128
	v_ashrrev_i32_e32 v129, 31, v128
	v_lshlrev_b64 v[128:129], 3, v[128:129]
	v_lshl_add_u64 v[130:131], v[148:149], 0, v[128:129]
	v_lshl_add_u64 v[128:129], v[146:147], 0, v[128:129]
	v_add_co_u32_e32 v128, vcc, s21, v128
	s_nop 1
	v_addc_co_u32_e32 v129, vcc, 0, v129, vcc
	global_load_dwordx4 v[132:135], v[130:131], off
	s_nop 0
	global_load_dwordx4 v[128:131], v[128:129], off offset:1040
	ds_read_b32 v146, v154 offset:512
	v_mov_b32_e32 v148, v48
	v_mov_b32_e32 v149, v56
	s_waitcnt lgkmcnt(0)
; #define p_rope W_(float2, OFF_ROPE)
; __device__ __forceinline__ u32x2 pack4(float a, float b, float c, float d) { return u32x2{cvtpk(a, b), cvtpk(c, d)}; }
; __device__ __forceinline__ u32x2 pack4(const f32x4& v) { return u32x2{cvtpk(v[0], v[1]), cvtpk(v[2], v[3])}; }
; #define SBAR() __builtin_amdgcn_sched_barrier(0)
; __global__ void __launch_bounds__(512) fwd_megakernel(Params p) {
;     ...
;                 int pos = (brow + ai * 128 + wr * 64 + m * 16 + fr) % LTOK;
;                 csa[m] = *reinterpret_cast<const f32x4*>(p_rope + pos * 16 + fq * 4); csb[m] = *reinterpret_cast<const f32x4*>(p_rope + pos * 16 + fq * 4 + 2);
;               }
;               SBAR();
;               #pragma unroll
;               for (int m = 0; m < 4; ++m) {
;                 int lrow = ai * 128 + wr * 64 + m * 16 + fr, row = brow + lrow; float rs = xl[lrow];
;                 int b = row / LTOK, pos = row - b * LTOK;
;                 const float cs_c[4] = {csa[m][0], csa[m][2], csb[m][0], csb[m][2]}, cs_s[4] = {csa[m][1], csa[m][3], csb[m][1], csb[m][3]};
;                 float o1[4], o2[4];
;                 #pragma unroll
;                 for (int j = 0; j < 4; ++j) { float x1 = acc[ai][0][m][0][j] * rs, x2 = acc[ai][0][m][1][j] * rs;
;                   o1[j] = x1 * cs_c[j] - x2 * cs_s[j]; o2[j] = x2 * cs_c[j] + x1 * cs_s[j]; }
;                 const u32x2 w1 = pack4(o1[0], o1[1], o1[2], o1[3]), w2 = pack4(o2[0], o2[1], o2[2], o2[3]);
;                 int key = pos < NMETA ? SEQ + pos : pos - NMETA;
;                 bf16* kd = p_Kb + ((long)(b * NH) * KPAD + key) * DQK + 64 + fq * 4;
;                 #pragma unroll
;                 for (int h = 0; h < NH; ++h) { *reinterpret_cast<u32x2*>(kd + (long)h * KPAD * DQK) = w1; *reinterpret_cast<u32x2*>(kd + (long)h * KPAD * DQK + 16) = w2; }
	v_pk_mul_f32 v[148:149], v[148:149], v[146:147] op_sel_hi:[1,0]
	s_waitcnt vmcnt(7)
	v_pk_mul_f32 v[172:173], v[156:157], v[148:149] op_sel:[0,1] op_sel_hi:[1,0]
	v_pk_mul_f32 v[148:149], v[156:157], v[148:149]
	v_sub_f32_e32 v172, v172, v173
	v_add_f32_e32 v173, v149, v148
	v_mov_b32_e32 v148, v49
	v_mov_b32_e32 v149, v57
	v_pk_mul_f32 v[148:149], v[148:149], v[146:147] op_sel_hi:[1,0]
	s_nop 0
	v_pk_mul_f32 v[156:157], v[158:159], v[148:149] op_sel:[0,1] op_sel_hi:[1,0]
	v_pk_mul_f32 v[148:149], v[158:159], v[148:149]
	v_sub_f32_e32 v181, v156, v157
	v_add_f32_e32 v158, v149, v148
	v_mov_b32_e32 v148, v50
	v_mov_b32_e32 v149, v58
	v_pk_mul_f32 v[148:149], v[148:149], v[146:147] op_sel_hi:[1,0]
	v_mad_i32_i24 v159, v175, s22, v174
	s_waitcnt vmcnt(6)
	v_pk_mul_f32 v[156:157], v[160:161], v[148:149] op_sel:[0,1] op_sel_hi:[1,0]
	v_pk_mul_f32 v[148:149], v[160:161], v[148:149]
	v_sub_f32_e32 v156, v156, v157
	v_add_f32_e32 v157, v149, v148
	v_mov_b32_e32 v148, v51
	v_mov_b32_e32 v149, v59
	v_pk_mul_f32 v[146:147], v[148:149], v[146:147] op_sel_hi:[1,0]
	v_cmp_gt_i32_e32 vcc, 16, v159
	v_pk_mul_f32 v[148:149], v[162:163], v[146:147] op_sel:[0,1] op_sel_hi:[1,0]
	v_pk_mul_f32 v[146:147], v[162:163], v[146:147]
	v_sub_f32_e32 v148, v148, v149
	v_add_f32_e32 v149, v147, v146
	v_cvt_pk_bf16_f32 v146, v172, v181
	v_cvt_pk_bf16_f32 v147, v156, v148
	v_cndmask_b32_e32 v156, -16, v204, vcc
	v_cvt_pk_bf16_f32 v148, v173, v158
	v_cvt_pk_bf16_f32 v149, v157, v149
	v_add_u32_e32 v156, v156, v159
	v_lshlrev_b32_e32 v157, 3, v175
	v_mul_hi_i32_i24_e32 v159, 0x840, v157
	v_mul_i32_i24_e32 v158, 0x840, v157
	v_ashrrev_i32_e32 v157, 31, v156
	v_lshl_add_u64 v[156:157], v[158:159], 0, v[156:157]
	v_mad_u64_u32 v[158:159], s[4:5], v156, s9, v[144:145]
	v_mov_b32_e32 v156, v159
	v_mad_u64_u32 v[156:157], s[4:5], v157, s9, v[156:157]
	v_mov_b32_e32 v159, v156
	v_lshl_add_u64 v[156:157], v[158:159], 0, v[194:195]
	v_add_co_u32_e32 v160, vcc, s23, v156
	v_lshl_add_u64 v[158:159], v[156:157], 0, s[24:25]
	s_nop 0
	v_addc_co_u32_e32 v161, vcc, 0, v157, vcc
	global_store_dwordx2 v[160:161], v[146:147], off offset:128
	global_store_dwordx2 v[158:159], v[148:149], off offset:32
	v_add_co_u32_e32 v158, vcc, s66, v156
	v_mad_i32_i24 v162, v177, s22, v176
	s_nop 0
	v_addc_co_u32_e32 v159, vcc, 0, v157, vcc
	v_mov_b32_e32 v184, v146
	v_mov_b32_e32 v185, v147
	v_mov_b32_e32 v186, v148
	v_mov_b32_e32 v187, v149
	v_bfe_u32 v188, v252, 4, 1
	v_mul_u32_u24_e32 v188, 24, v188
	v_mov_b32_e32 v189, 0
	v_lshl_add_u64 v[182:183], v[158:159], 0, v[188:189]
	v_permlane16_swap_b32_e32 v184, v186
	v_permlane16_swap_b32_e32 v185, v187
	global_store_dwordx4 v[182:183], v[184:187], off offset:128
	s_nop 1
	v_add_co_u32_e32 v158, vcc, s64, v156
	s_nop 1
	v_addc_co_u32_e32 v159, vcc, 0, v157, vcc
	v_mov_b32_e32 v184, v146
	v_mov_b32_e32 v185, v147
	v_mov_b32_e32 v186, v148
	v_mov_b32_e32 v187, v149
	v_bfe_u32 v188, v252, 4, 1
	v_mul_u32_u24_e32 v188, 24, v188
	v_mov_b32_e32 v189, 0
	v_lshl_add_u64 v[182:183], v[158:159], 0, v[188:189]
	v_permlane16_swap_b32_e32 v184, v186
	v_permlane16_swap_b32_e32 v185, v187
	global_store_dwordx4 v[182:183], v[184:187], off offset:128
	s_nop 1
	v_add_co_u32_e32 v158, vcc, s68, v156
	s_nop 1
	v_addc_co_u32_e32 v159, vcc, 0, v157, vcc
	v_mov_b32_e32 v184, v146
	v_mov_b32_e32 v185, v147
	v_mov_b32_e32 v186, v148
	v_mov_b32_e32 v187, v149
	v_bfe_u32 v188, v252, 4, 1
	v_mul_u32_u24_e32 v188, 24, v188
	v_mov_b32_e32 v189, 0
	v_lshl_add_u64 v[182:183], v[158:159], 0, v[188:189]
	v_permlane16_swap_b32_e32 v184, v186
	v_permlane16_swap_b32_e32 v185, v187
	global_store_dwordx4 v[182:183], v[184:187], off offset:128
	s_nop 1
	v_add_co_u32_e32 v158, vcc, s69, v156
	s_nop 1
	v_addc_co_u32_e32 v159, vcc, 0, v157, vcc
	v_mov_b32_e32 v184, v146
	v_mov_b32_e32 v185, v147
	v_mov_b32_e32 v186, v148
	v_mov_b32_e32 v187, v149
	v_bfe_u32 v188, v252, 4, 1
	v_mul_u32_u24_e32 v188, 24, v188
	v_mov_b32_e32 v189, 0
	v_lshl_add_u64 v[182:183], v[158:159], 0, v[188:189]
	v_permlane16_swap_b32_e32 v184, v186
	v_permlane16_swap_b32_e32 v185, v187
	global_store_dwordx4 v[182:183], v[184:187], off offset:128
	s_nop 1
	v_add_co_u32_e32 v158, vcc, s6, v156
	s_nop 1
	v_addc_co_u32_e32 v159, vcc, 0, v157, vcc
	v_mov_b32_e32 v184, v146
	v_mov_b32_e32 v185, v147
	v_mov_b32_e32 v186, v148
	v_mov_b32_e32 v187, v149
	v_bfe_u32 v188, v252, 4, 1
	v_mul_u32_u24_e32 v188, 24, v188
	v_mov_b32_e32 v189, 0
	v_lshl_add_u64 v[182:183], v[158:159], 0, v[188:189]
	v_permlane16_swap_b32_e32 v184, v186
	v_permlane16_swap_b32_e32 v185, v187
	global_store_dwordx4 v[182:183], v[184:187], off offset:128
	s_nop 1
	v_add_co_u32_e32 v158, vcc, s7, v156
	s_nop 1
	v_addc_co_u32_e32 v159, vcc, 0, v157, vcc
	v_add_co_u32_e32 v156, vcc, s28, v156
	v_mov_b32_e32 v184, v146
	v_mov_b32_e32 v185, v147
	v_mov_b32_e32 v186, v148
	v_mov_b32_e32 v187, v149
	v_bfe_u32 v188, v252, 4, 1
	v_mul_u32_u24_e32 v188, 24, v188
	v_mov_b32_e32 v189, 0
	v_lshl_add_u64 v[182:183], v[158:159], 0, v[188:189]
	v_permlane16_swap_b32_e32 v184, v186
	v_permlane16_swap_b32_e32 v185, v187
	global_store_dwordx4 v[182:183], v[184:187], off offset:128
	s_nop 1
	v_addc_co_u32_e32 v157, vcc, 0, v157, vcc
	v_mov_b32_e32 v184, v146
	v_mov_b32_e32 v185, v147
	v_mov_b32_e32 v186, v148
	v_mov_b32_e32 v187, v149
	v_bfe_u32 v188, v252, 4, 1
	v_mul_u32_u24_e32 v188, 24, v188
	v_mov_b32_e32 v189, 0
	v_lshl_add_u64 v[182:183], v[156:157], 0, v[188:189]
	v_permlane16_swap_b32_e32 v184, v186
	v_permlane16_swap_b32_e32 v185, v187
	global_store_dwordx4 v[182:183], v[184:187], off offset:128
	s_nop 1
	ds_read_b32 v146, v154 offset:576
	v_mov_b32_e32 v148, v32
	v_mov_b32_e32 v149, v40
	v_cmp_gt_i32_e32 vcc, 16, v162
	s_waitcnt lgkmcnt(0)
; #define p_rope W_(float2, OFF_ROPE)
; __device__ __forceinline__ u32x2 pack4(float a, float b, float c, float d) { return u32x2{cvtpk(a, b), cvtpk(c, d)}; }
; __device__ __forceinline__ u32x2 pack4(const f32x4& v) { return u32x2{cvtpk(v[0], v[1]), cvtpk(v[2], v[3])}; }
; #define SBAR() __builtin_amdgcn_sched_barrier(0)
; __global__ void __launch_bounds__(512) fwd_megakernel(Params p) {
;     ...
;                 int pos = (brow + ai * 128 + wr * 64 + m * 16 + fr) % LTOK;
;                 csa[m] = *reinterpret_cast<const f32x4*>(p_rope + pos * 16 + fq * 4); csb[m] = *reinterpret_cast<const f32x4*>(p_rope + pos * 16 + fq * 4 + 2);
;               }
;               SBAR();
;               #pragma unroll
;               for (int m = 0; m < 4; ++m) {
;                 int lrow = ai * 128 + wr * 64 + m * 16 + fr, row = brow + lrow; float rs = xl[lrow];
;                 int b = row / LTOK, pos = row - b * LTOK;
;                 const float cs_c[4] = {csa[m][0], csa[m][2], csb[m][0], csb[m][2]}, cs_s[4] = {csa[m][1], csa[m][3], csb[m][1], csb[m][3]};
;                 float o1[4], o2[4];
;                 #pragma unroll
;                 for (int j = 0; j < 4; ++j) { float x1 = acc[ai][0][m][0][j] * rs, x2 = acc[ai][0][m][1][j] * rs;
;                   o1[j] = x1 * cs_c[j] - x2 * cs_s[j]; o2[j] = x2 * cs_c[j] + x1 * cs_s[j]; }
;                 const u32x2 w1 = pack4(o1[0], o1[1], o1[2], o1[3]), w2 = pack4(o2[0], o2[1], o2[2], o2[3]);
;                 int key = pos < NMETA ? SEQ + pos : pos - NMETA;
;                 bf16* kd = p_Kb + ((long)(b * NH) * KPAD + key) * DQK + 64 + fq * 4;
;                 #pragma unroll
;                 for (int h = 0; h < NH; ++h) { *reinterpret_cast<u32x2*>(kd + (long)h * KPAD * DQK) = w1; *reinterpret_cast<u32x2*>(kd + (long)h * KPAD * DQK + 16) = w2; }
	v_pk_mul_f32 v[148:149], v[148:149], v[146:147] op_sel_hi:[1,0]
	s_waitcnt vmcnt(14)
	v_pk_mul_f32 v[156:157], v[164:165], v[148:149] op_sel:[0,1] op_sel_hi:[1,0]
	v_pk_mul_f32 v[148:149], v[164:165], v[148:149]
	v_sub_f32_e32 v158, v156, v157
	v_add_f32_e32 v159, v149, v148
	v_mov_b32_e32 v148, v33
	v_mov_b32_e32 v149, v41
	v_pk_mul_f32 v[148:149], v[148:149], v[146:147] op_sel_hi:[1,0]
	s_nop 0
	v_pk_mul_f32 v[156:157], v[166:167], v[148:149] op_sel:[0,1] op_sel_hi:[1,0]
	v_pk_mul_f32 v[148:149], v[166:167], v[148:149]
	v_sub_f32_e32 v160, v156, v157
	v_add_f32_e32 v161, v149, v148
	v_mov_b32_e32 v148, v34
	v_mov_b32_e32 v149, v42
	v_pk_mul_f32 v[148:149], v[148:149], v[146:147] op_sel_hi:[1,0]
	s_waitcnt vmcnt(13)
	v_pk_mul_f32 v[156:157], v[168:169], v[148:149] op_sel:[0,1] op_sel_hi:[1,0]
	v_pk_mul_f32 v[148:149], v[168:169], v[148:149]
	v_sub_f32_e32 v156, v156, v157
	v_add_f32_e32 v157, v149, v148
	v_mov_b32_e32 v148, v35
	v_mov_b32_e32 v149, v43
	v_pk_mul_f32 v[146:147], v[148:149], v[146:147] op_sel_hi:[1,0]
	s_nop 0
	v_pk_mul_f32 v[148:149], v[170:171], v[146:147] op_sel:[0,1] op_sel_hi:[1,0]
	v_pk_mul_f32 v[146:147], v[170:171], v[146:147]
	v_sub_f32_e32 v148, v148, v149
	v_add_f32_e32 v149, v147, v146
	v_cvt_pk_bf16_f32 v146, v158, v160
	v_cvt_pk_bf16_f32 v147, v156, v148
	v_cndmask_b32_e32 v156, -16, v204, vcc
	v_cvt_pk_bf16_f32 v148, v159, v161
	v_cvt_pk_bf16_f32 v149, v157, v149
	v_add_u32_e32 v156, v156, v162
	v_lshlrev_b32_e32 v157, 3, v177
	v_mul_hi_i32_i24_e32 v159, 0x840, v157
	v_mul_i32_i24_e32 v158, 0x840, v157
	v_ashrrev_i32_e32 v157, 31, v156
	v_lshl_add_u64 v[156:157], v[158:159], 0, v[156:157]
	v_mad_u64_u32 v[158:159], s[4:5], v156, s9, v[144:145]
	v_mov_b32_e32 v156, v159
	v_mad_u64_u32 v[156:157], s[4:5], v157, s9, v[156:157]
	v_mov_b32_e32 v159, v156
	v_lshl_add_u64 v[156:157], v[158:159], 0, v[194:195]
	v_add_co_u32_e32 v160, vcc, s23, v156
	v_lshl_add_u64 v[158:159], v[156:157], 0, s[24:25]
	s_nop 0
	v_addc_co_u32_e32 v161, vcc, 0, v157, vcc
	global_store_dwordx2 v[160:161], v[146:147], off offset:128
	global_store_dwordx2 v[158:159], v[148:149], off offset:32
	v_add_co_u32_e32 v158, vcc, s66, v156
	s_nop 1
	v_addc_co_u32_e32 v159, vcc, 0, v157, vcc
	v_mov_b32_e32 v184, v146
	v_mov_b32_e32 v185, v147
	v_mov_b32_e32 v186, v148
	v_mov_b32_e32 v187, v149
	v_bfe_u32 v188, v252, 4, 1
	v_mul_u32_u24_e32 v188, 24, v188
	v_mov_b32_e32 v189, 0
	v_lshl_add_u64 v[182:183], v[158:159], 0, v[188:189]
	v_permlane16_swap_b32_e32 v184, v186
	v_permlane16_swap_b32_e32 v185, v187
	global_store_dwordx4 v[182:183], v[184:187], off offset:128
	s_nop 1
	v_add_co_u32_e32 v158, vcc, s64, v156
	s_nop 1
	v_addc_co_u32_e32 v159, vcc, 0, v157, vcc
	v_mov_b32_e32 v184, v146
	v_mov_b32_e32 v185, v147
	v_mov_b32_e32 v186, v148
	v_mov_b32_e32 v187, v149
	v_bfe_u32 v188, v252, 4, 1
	v_mul_u32_u24_e32 v188, 24, v188
	v_mov_b32_e32 v189, 0
	v_lshl_add_u64 v[182:183], v[158:159], 0, v[188:189]
	v_permlane16_swap_b32_e32 v184, v186
	v_permlane16_swap_b32_e32 v185, v187
	global_store_dwordx4 v[182:183], v[184:187], off offset:128
	s_nop 1
	v_add_co_u32_e32 v158, vcc, s68, v156
	s_nop 1
	v_addc_co_u32_e32 v159, vcc, 0, v157, vcc
	v_mov_b32_e32 v184, v146
	v_mov_b32_e32 v185, v147
	v_mov_b32_e32 v186, v148
	v_mov_b32_e32 v187, v149
	v_bfe_u32 v188, v252, 4, 1
	v_mul_u32_u24_e32 v188, 24, v188
	v_mov_b32_e32 v189, 0
	v_lshl_add_u64 v[182:183], v[158:159], 0, v[188:189]
	v_permlane16_swap_b32_e32 v184, v186
	v_permlane16_swap_b32_e32 v185, v187
	global_store_dwordx4 v[182:183], v[184:187], off offset:128
	s_nop 1
	v_add_co_u32_e32 v158, vcc, s69, v156
	s_nop 1
	v_addc_co_u32_e32 v159, vcc, 0, v157, vcc
	v_mov_b32_e32 v184, v146
	v_mov_b32_e32 v185, v147
	v_mov_b32_e32 v186, v148
	v_mov_b32_e32 v187, v149
	v_bfe_u32 v188, v252, 4, 1
	v_mul_u32_u24_e32 v188, 24, v188
	v_mov_b32_e32 v189, 0
	v_lshl_add_u64 v[182:183], v[158:159], 0, v[188:189]
	v_permlane16_swap_b32_e32 v184, v186
	v_permlane16_swap_b32_e32 v185, v187
	global_store_dwordx4 v[182:183], v[184:187], off offset:128
	s_nop 1
	v_add_co_u32_e32 v158, vcc, s6, v156
	s_nop 1
	v_addc_co_u32_e32 v159, vcc, 0, v157, vcc
	v_mov_b32_e32 v184, v146
	v_mov_b32_e32 v185, v147
	v_mov_b32_e32 v186, v148
	v_mov_b32_e32 v187, v149
	v_bfe_u32 v188, v252, 4, 1
	v_mul_u32_u24_e32 v188, 24, v188
	v_mov_b32_e32 v189, 0
	v_lshl_add_u64 v[182:183], v[158:159], 0, v[188:189]
	v_permlane16_swap_b32_e32 v184, v186
	v_permlane16_swap_b32_e32 v185, v187
	global_store_dwordx4 v[182:183], v[184:187], off offset:128
	s_nop 1
	v_add_co_u32_e32 v158, vcc, s7, v156
	s_nop 1
	v_addc_co_u32_e32 v159, vcc, 0, v157, vcc
	v_add_co_u32_e32 v156, vcc, s28, v156
	v_mov_b32_e32 v184, v146
	v_mov_b32_e32 v185, v147
	v_mov_b32_e32 v186, v148
	v_mov_b32_e32 v187, v149
	v_bfe_u32 v188, v252, 4, 1
	v_mul_u32_u24_e32 v188, 24, v188
	v_mov_b32_e32 v189, 0
	v_lshl_add_u64 v[182:183], v[158:159], 0, v[188:189]
	v_permlane16_swap_b32_e32 v184, v186
	v_permlane16_swap_b32_e32 v185, v187
	global_store_dwordx4 v[182:183], v[184:187], off offset:128
	s_nop 1
	v_addc_co_u32_e32 v157, vcc, 0, v157, vcc
	v_mov_b32_e32 v184, v146
	v_mov_b32_e32 v185, v147
	v_mov_b32_e32 v186, v148
	v_mov_b32_e32 v187, v149
	v_bfe_u32 v188, v252, 4, 1
	v_mul_u32_u24_e32 v188, 24, v188
	v_mov_b32_e32 v189, 0
	v_lshl_add_u64 v[182:183], v[156:157], 0, v[188:189]
	v_permlane16_swap_b32_e32 v184, v186
	v_permlane16_swap_b32_e32 v185, v187
	global_store_dwordx4 v[182:183], v[184:187], off offset:128
	s_nop 1
	ds_read_b32 v146, v154 offset:640
	v_mov_b32_e32 v148, v16
	v_mov_b32_e32 v149, v24
	s_waitcnt lgkmcnt(0)
	v_pk_mul_f32 v[148:149], v[148:149], v[146:147] op_sel_hi:[1,0]
	s_waitcnt vmcnt(21)
; __device__ __forceinline__ u32x2 pack4(float a, float b, float c, float d) { return u32x2{cvtpk(a, b), cvtpk(c, d)}; }
; __device__ __forceinline__ u32x2 pack4(const f32x4& v) { return u32x2{cvtpk(v[0], v[1]), cvtpk(v[2], v[3])}; }
; __global__ void __launch_bounds__(512) fwd_megakernel(Params p) {
;     ...
;               for (int m = 0; m < 4; ++m) {
;                 int lrow = ai * 128 + wr * 64 + m * 16 + fr, row = brow + lrow; float rs = xl[lrow];
;                 int b = row / LTOK, pos = row - b * LTOK;
;                 const float cs_c[4] = {csa[m][0], csa[m][2], csb[m][0], csb[m][2]}, cs_s[4] = {csa[m][1], csa[m][3], csb[m][1], csb[m][3]};
;                 float o1[4], o2[4];
;                 #pragma unroll
;                 for (int j = 0; j < 4; ++j) { float x1 = acc[ai][0][m][0][j] * rs, x2 = acc[ai][0][m][1][j] * rs;
;                   o1[j] = x1 * cs_c[j] - x2 * cs_s[j]; o2[j] = x2 * cs_c[j] + x1 * cs_s[j]; }
;                 const u32x2 w1 = pack4(o1[0], o1[1], o1[2], o1[3]), w2 = pack4(o2[0], o2[1], o2[2], o2[3]);
;                 int key = pos < NMETA ? SEQ + pos : pos - NMETA;
;                 bf16* kd = p_Kb + ((long)(b * NH) * KPAD + key) * DQK + 64 + fq * 4;
;                 #pragma unroll
;                 for (int h = 0; h < NH; ++h) { *reinterpret_cast<u32x2*>(kd + (long)h * KPAD * DQK) = w1; *reinterpret_cast<u32x2*>(kd + (long)h * KPAD * DQK + 16) = w2; }
;               }
	v_pk_mul_f32 v[156:157], v[140:141], v[148:149] op_sel:[0,1] op_sel_hi:[1,0]
	v_pk_mul_f32 v[140:141], v[140:141], v[148:149]
	v_sub_f32_e32 v147, v156, v157
	v_add_f32_e32 v156, v141, v140
	v_mov_b32_e32 v140, v17
	v_mov_b32_e32 v141, v25
	v_pk_mul_f32 v[140:141], v[140:141], v[146:147] op_sel_hi:[1,0]
	s_nop 0
	v_pk_mul_f32 v[148:149], v[142:143], v[140:141] op_sel:[0,1] op_sel_hi:[1,0]
	v_pk_mul_f32 v[140:141], v[142:143], v[140:141]
	v_sub_f32_e32 v148, v148, v149
	v_add_f32_e32 v149, v141, v140
	v_mov_b32_e32 v140, v18
	v_mov_b32_e32 v141, v26
	v_pk_mul_f32 v[140:141], v[140:141], v[146:147] op_sel_hi:[1,0]
	s_waitcnt vmcnt(20)
	v_pk_mul_f32 v[142:143], v[136:137], v[140:141] op_sel:[0,1] op_sel_hi:[1,0]
	v_pk_mul_f32 v[136:137], v[136:137], v[140:141]
	v_sub_f32_e32 v142, v142, v143
	v_add_f32_e32 v143, v137, v136
	v_mov_b32_e32 v136, v19
	v_mov_b32_e32 v137, v27
	v_pk_mul_f32 v[136:137], v[136:137], v[146:147] op_sel_hi:[1,0]
	s_nop 0
	v_pk_mul_f32 v[140:141], v[138:139], v[136:137] op_sel:[0,1] op_sel_hi:[1,0]
	v_pk_mul_f32 v[136:137], v[138:139], v[136:137]
	v_sub_f32_e32 v140, v140, v141
	v_mad_i32_i24 v141, v179, s22, v178
	v_cmp_gt_i32_e32 vcc, 16, v141
	v_add_f32_e32 v139, v137, v136
	v_cvt_pk_bf16_f32 v136, v147, v148
	v_cvt_pk_bf16_f32 v137, v142, v140
	v_cvt_pk_bf16_f32 v138, v156, v149
	v_cvt_pk_bf16_f32 v139, v143, v139
	s_nop 0
	v_cndmask_b32_e32 v140, -16, v204, vcc
	v_add_u32_e32 v140, v140, v141
	v_lshlrev_b32_e32 v141, 3, v179
	v_mul_hi_i32_i24_e32 v143, 0x840, v141
	v_mul_i32_i24_e32 v142, 0x840, v141
	v_ashrrev_i32_e32 v141, 31, v140
	v_lshl_add_u64 v[140:141], v[142:143], 0, v[140:141]
	v_mad_u64_u32 v[142:143], s[4:5], v140, s9, v[144:145]
	v_mov_b32_e32 v140, v143
	v_mad_u64_u32 v[140:141], s[4:5], v141, s9, v[140:141]
	v_mov_b32_e32 v143, v140
	v_lshl_add_u64 v[140:141], v[142:143], 0, v[194:195]
	v_add_co_u32_e32 v146, vcc, s23, v140
	v_lshl_add_u64 v[142:143], v[140:141], 0, s[24:25]
	s_nop 0
	v_addc_co_u32_e32 v147, vcc, 0, v141, vcc
	global_store_dwordx2 v[146:147], v[136:137], off offset:128
	global_store_dwordx2 v[142:143], v[138:139], off offset:32
	v_add_co_u32_e32 v142, vcc, s66, v140
	s_nop 1
	v_addc_co_u32_e32 v143, vcc, 0, v141, vcc
	v_mov_b32_e32 v184, v136
	v_mov_b32_e32 v185, v137
	v_mov_b32_e32 v186, v138
	v_mov_b32_e32 v187, v139
	v_bfe_u32 v188, v252, 4, 1
	v_mul_u32_u24_e32 v188, 24, v188
	v_mov_b32_e32 v189, 0
	v_lshl_add_u64 v[182:183], v[142:143], 0, v[188:189]
	v_permlane16_swap_b32_e32 v184, v186
	v_permlane16_swap_b32_e32 v185, v187
	global_store_dwordx4 v[182:183], v[184:187], off offset:128
	s_nop 1
	v_add_co_u32_e32 v142, vcc, s64, v140
	s_nop 1
	v_addc_co_u32_e32 v143, vcc, 0, v141, vcc
	v_mov_b32_e32 v184, v136
	v_mov_b32_e32 v185, v137
	v_mov_b32_e32 v186, v138
	v_mov_b32_e32 v187, v139
	v_bfe_u32 v188, v252, 4, 1
	v_mul_u32_u24_e32 v188, 24, v188
	v_mov_b32_e32 v189, 0
	v_lshl_add_u64 v[182:183], v[142:143], 0, v[188:189]
	v_permlane16_swap_b32_e32 v184, v186
	v_permlane16_swap_b32_e32 v185, v187
	global_store_dwordx4 v[182:183], v[184:187], off offset:128
	s_nop 1
	v_add_co_u32_e32 v142, vcc, s68, v140
	s_nop 1
	v_addc_co_u32_e32 v143, vcc, 0, v141, vcc
	v_mov_b32_e32 v184, v136
	v_mov_b32_e32 v185, v137
	v_mov_b32_e32 v186, v138
	v_mov_b32_e32 v187, v139
	v_bfe_u32 v188, v252, 4, 1
	v_mul_u32_u24_e32 v188, 24, v188
	v_mov_b32_e32 v189, 0
	v_lshl_add_u64 v[182:183], v[142:143], 0, v[188:189]
	v_permlane16_swap_b32_e32 v184, v186
	v_permlane16_swap_b32_e32 v185, v187
	global_store_dwordx4 v[182:183], v[184:187], off offset:128
	s_nop 1
	v_add_co_u32_e32 v142, vcc, s69, v140
	s_nop 1
	v_addc_co_u32_e32 v143, vcc, 0, v141, vcc
	v_mov_b32_e32 v184, v136
	v_mov_b32_e32 v185, v137
	v_mov_b32_e32 v186, v138
	v_mov_b32_e32 v187, v139
	v_bfe_u32 v188, v252, 4, 1
	v_mul_u32_u24_e32 v188, 24, v188
	v_mov_b32_e32 v189, 0
	v_lshl_add_u64 v[182:183], v[142:143], 0, v[188:189]
	v_permlane16_swap_b32_e32 v184, v186
	v_permlane16_swap_b32_e32 v185, v187
	global_store_dwordx4 v[182:183], v[184:187], off offset:128
	s_nop 1
	v_add_co_u32_e32 v142, vcc, s6, v140
	s_nop 1
	v_addc_co_u32_e32 v143, vcc, 0, v141, vcc
	v_mov_b32_e32 v184, v136
	v_mov_b32_e32 v185, v137
	v_mov_b32_e32 v186, v138
	v_mov_b32_e32 v187, v139
	v_bfe_u32 v188, v252, 4, 1
	v_mul_u32_u24_e32 v188, 24, v188
	v_mov_b32_e32 v189, 0
	v_lshl_add_u64 v[182:183], v[142:143], 0, v[188:189]
	v_permlane16_swap_b32_e32 v184, v186
	v_permlane16_swap_b32_e32 v185, v187
	global_store_dwordx4 v[182:183], v[184:187], off offset:128
	s_nop 1
	v_add_co_u32_e32 v142, vcc, s7, v140
	s_nop 1
	v_addc_co_u32_e32 v143, vcc, 0, v141, vcc
	v_add_co_u32_e32 v140, vcc, s28, v140
	v_mov_b32_e32 v184, v136
	v_mov_b32_e32 v185, v137
	v_mov_b32_e32 v186, v138
	v_mov_b32_e32 v187, v139
	v_bfe_u32 v188, v252, 4, 1
	v_mul_u32_u24_e32 v188, 24, v188
	v_mov_b32_e32 v189, 0
	v_lshl_add_u64 v[182:183], v[142:143], 0, v[188:189]
	v_permlane16_swap_b32_e32 v184, v186
	v_permlane16_swap_b32_e32 v185, v187
	global_store_dwordx4 v[182:183], v[184:187], off offset:128
	s_nop 1
	v_addc_co_u32_e32 v141, vcc, 0, v141, vcc
	v_mov_b32_e32 v184, v136
	v_mov_b32_e32 v185, v137
	v_mov_b32_e32 v186, v138
	v_mov_b32_e32 v187, v139
	v_bfe_u32 v188, v252, 4, 1
	v_mul_u32_u24_e32 v188, 24, v188
	v_mov_b32_e32 v189, 0
	v_lshl_add_u64 v[182:183], v[140:141], 0, v[188:189]
	v_permlane16_swap_b32_e32 v184, v186
	v_permlane16_swap_b32_e32 v185, v187
	global_store_dwordx4 v[182:183], v[184:187], off offset:128
	s_nop 1
	ds_read_b32 v136, v154 offset:704
	v_mov_b32_e32 v138, v0
	v_mov_b32_e32 v139, v8
	s_waitcnt lgkmcnt(0)
; __device__ __forceinline__ u32x2 pack4(float a, float b, float c, float d) { return u32x2{cvtpk(a, b), cvtpk(c, d)}; }
; __device__ __forceinline__ u32x2 pack4(const f32x4& v) { return u32x2{cvtpk(v[0], v[1]), cvtpk(v[2], v[3])}; }
; __global__ void __launch_bounds__(512) fwd_megakernel(Params p) {
;     ...
;               for (int m = 0; m < 4; ++m) {
;                 int lrow = ai * 128 + wr * 64 + m * 16 + fr, row = brow + lrow; float rs = xl[lrow];
;                 int b = row / LTOK, pos = row - b * LTOK;
;                 const float cs_c[4] = {csa[m][0], csa[m][2], csb[m][0], csb[m][2]}, cs_s[4] = {csa[m][1], csa[m][3], csb[m][1], csb[m][3]};
;                 float o1[4], o2[4];
;                 #pragma unroll
;                 for (int j = 0; j < 4; ++j) { float x1 = acc[ai][0][m][0][j] * rs, x2 = acc[ai][0][m][1][j] * rs;
;                   o1[j] = x1 * cs_c[j] - x2 * cs_s[j]; o2[j] = x2 * cs_c[j] + x1 * cs_s[j]; }
;                 const u32x2 w1 = pack4(o1[0], o1[1], o1[2], o1[3]), w2 = pack4(o2[0], o2[1], o2[2], o2[3]);
;                 int key = pos < NMETA ? SEQ + pos : pos - NMETA;
;                 bf16* kd = p_Kb + ((long)(b * NH) * KPAD + key) * DQK + 64 + fq * 4;
;                 #pragma unroll
;                 for (int h = 0; h < NH; ++h) { *reinterpret_cast<u32x2*>(kd + (long)h * KPAD * DQK) = w1; *reinterpret_cast<u32x2*>(kd + (long)h * KPAD * DQK + 16) = w2; }
;               }
	v_pk_mul_f32 v[138:139], v[138:139], v[136:137] op_sel_hi:[1,0]
	s_waitcnt vmcnt(28)
	v_pk_mul_f32 v[140:141], v[132:133], v[138:139] op_sel:[0,1] op_sel_hi:[1,0]
	v_pk_mul_f32 v[132:133], v[132:133], v[138:139]
	v_sub_f32_e32 v137, v140, v141
	v_add_f32_e32 v140, v133, v132
	v_mov_b32_e32 v132, v1
	v_mov_b32_e32 v133, v9
	v_pk_mul_f32 v[132:133], v[132:133], v[136:137] op_sel_hi:[1,0]
	s_nop 0
	v_pk_mul_f32 v[138:139], v[134:135], v[132:133] op_sel:[0,1] op_sel_hi:[1,0]
	v_pk_mul_f32 v[132:133], v[134:135], v[132:133]
	v_sub_f32_e32 v138, v138, v139
	v_add_f32_e32 v139, v133, v132
	v_mov_b32_e32 v132, v2
	v_mov_b32_e32 v133, v10
	v_pk_mul_f32 v[132:133], v[132:133], v[136:137] op_sel_hi:[1,0]
	s_waitcnt vmcnt(27)
	v_pk_mul_f32 v[134:135], v[128:129], v[132:133] op_sel:[0,1] op_sel_hi:[1,0]
	v_pk_mul_f32 v[128:129], v[128:129], v[132:133]
	v_sub_f32_e32 v134, v134, v135
	v_add_f32_e32 v135, v129, v128
	v_mov_b32_e32 v128, v3
	v_mov_b32_e32 v129, v11
	v_pk_mul_f32 v[128:129], v[128:129], v[136:137] op_sel_hi:[1,0]
	s_nop 0
	v_pk_mul_f32 v[132:133], v[130:131], v[128:129] op_sel:[0,1] op_sel_hi:[1,0]
	v_pk_mul_f32 v[128:129], v[130:131], v[128:129]
	v_sub_f32_e32 v132, v132, v133
	v_mad_i32_i24 v133, v180, s22, v155
	v_cmp_gt_i32_e32 vcc, 16, v133
	v_add_f32_e32 v131, v129, v128
	v_cvt_pk_bf16_f32 v128, v137, v138
	v_cvt_pk_bf16_f32 v129, v134, v132
	v_cvt_pk_bf16_f32 v130, v140, v139
	v_cvt_pk_bf16_f32 v131, v135, v131
	s_nop 0
	v_cndmask_b32_e32 v132, -16, v204, vcc
	v_add_u32_e32 v132, v132, v133
	v_lshlrev_b32_e32 v133, 3, v180
	v_mul_hi_i32_i24_e32 v135, 0x840, v133
	v_mul_i32_i24_e32 v134, 0x840, v133
	v_ashrrev_i32_e32 v133, 31, v132
	v_lshl_add_u64 v[132:133], v[134:135], 0, v[132:133]
	v_mad_u64_u32 v[134:135], s[4:5], v132, s9, v[144:145]
	v_mov_b32_e32 v132, v135
	v_mad_u64_u32 v[132:133], s[4:5], v133, s9, v[132:133]
	v_mov_b32_e32 v135, v132
	v_lshl_add_u64 v[132:133], v[134:135], 0, v[194:195]
	v_add_co_u32_e32 v136, vcc, s23, v132
	v_lshl_add_u64 v[134:135], v[132:133], 0, s[24:25]
	s_nop 0
	v_addc_co_u32_e32 v137, vcc, 0, v133, vcc
	global_store_dwordx2 v[136:137], v[128:129], off offset:128
	global_store_dwordx2 v[134:135], v[130:131], off offset:32
	v_add_co_u32_e32 v134, vcc, s66, v132
	s_nop 1
	v_addc_co_u32_e32 v135, vcc, 0, v133, vcc
	v_mov_b32_e32 v184, v128
	v_mov_b32_e32 v185, v129
	v_mov_b32_e32 v186, v130
	v_mov_b32_e32 v187, v131
	v_bfe_u32 v188, v252, 4, 1
	v_mul_u32_u24_e32 v188, 24, v188
	v_mov_b32_e32 v189, 0
	v_lshl_add_u64 v[182:183], v[134:135], 0, v[188:189]
	v_permlane16_swap_b32_e32 v184, v186
	v_permlane16_swap_b32_e32 v185, v187
	global_store_dwordx4 v[182:183], v[184:187], off offset:128
	s_nop 1
	v_add_co_u32_e32 v134, vcc, s64, v132
	s_nop 1
	v_addc_co_u32_e32 v135, vcc, 0, v133, vcc
	v_mov_b32_e32 v184, v128
	v_mov_b32_e32 v185, v129
	v_mov_b32_e32 v186, v130
	v_mov_b32_e32 v187, v131
	v_bfe_u32 v188, v252, 4, 1
	v_mul_u32_u24_e32 v188, 24, v188
	v_mov_b32_e32 v189, 0
	v_lshl_add_u64 v[182:183], v[134:135], 0, v[188:189]
	v_permlane16_swap_b32_e32 v184, v186
	v_permlane16_swap_b32_e32 v185, v187
	global_store_dwordx4 v[182:183], v[184:187], off offset:128
	s_nop 1
	v_add_co_u32_e32 v134, vcc, s68, v132
	s_nop 1
	v_addc_co_u32_e32 v135, vcc, 0, v133, vcc
	v_mov_b32_e32 v184, v128
	v_mov_b32_e32 v185, v129
	v_mov_b32_e32 v186, v130
	v_mov_b32_e32 v187, v131
	v_bfe_u32 v188, v252, 4, 1
	v_mul_u32_u24_e32 v188, 24, v188
	v_mov_b32_e32 v189, 0
	v_lshl_add_u64 v[182:183], v[134:135], 0, v[188:189]
	v_permlane16_swap_b32_e32 v184, v186
	v_permlane16_swap_b32_e32 v185, v187
	global_store_dwordx4 v[182:183], v[184:187], off offset:128
	s_nop 1
	v_add_co_u32_e32 v134, vcc, s69, v132
	s_nop 1
	v_addc_co_u32_e32 v135, vcc, 0, v133, vcc
	v_mov_b32_e32 v184, v128
	v_mov_b32_e32 v185, v129
	v_mov_b32_e32 v186, v130
	v_mov_b32_e32 v187, v131
	v_bfe_u32 v188, v252, 4, 1
	v_mul_u32_u24_e32 v188, 24, v188
	v_mov_b32_e32 v189, 0
	v_lshl_add_u64 v[182:183], v[134:135], 0, v[188:189]
	v_permlane16_swap_b32_e32 v184, v186
	v_permlane16_swap_b32_e32 v185, v187
	global_store_dwordx4 v[182:183], v[184:187], off offset:128
	s_nop 1
	v_add_co_u32_e32 v134, vcc, 0x930f000, v132
	s_nop 1
	v_addc_co_u32_e32 v135, vcc, 0, v133, vcc
	v_mov_b32_e32 v184, v128
	v_mov_b32_e32 v185, v129
	v_mov_b32_e32 v186, v130
	v_mov_b32_e32 v187, v131
	v_bfe_u32 v188, v252, 4, 1
	v_mul_u32_u24_e32 v188, 24, v188
	v_mov_b32_e32 v189, 0
	v_lshl_add_u64 v[182:183], v[134:135], 0, v[188:189]
	v_permlane16_swap_b32_e32 v184, v186
	v_permlane16_swap_b32_e32 v185, v187
	global_store_dwordx4 v[182:183], v[184:187], off offset:128
	s_nop 1
	v_add_co_u32_e32 v134, vcc, 0x9372000, v132
	s_nop 1
	v_addc_co_u32_e32 v135, vcc, 0, v133, vcc
	v_add_co_u32_e32 v132, vcc, 0x93d5000, v132
	v_mov_b32_e32 v184, v128
	v_mov_b32_e32 v185, v129
	v_mov_b32_e32 v186, v130
	v_mov_b32_e32 v187, v131
	v_bfe_u32 v188, v252, 4, 1
	v_mul_u32_u24_e32 v188, 24, v188
	v_mov_b32_e32 v189, 0
	v_lshl_add_u64 v[182:183], v[134:135], 0, v[188:189]
	v_permlane16_swap_b32_e32 v184, v186
	v_permlane16_swap_b32_e32 v185, v187
	global_store_dwordx4 v[182:183], v[184:187], off offset:128
	s_nop 1
	v_addc_co_u32_e32 v133, vcc, 0, v133, vcc
	v_mov_b32_e32 v184, v128
	v_mov_b32_e32 v185, v129
	v_mov_b32_e32 v186, v130
	v_mov_b32_e32 v187, v131
	v_bfe_u32 v188, v252, 4, 1
	v_mul_u32_u24_e32 v188, 24, v188
	v_mov_b32_e32 v189, 0
	v_lshl_add_u64 v[182:183], v[132:133], 0, v[188:189]
	v_permlane16_swap_b32_e32 v184, v186
	v_permlane16_swap_b32_e32 v185, v187
	global_store_dwordx4 v[182:183], v[184:187], off offset:128
	s_nop 1

; #define p_rstdq W_(float, OFF_RSTDQ)
; #define p_rstdkv W_(float, OFF_RSTDKV)
; __device__ __forceinline__ u32x2 pack4(float a, float b, float c, float d) { return u32x2{cvtpk(a, b), cvtpk(c, d)}; }
; __device__ __forceinline__ u32x2 pack4(const f32x4& v) { return u32x2{cvtpk(v[0], v[1]), cvtpk(v[2], v[3])}; }
; #define SBAR() __builtin_amdgcn_sched_barrier(0)
; __global__ void __launch_bounds__(512) fwd_megakernel(Params p) {
;     ...
;         } else if (pn < 6) {
;           bf16* dst = pn == 4 ? p_cq : p_ckv; float* rdst = pn == 4 ? p_rstdq : p_rstdkv;
;           float* red = (float*)(shm_raw + EPI_LDS_OFF);
;           #pragma unroll
;           for (int ai = 0; ai < 2; ++ai)
;             #pragma unroll
;             for (int m = 0; m < 4; ++m) { SBAR();
;               int lrow = ai * 128 + wr * 64 + m * 16 + fr, row = brow + lrow; float rs = xl[lrow]; float ss = 0.f;
;               #pragma unroll
;               for (int bj = 0; bj < 2; ++bj)
;                 #pragma unroll
;                 for (int n = 0; n < 2; ++n) {
;                   f32x4 v = acc[ai][bj][m][n] * rs; ss += (v[0] * v[0] + v[1] * v[1]) + (v[2] * v[2] + v[3] * v[3]);
;                   *reinterpret_cast<u32x2*>(dst + (long)row * 256 + bj * 128 + wc * 32 + n * 16 + fq * 4) = pack4(v);
;                 }
;               ss += __shfl_xor(ss, 16); ss += __shfl_xor(ss, 32);
;               if (fq == 0) red[wc * 256 + lrow] = ss;
;             }
;           asm volatile("s_waitcnt lgkmcnt(0)" ::: "memory"); __builtin_amdgcn_s_barrier();
;           if (tid < 256) { float s = red[tid] + red[256 + tid] + red[512 + tid] + red[768 + tid]; rdst[brow + tid] = rsqrtf(s * (1.f / 256.f) + EPS); }
.LBB0_283:
	s_andn2_b64 vcc, exec, s[0:1]
	s_cbranch_vccnz .LBB0_303
	s_cmp_eq_u32 s76, 4
	s_cselect_b64 s[4:5], -1, 0
	s_and_b64 s[0:1], s[4:5], exec
	s_brev_b32 s0, 48
	s_cselect_b32 s0, s0, 0xf060000
	s_add_u32 s0, s58, s0
	s_addc_u32 s1, s59, 0
	v_lshlrev_b32_e32 v194, 6, v151
	v_lshl_add_u64 v[128:129], s[0:1], 0, v[194:195]
	v_lshlrev_b32_e32 v194, 3, v150
	v_lshl_or_b32 v135, v152, 6, v153
	v_lshl_add_u64 v[128:129], v[128:129], 0, v[194:195]
	v_cmp_eq_u32_e32 vcc, 0, v150
	v_readlane_b32 s0, v254, 33
	s_nop 1
	v_lshl_add_u32 v142, v151, 10, s0
	v_lshl_add_u32 v131, v135, 2, 0
	v_add_u32_e32 v132, 0x20000, v131
	ds_read_b32 v134, v132
	v_add_u32_e32 v130, s80, v135
	v_ashrrev_i32_e32 v131, 31, v130
	v_lshlrev_b64 v[136:137], 9, v[130:131]
	v_lshl_add_u64 v[136:137], v[128:129], 0, v[136:137]
	s_waitcnt lgkmcnt(0)
	v_pk_mul_f32 v[140:141], v[120:121], v[134:135] op_sel_hi:[1,0]
	v_pk_mul_f32 v[138:139], v[122:123], v[134:135] op_sel_hi:[1,0]
	v_mul_f32_e32 v131, v141, v141
	v_fmac_f32_e32 v131, v140, v140
	v_mul_f32_e32 v133, v139, v139
	v_cvt_pk_bf16_f32 v140, v140, v141
	v_cvt_pk_bf16_f32 v141, v138, v139
	v_fmac_f32_e32 v133, v138, v138
	v_mov_b32_e32 v184, v140
	v_mov_b32_e32 v185, v141
	v_pk_mul_f32 v[138:139], v[114:115], v[134:135] op_sel_hi:[1,0]
	v_pk_mul_f32 v[140:141], v[112:113], v[134:135] op_sel_hi:[1,0]
	v_add_f32_e32 v131, v131, v133
	v_mul_f32_e32 v133, v141, v141
	v_mul_f32_e32 v143, v139, v139
	v_fmac_f32_e32 v133, v140, v140
	v_fmac_f32_e32 v143, v138, v138
	v_cvt_pk_bf16_f32 v140, v140, v141
	v_cvt_pk_bf16_f32 v141, v138, v139
	v_add_f32_e32 v133, v133, v143
	v_mov_b32_e32 v186, v140
	v_mov_b32_e32 v187, v141
	v_bfe_u32 v188, v252, 4, 1
	v_mul_u32_u24_e32 v188, 24, v188
	v_mov_b32_e32 v189, 0
	v_lshl_add_u64 v[182:183], v[136:137], 0, v[188:189]
	v_permlane16_swap_b32_e32 v184, v186
	v_permlane16_swap_b32_e32 v185, v187
	global_store_dwordx4 v[182:183], v[184:187], off
	s_nop 1
	v_pk_mul_f32 v[138:139], v[126:127], v[134:135] op_sel_hi:[1,0]
	v_pk_mul_f32 v[140:141], v[124:125], v[134:135] op_sel_hi:[1,0]
	v_add_f32_e32 v131, v131, v133
	v_mul_f32_e32 v133, v141, v141
	v_mul_f32_e32 v143, v139, v139
	v_fmac_f32_e32 v133, v140, v140
	v_fmac_f32_e32 v143, v138, v138
	v_cvt_pk_bf16_f32 v140, v140, v141
	v_cvt_pk_bf16_f32 v141, v138, v139
	v_add_f32_e32 v133, v133, v143
	v_mov_b32_e32 v184, v140
	v_mov_b32_e32 v185, v141
	v_pk_mul_f32 v[138:139], v[118:119], v[134:135] op_sel_hi:[1,0]
	v_pk_mul_f32 v[140:141], v[116:117], v[134:135] op_sel_hi:[1,0]
	v_add_f32_e32 v131, v133, v131
	v_mul_f32_e32 v133, v141, v141
	v_mul_f32_e32 v134, v139, v139
	v_fmac_f32_e32 v133, v140, v140
	v_fmac_f32_e32 v134, v138, v138
	v_add_f32_e32 v133, v133, v134
	v_and_b32_e32 v134, 64, v205
	v_add_f32_e32 v131, v133, v131
	v_xor_b32_e32 v133, 16, v205
	v_add_u32_e32 v134, 64, v134
	v_cmp_lt_i32_e64 s[0:1], v133, v134
	v_cvt_pk_bf16_f32 v140, v140, v141
	v_cvt_pk_bf16_f32 v141, v138, v139
	v_mov_b32_e32 v186, v140
	v_mov_b32_e32 v187, v141
	v_bfe_u32 v188, v252, 4, 1
	v_mul_u32_u24_e32 v188, 24, v188
	v_mov_b32_e32 v189, 0
	v_lshl_add_u64 v[182:183], v[136:137], 0, v[188:189]
	v_permlane16_swap_b32_e32 v184, v186
	v_permlane16_swap_b32_e32 v185, v187
	global_store_dwordx4 v[182:183], v[184:187], off offset:256
	s_nop 1
	s_nop 0
	v_cndmask_b32_e64 v133, v205, v133, s[0:1]
	v_lshlrev_b32_e32 v133, 2, v133
	ds_bpermute_b32 v136, v133, v131
	s_waitcnt lgkmcnt(0)
	v_add_f32_e32 v136, v131, v136
	v_xor_b32_e32 v131, 32, v205
	v_cmp_lt_i32_e64 s[0:1], v131, v134
	s_nop 1
	v_cndmask_b32_e64 v131, v205, v131, s[0:1]
	v_lshlrev_b32_e32 v134, 2, v131
	ds_bpermute_b32 v137, v134, v136
	v_lshl_add_u32 v131, v135, 2, v142
	s_and_saveexec_b64 s[0:1], vcc
	s_cbranch_execz .LBB0_286
	s_waitcnt lgkmcnt(0)
	v_add_f32_e32 v136, v136, v137
	ds_write_b32 v131, v136
.LBB0_286:
	s_or_b64 exec, exec, s[0:1]
	s_waitcnt lgkmcnt(0)
	v_or_b32_e32 v137, 16, v135
	v_add_u32_e32 v136, s80, v137
	v_lshl_add_u32 v137, v137, 2, 0
	v_add_u32_e32 v137, 0x20000, v137
	ds_read_b32 v138, v137
	v_ashrrev_i32_e32 v137, 31, v136
	v_lshlrev_b64 v[136:137], 9, v[136:137]
	v_lshl_add_u64 v[136:137], v[128:129], 0, v[136:137]
	s_waitcnt lgkmcnt(0)
	v_pk_mul_f32 v[140:141], v[106:107], v[138:139] op_sel_hi:[1,0]
	v_pk_mul_f32 v[142:143], v[104:105], v[138:139] op_sel_hi:[1,0]
	v_mul_f32_e32 v144, v141, v141
	v_mul_f32_e32 v139, v143, v143
	v_fmac_f32_e32 v139, v142, v142
	v_fmac_f32_e32 v144, v140, v140
	v_add_f32_e32 v139, v139, v144
	v_cvt_pk_bf16_f32 v142, v142, v143
	v_cvt_pk_bf16_f32 v143, v140, v141
	v_mov_b32_e32 v184, v142
	v_mov_b32_e32 v185, v143
	v_pk_mul_f32 v[140:141], v[98:99], v[138:139] op_sel_hi:[1,0]
	v_pk_mul_f32 v[142:143], v[96:97], v[138:139] op_sel_hi:[1,0]
	v_mul_f32_e32 v145, v141, v141
	v_mul_f32_e32 v144, v143, v143
	v_fmac_f32_e32 v144, v142, v142
	v_fmac_f32_e32 v145, v140, v140
	v_add_f32_e32 v144, v144, v145
	v_add_f32_e32 v139, v139, v144
	v_cvt_pk_bf16_f32 v142, v142, v143
	v_cvt_pk_bf16_f32 v143, v140, v141
	v_mov_b32_e32 v186, v142
	v_mov_b32_e32 v187, v143
	v_bfe_u32 v188, v252, 4, 1
	v_mul_u32_u24_e32 v188, 24, v188
	v_mov_b32_e32 v189, 0
	v_lshl_add_u64 v[182:183], v[136:137], 0, v[188:189]
	v_permlane16_swap_b32_e32 v184, v186
	v_permlane16_swap_b32_e32 v185, v187
	global_store_dwordx4 v[182:183], v[184:187], off
	s_nop 1
	v_pk_mul_f32 v[140:141], v[110:111], v[138:139] op_sel_hi:[1,0]
	v_pk_mul_f32 v[142:143], v[108:109], v[138:139] op_sel_hi:[1,0]
	v_mul_f32_e32 v145, v141, v141
	v_mul_f32_e32 v144, v143, v143
	v_fmac_f32_e32 v144, v142, v142
	v_fmac_f32_e32 v145, v140, v140
	v_add_f32_e32 v144, v144, v145
	v_add_f32_e32 v144, v144, v139
	v_cvt_pk_bf16_f32 v142, v142, v143
	v_cvt_pk_bf16_f32 v143, v140, v141
	v_pk_mul_f32 v[140:141], v[102:103], v[138:139] op_sel_hi:[1,0]
	v_pk_mul_f32 v[138:139], v[100:101], v[138:139] op_sel_hi:[1,0]
	v_mov_b32_e32 v184, v142
	v_mov_b32_e32 v185, v143
	v_mul_f32_e32 v142, v139, v139
	v_mul_f32_e32 v143, v141, v141
	v_fmac_f32_e32 v142, v138, v138
	v_fmac_f32_e32 v143, v140, v140
	v_add_f32_e32 v142, v142, v143
	v_add_f32_e32 v142, v142, v144
	v_cvt_pk_bf16_f32 v138, v138, v139
	v_cvt_pk_bf16_f32 v139, v140, v141
	v_mov_b32_e32 v186, v138
	v_mov_b32_e32 v187, v139
	v_bfe_u32 v188, v252, 4, 1
	v_mul_u32_u24_e32 v188, 24, v188
	v_mov_b32_e32 v189, 0
	v_lshl_add_u64 v[182:183], v[136:137], 0, v[188:189]
	v_permlane16_swap_b32_e32 v184, v186
	v_permlane16_swap_b32_e32 v185, v187
	global_store_dwordx4 v[182:183], v[184:187], off offset:256
	s_nop 1
	ds_bpermute_b32 v136, v133, v142
	s_waitcnt lgkmcnt(0)
	v_add_f32_e32 v136, v142, v136
	ds_bpermute_b32 v137, v134, v136
	s_and_saveexec_b64 s[0:1], vcc
	s_cbranch_execz .LBB0_288
	s_waitcnt lgkmcnt(0)
	v_add_f32_e32 v136, v136, v137
	ds_write_b32 v131, v136 offset:64
; __device__ __forceinline__ u32x2 pack4(float a, float b, float c, float d) { return u32x2{cvtpk(a, b), cvtpk(c, d)}; }
; __device__ __forceinline__ u32x2 pack4(const f32x4& v) { return u32x2{cvtpk(v[0], v[1]), cvtpk(v[2], v[3])}; }
; #define SBAR() __builtin_amdgcn_sched_barrier(0)
; __global__ void __launch_bounds__(512) fwd_megakernel(Params p) {
;     ...
;           for (int ai = 0; ai < 2; ++ai)
;             #pragma unroll
;             for (int m = 0; m < 4; ++m) { SBAR();
;               int lrow = ai * 128 + wr * 64 + m * 16 + fr, row = brow + lrow; float rs = xl[lrow]; float ss = 0.f;
;               #pragma unroll
;               for (int bj = 0; bj < 2; ++bj)
;                 #pragma unroll
;                 for (int n = 0; n < 2; ++n) {
;                   f32x4 v = acc[ai][bj][m][n] * rs; ss += (v[0] * v[0] + v[1] * v[1]) + (v[2] * v[2] + v[3] * v[3]);
;                   *reinterpret_cast<u32x2*>(dst + (long)row * 256 + bj * 128 + wc * 32 + n * 16 + fq * 4) = pack4(v);
;                 }
;               ss += __shfl_xor(ss, 16); ss += __shfl_xor(ss, 32);
;               if (fq == 0) red[wc * 256 + lrow] = ss;
.LBB0_288:
	s_or_b64 exec, exec, s[0:1]
	s_waitcnt lgkmcnt(0)
	v_or_b32_e32 v137, 32, v135
	v_add_u32_e32 v136, s80, v137
	v_lshl_add_u32 v137, v137, 2, 0
	v_add_u32_e32 v137, 0x20000, v137
	ds_read_b32 v138, v137
	v_ashrrev_i32_e32 v137, 31, v136
	v_lshlrev_b64 v[136:137], 9, v[136:137]
	v_lshl_add_u64 v[136:137], v[128:129], 0, v[136:137]
	s_waitcnt lgkmcnt(0)
	v_pk_mul_f32 v[140:141], v[90:91], v[138:139] op_sel_hi:[1,0]
	v_pk_mul_f32 v[142:143], v[88:89], v[138:139] op_sel_hi:[1,0]
	v_mul_f32_e32 v144, v141, v141
	v_mul_f32_e32 v139, v143, v143
	v_fmac_f32_e32 v139, v142, v142
	v_fmac_f32_e32 v144, v140, v140
	v_add_f32_e32 v139, v139, v144
	v_cvt_pk_bf16_f32 v142, v142, v143
	v_cvt_pk_bf16_f32 v143, v140, v141
	v_mov_b32_e32 v184, v142
	v_mov_b32_e32 v185, v143
	v_pk_mul_f32 v[140:141], v[82:83], v[138:139] op_sel_hi:[1,0]
	v_pk_mul_f32 v[142:143], v[80:81], v[138:139] op_sel_hi:[1,0]
	v_mul_f32_e32 v145, v141, v141
	v_mul_f32_e32 v144, v143, v143
	v_fmac_f32_e32 v144, v142, v142
	v_fmac_f32_e32 v145, v140, v140
	v_add_f32_e32 v144, v144, v145
	v_add_f32_e32 v139, v139, v144
	v_cvt_pk_bf16_f32 v142, v142, v143
	v_cvt_pk_bf16_f32 v143, v140, v141
	v_mov_b32_e32 v186, v142
	v_mov_b32_e32 v187, v143
	v_bfe_u32 v188, v252, 4, 1
	v_mul_u32_u24_e32 v188, 24, v188
	v_mov_b32_e32 v189, 0
	v_lshl_add_u64 v[182:183], v[136:137], 0, v[188:189]
	v_permlane16_swap_b32_e32 v184, v186
	v_permlane16_swap_b32_e32 v185, v187
	global_store_dwordx4 v[182:183], v[184:187], off
	s_nop 1
	v_pk_mul_f32 v[140:141], v[94:95], v[138:139] op_sel_hi:[1,0]
	v_pk_mul_f32 v[142:143], v[92:93], v[138:139] op_sel_hi:[1,0]
	v_mul_f32_e32 v145, v141, v141
	v_mul_f32_e32 v144, v143, v143
	v_fmac_f32_e32 v144, v142, v142
	v_fmac_f32_e32 v145, v140, v140
	v_add_f32_e32 v144, v144, v145
	v_add_f32_e32 v144, v144, v139
	v_cvt_pk_bf16_f32 v142, v142, v143
	v_cvt_pk_bf16_f32 v143, v140, v141
	v_pk_mul_f32 v[140:141], v[86:87], v[138:139] op_sel_hi:[1,0]
	v_pk_mul_f32 v[138:139], v[84:85], v[138:139] op_sel_hi:[1,0]
	v_mov_b32_e32 v184, v142
	v_mov_b32_e32 v185, v143
	v_mul_f32_e32 v142, v139, v139
	v_mul_f32_e32 v143, v141, v141
	v_fmac_f32_e32 v142, v138, v138
	v_fmac_f32_e32 v143, v140, v140
	v_add_f32_e32 v142, v142, v143
	v_add_f32_e32 v142, v142, v144
	v_cvt_pk_bf16_f32 v138, v138, v139
	v_cvt_pk_bf16_f32 v139, v140, v141
	v_mov_b32_e32 v186, v138
	v_mov_b32_e32 v187, v139
	v_bfe_u32 v188, v252, 4, 1
	v_mul_u32_u24_e32 v188, 24, v188
	v_mov_b32_e32 v189, 0
	v_lshl_add_u64 v[182:183], v[136:137], 0, v[188:189]
	v_permlane16_swap_b32_e32 v184, v186
	v_permlane16_swap_b32_e32 v185, v187
	global_store_dwordx4 v[182:183], v[184:187], off offset:256
	s_nop 1
	ds_bpermute_b32 v136, v133, v142
	s_waitcnt lgkmcnt(0)
	v_add_f32_e32 v136, v142, v136
	ds_bpermute_b32 v137, v134, v136
	s_and_saveexec_b64 s[0:1], vcc
	s_cbranch_execz .LBB0_290
	s_waitcnt lgkmcnt(0)
	v_add_f32_e32 v136, v136, v137
	ds_write_b32 v131, v136 offset:128
.LBB0_290:
	s_or_b64 exec, exec, s[0:1]
	v_or_b32_e32 v135, 48, v135
	v_add_u32_e32 v136, s80, v135
	v_lshl_add_u32 v135, v135, 2, 0
	v_add_u32_e32 v135, 0x20000, v135
	ds_read_b32 v138, v135
	s_waitcnt lgkmcnt(0)
	v_ashrrev_i32_e32 v137, 31, v136
	v_lshlrev_b64 v[136:137], 9, v[136:137]
	v_lshl_add_u64 v[136:137], v[128:129], 0, v[136:137]
	v_pk_mul_f32 v[140:141], v[74:75], v[138:139] op_sel_hi:[1,0]
	v_pk_mul_f32 v[142:143], v[72:73], v[138:139] op_sel_hi:[1,0]
	v_mul_f32_e32 v139, v141, v141
	v_mul_f32_e32 v135, v143, v143
	v_fmac_f32_e32 v135, v142, v142
	v_fmac_f32_e32 v139, v140, v140
	v_cvt_pk_bf16_f32 v142, v142, v143
	v_cvt_pk_bf16_f32 v143, v140, v141
	v_mov_b32_e32 v184, v142
	v_mov_b32_e32 v185, v143
	v_pk_mul_f32 v[140:141], v[66:67], v[138:139] op_sel_hi:[1,0]
	v_pk_mul_f32 v[142:143], v[64:65], v[138:139] op_sel_hi:[1,0]
	v_add_f32_e32 v135, v135, v139
	v_mul_f32_e32 v139, v143, v143
	v_mul_f32_e32 v144, v141, v141
	v_fmac_f32_e32 v139, v142, v142
	v_fmac_f32_e32 v144, v140, v140
	v_add_f32_e32 v139, v139, v144
	v_cvt_pk_bf16_f32 v142, v142, v143
	v_cvt_pk_bf16_f32 v143, v140, v141
	v_mov_b32_e32 v186, v142
	v_mov_b32_e32 v187, v143
	v_bfe_u32 v188, v252, 4, 1
	v_mul_u32_u24_e32 v188, 24, v188
	v_mov_b32_e32 v189, 0
	v_lshl_add_u64 v[182:183], v[136:137], 0, v[188:189]
	v_permlane16_swap_b32_e32 v184, v186
	v_permlane16_swap_b32_e32 v185, v187
	global_store_dwordx4 v[182:183], v[184:187], off
	s_nop 1
	v_pk_mul_f32 v[140:141], v[78:79], v[138:139] op_sel_hi:[1,0]
	v_pk_mul_f32 v[142:143], v[76:77], v[138:139] op_sel_hi:[1,0]
	v_add_f32_e32 v135, v135, v139
	v_mul_f32_e32 v139, v143, v143
	v_mul_f32_e32 v144, v141, v141
	v_fmac_f32_e32 v139, v142, v142
	v_fmac_f32_e32 v144, v140, v140
	v_add_f32_e32 v139, v139, v144
	v_add_f32_e32 v135, v139, v135
	v_cvt_pk_bf16_f32 v142, v142, v143
	v_cvt_pk_bf16_f32 v143, v140, v141
	v_pk_mul_f32 v[140:141], v[70:71], v[138:139] op_sel_hi:[1,0]
	v_pk_mul_f32 v[138:139], v[68:69], v[138:139] op_sel_hi:[1,0]
	v_mov_b32_e32 v184, v142
	v_mov_b32_e32 v185, v143
	v_mul_f32_e32 v142, v139, v139
	v_mul_f32_e32 v143, v141, v141
	v_fmac_f32_e32 v142, v138, v138
	v_fmac_f32_e32 v143, v140, v140
	v_add_f32_e32 v142, v142, v143
	v_add_f32_e32 v135, v142, v135
	v_cvt_pk_bf16_f32 v138, v138, v139
	v_cvt_pk_bf16_f32 v139, v140, v141
	v_mov_b32_e32 v186, v138
	v_mov_b32_e32 v187, v139
	v_bfe_u32 v188, v252, 4, 1
	v_mul_u32_u24_e32 v188, 24, v188
	v_mov_b32_e32 v189, 0
	v_lshl_add_u64 v[182:183], v[136:137], 0, v[188:189]
	v_permlane16_swap_b32_e32 v184, v186
	v_permlane16_swap_b32_e32 v185, v187
	global_store_dwordx4 v[182:183], v[184:187], off offset:256
	s_nop 1
	ds_bpermute_b32 v136, v133, v135
	s_waitcnt lgkmcnt(0)
	v_add_f32_e32 v135, v135, v136
	ds_bpermute_b32 v136, v134, v135
	s_and_saveexec_b64 s[0:1], vcc
	s_cbranch_execz .LBB0_292
	s_waitcnt lgkmcnt(0)
	v_add_f32_e32 v135, v135, v136
	ds_write_b32 v131, v135 offset:192
; __device__ __forceinline__ u32x2 pack4(float a, float b, float c, float d) { return u32x2{cvtpk(a, b), cvtpk(c, d)}; }
; __device__ __forceinline__ u32x2 pack4(const f32x4& v) { return u32x2{cvtpk(v[0], v[1]), cvtpk(v[2], v[3])}; }
; #define SBAR() __builtin_amdgcn_sched_barrier(0)
; __global__ void __launch_bounds__(512) fwd_megakernel(Params p) {
;     ...
;           for (int ai = 0; ai < 2; ++ai)
;             #pragma unroll
;             for (int m = 0; m < 4; ++m) { SBAR();
;               int lrow = ai * 128 + wr * 64 + m * 16 + fr, row = brow + lrow; float rs = xl[lrow]; float ss = 0.f;
;               #pragma unroll
;               for (int bj = 0; bj < 2; ++bj)
;                 #pragma unroll
;                 for (int n = 0; n < 2; ++n) {
;                   f32x4 v = acc[ai][bj][m][n] * rs; ss += (v[0] * v[0] + v[1] * v[1]) + (v[2] * v[2] + v[3] * v[3]);
;                   *reinterpret_cast<u32x2*>(dst + (long)row * 256 + bj * 128 + wc * 32 + n * 16 + fq * 4) = pack4(v);
;                 }
;               ss += __shfl_xor(ss, 16); ss += __shfl_xor(ss, 32);
;               if (fq == 0) red[wc * 256 + lrow] = ss;
.LBB0_292:
	s_or_b64 exec, exec, s[0:1]
	ds_read_b32 v138, v132 offset:512
	s_waitcnt lgkmcnt(0)
	v_add_u32_e32 v136, 0x80, v130
	v_ashrrev_i32_e32 v137, 31, v136
	v_lshlrev_b64 v[136:137], 9, v[136:137]
	v_lshl_add_u64 v[136:137], v[128:129], 0, v[136:137]
	v_pk_mul_f32 v[140:141], v[58:59], v[138:139] op_sel_hi:[1,0]
	v_pk_mul_f32 v[142:143], v[56:57], v[138:139] op_sel_hi:[1,0]
	v_mul_f32_e32 v139, v141, v141
	v_mul_f32_e32 v135, v143, v143
	v_fmac_f32_e32 v135, v142, v142
	v_fmac_f32_e32 v139, v140, v140
	v_cvt_pk_bf16_f32 v142, v142, v143
	v_cvt_pk_bf16_f32 v143, v140, v141
	v_mov_b32_e32 v184, v142
	v_mov_b32_e32 v185, v143
	v_pk_mul_f32 v[140:141], v[50:51], v[138:139] op_sel_hi:[1,0]
	v_pk_mul_f32 v[142:143], v[48:49], v[138:139] op_sel_hi:[1,0]
	v_add_f32_e32 v135, v135, v139
	v_mul_f32_e32 v139, v143, v143
	v_mul_f32_e32 v144, v141, v141
	v_fmac_f32_e32 v139, v142, v142
	v_fmac_f32_e32 v144, v140, v140
	v_add_f32_e32 v139, v139, v144
	v_cvt_pk_bf16_f32 v142, v142, v143
	v_cvt_pk_bf16_f32 v143, v140, v141
	v_mov_b32_e32 v186, v142
	v_mov_b32_e32 v187, v143
	v_bfe_u32 v188, v252, 4, 1
	v_mul_u32_u24_e32 v188, 24, v188
	v_mov_b32_e32 v189, 0
	v_lshl_add_u64 v[182:183], v[136:137], 0, v[188:189]
	v_permlane16_swap_b32_e32 v184, v186
	v_permlane16_swap_b32_e32 v185, v187
	global_store_dwordx4 v[182:183], v[184:187], off
	s_nop 1
	v_pk_mul_f32 v[140:141], v[62:63], v[138:139] op_sel_hi:[1,0]
	v_pk_mul_f32 v[142:143], v[60:61], v[138:139] op_sel_hi:[1,0]
	v_add_f32_e32 v135, v135, v139
	v_mul_f32_e32 v139, v143, v143
	v_mul_f32_e32 v144, v141, v141
	v_fmac_f32_e32 v139, v142, v142
	v_fmac_f32_e32 v144, v140, v140
	v_add_f32_e32 v139, v139, v144
	v_add_f32_e32 v135, v139, v135
	v_cvt_pk_bf16_f32 v142, v142, v143
	v_cvt_pk_bf16_f32 v143, v140, v141
	v_pk_mul_f32 v[140:141], v[54:55], v[138:139] op_sel_hi:[1,0]
	v_pk_mul_f32 v[138:139], v[52:53], v[138:139] op_sel_hi:[1,0]
	v_mov_b32_e32 v184, v142
	v_mov_b32_e32 v185, v143
	v_mul_f32_e32 v142, v139, v139
	v_mul_f32_e32 v143, v141, v141
	v_fmac_f32_e32 v142, v138, v138
	v_fmac_f32_e32 v143, v140, v140
	v_add_f32_e32 v142, v142, v143
	v_add_f32_e32 v135, v142, v135
	v_cvt_pk_bf16_f32 v138, v138, v139
	v_cvt_pk_bf16_f32 v139, v140, v141
	v_mov_b32_e32 v186, v138
	v_mov_b32_e32 v187, v139
	v_bfe_u32 v188, v252, 4, 1
	v_mul_u32_u24_e32 v188, 24, v188
	v_mov_b32_e32 v189, 0
	v_lshl_add_u64 v[182:183], v[136:137], 0, v[188:189]
	v_permlane16_swap_b32_e32 v184, v186
	v_permlane16_swap_b32_e32 v185, v187
	global_store_dwordx4 v[182:183], v[184:187], off offset:256
	s_nop 1
	ds_bpermute_b32 v136, v133, v135
	s_waitcnt lgkmcnt(0)
	v_add_f32_e32 v135, v135, v136
	ds_bpermute_b32 v136, v134, v135
	s_and_saveexec_b64 s[0:1], vcc
	s_cbranch_execz .LBB0_294
	s_waitcnt lgkmcnt(0)
	v_add_f32_e32 v135, v135, v136
	ds_write_b32 v131, v135 offset:512
.LBB0_294:
	s_or_b64 exec, exec, s[0:1]
	ds_read_b32 v138, v132 offset:576
	s_waitcnt lgkmcnt(0)
	v_add_u32_e32 v136, 0x90, v130
	v_ashrrev_i32_e32 v137, 31, v136
	v_lshlrev_b64 v[136:137], 9, v[136:137]
	v_lshl_add_u64 v[136:137], v[128:129], 0, v[136:137]
	v_pk_mul_f32 v[140:141], v[42:43], v[138:139] op_sel_hi:[1,0]
	v_pk_mul_f32 v[142:143], v[40:41], v[138:139] op_sel_hi:[1,0]
	v_mul_f32_e32 v139, v141, v141
	v_mul_f32_e32 v135, v143, v143
	v_fmac_f32_e32 v135, v142, v142
	v_fmac_f32_e32 v139, v140, v140
	v_cvt_pk_bf16_f32 v142, v142, v143
	v_cvt_pk_bf16_f32 v143, v140, v141
	v_mov_b32_e32 v184, v142
	v_mov_b32_e32 v185, v143
	v_pk_mul_f32 v[140:141], v[34:35], v[138:139] op_sel_hi:[1,0]
	v_pk_mul_f32 v[142:143], v[32:33], v[138:139] op_sel_hi:[1,0]
	v_add_f32_e32 v135, v135, v139
	v_mul_f32_e32 v139, v143, v143
	v_mul_f32_e32 v144, v141, v141
	v_fmac_f32_e32 v139, v142, v142
	v_fmac_f32_e32 v144, v140, v140
	v_add_f32_e32 v139, v139, v144
	v_cvt_pk_bf16_f32 v142, v142, v143
	v_cvt_pk_bf16_f32 v143, v140, v141
	v_mov_b32_e32 v186, v142
	v_mov_b32_e32 v187, v143
	v_bfe_u32 v188, v252, 4, 1
	v_mul_u32_u24_e32 v188, 24, v188
	v_mov_b32_e32 v189, 0
	v_lshl_add_u64 v[182:183], v[136:137], 0, v[188:189]
	v_permlane16_swap_b32_e32 v184, v186
	v_permlane16_swap_b32_e32 v185, v187
	global_store_dwordx4 v[182:183], v[184:187], off
	s_nop 1
	v_pk_mul_f32 v[140:141], v[46:47], v[138:139] op_sel_hi:[1,0]
	v_pk_mul_f32 v[142:143], v[44:45], v[138:139] op_sel_hi:[1,0]
	v_add_f32_e32 v135, v135, v139
	v_mul_f32_e32 v139, v143, v143
	v_mul_f32_e32 v144, v141, v141
	v_fmac_f32_e32 v139, v142, v142
	v_fmac_f32_e32 v144, v140, v140
	v_add_f32_e32 v139, v139, v144
	v_add_f32_e32 v135, v139, v135
	v_cvt_pk_bf16_f32 v142, v142, v143
	v_cvt_pk_bf16_f32 v143, v140, v141
	v_pk_mul_f32 v[140:141], v[38:39], v[138:139] op_sel_hi:[1,0]
	v_pk_mul_f32 v[138:139], v[36:37], v[138:139] op_sel_hi:[1,0]
	v_mov_b32_e32 v184, v142
	v_mov_b32_e32 v185, v143
	v_mul_f32_e32 v142, v139, v139
	v_mul_f32_e32 v143, v141, v141
	v_fmac_f32_e32 v142, v138, v138
	v_fmac_f32_e32 v143, v140, v140
	v_add_f32_e32 v142, v142, v143
	v_add_f32_e32 v135, v142, v135
	v_cvt_pk_bf16_f32 v138, v138, v139
	v_cvt_pk_bf16_f32 v139, v140, v141
	v_mov_b32_e32 v186, v138
	v_mov_b32_e32 v187, v139
	v_bfe_u32 v188, v252, 4, 1
	v_mul_u32_u24_e32 v188, 24, v188
	v_mov_b32_e32 v189, 0
	v_lshl_add_u64 v[182:183], v[136:137], 0, v[188:189]
	v_permlane16_swap_b32_e32 v184, v186
	v_permlane16_swap_b32_e32 v185, v187
	global_store_dwordx4 v[182:183], v[184:187], off offset:256
	s_nop 1
	ds_bpermute_b32 v136, v133, v135
	s_waitcnt lgkmcnt(0)
	v_add_f32_e32 v135, v135, v136
	ds_bpermute_b32 v136, v134, v135
	s_and_saveexec_b64 s[0:1], vcc
	s_cbranch_execz .LBB0_296
	s_waitcnt lgkmcnt(0)
	v_add_f32_e32 v135, v135, v136
	ds_write_b32 v131, v135 offset:576
; __device__ __forceinline__ u32x2 pack4(float a, float b, float c, float d) { return u32x2{cvtpk(a, b), cvtpk(c, d)}; }
; __device__ __forceinline__ u32x2 pack4(const f32x4& v) { return u32x2{cvtpk(v[0], v[1]), cvtpk(v[2], v[3])}; }
; #define SBAR() __builtin_amdgcn_sched_barrier(0)
; __global__ void __launch_bounds__(512) fwd_megakernel(Params p) {
;     ...
;           for (int ai = 0; ai < 2; ++ai)
;             #pragma unroll
;             for (int m = 0; m < 4; ++m) { SBAR();
;               int lrow = ai * 128 + wr * 64 + m * 16 + fr, row = brow + lrow; float rs = xl[lrow]; float ss = 0.f;
;               #pragma unroll
;               for (int bj = 0; bj < 2; ++bj)
;                 #pragma unroll
;                 for (int n = 0; n < 2; ++n) {
;                   f32x4 v = acc[ai][bj][m][n] * rs; ss += (v[0] * v[0] + v[1] * v[1]) + (v[2] * v[2] + v[3] * v[3]);
;                   *reinterpret_cast<u32x2*>(dst + (long)row * 256 + bj * 128 + wc * 32 + n * 16 + fq * 4) = pack4(v);
;                 }
;               ss += __shfl_xor(ss, 16); ss += __shfl_xor(ss, 32);
;               if (fq == 0) red[wc * 256 + lrow] = ss;
;             }
;           asm volatile("s_waitcnt lgkmcnt(0)" ::: "memory"); __builtin_amdgcn_s_barrier();
;           if (tid < 256) { float s = red[tid] + red[256 + tid] + red[512 + tid] + red[768 + tid]; rdst[brow + tid] = rsqrtf(s * (1.f / 256.f) + EPS); }
.LBB0_296:
	s_or_b64 exec, exec, s[0:1]
	ds_read_b32 v138, v132 offset:640
	s_waitcnt lgkmcnt(0)
	v_add_u32_e32 v136, 0xa0, v130
	v_ashrrev_i32_e32 v137, 31, v136
	v_lshlrev_b64 v[136:137], 9, v[136:137]
	v_lshl_add_u64 v[136:137], v[128:129], 0, v[136:137]
	v_pk_mul_f32 v[140:141], v[26:27], v[138:139] op_sel_hi:[1,0]
	v_pk_mul_f32 v[142:143], v[24:25], v[138:139] op_sel_hi:[1,0]
	v_mul_f32_e32 v139, v141, v141
	v_mul_f32_e32 v135, v143, v143
	v_fmac_f32_e32 v135, v142, v142
	v_fmac_f32_e32 v139, v140, v140
	v_cvt_pk_bf16_f32 v142, v142, v143
	v_cvt_pk_bf16_f32 v143, v140, v141
	v_mov_b32_e32 v184, v142
	v_mov_b32_e32 v185, v143
	v_pk_mul_f32 v[140:141], v[18:19], v[138:139] op_sel_hi:[1,0]
	v_pk_mul_f32 v[142:143], v[16:17], v[138:139] op_sel_hi:[1,0]
	v_add_f32_e32 v135, v135, v139
	v_mul_f32_e32 v139, v143, v143
	v_mul_f32_e32 v144, v141, v141
	v_fmac_f32_e32 v139, v142, v142
	v_fmac_f32_e32 v144, v140, v140
	v_add_f32_e32 v139, v139, v144
	v_cvt_pk_bf16_f32 v142, v142, v143
	v_cvt_pk_bf16_f32 v143, v140, v141
	v_mov_b32_e32 v186, v142
	v_mov_b32_e32 v187, v143
	v_bfe_u32 v188, v252, 4, 1
	v_mul_u32_u24_e32 v188, 24, v188
	v_mov_b32_e32 v189, 0
	v_lshl_add_u64 v[182:183], v[136:137], 0, v[188:189]
	v_permlane16_swap_b32_e32 v184, v186
	v_permlane16_swap_b32_e32 v185, v187
	global_store_dwordx4 v[182:183], v[184:187], off
	s_nop 1
	v_pk_mul_f32 v[140:141], v[30:31], v[138:139] op_sel_hi:[1,0]
	v_pk_mul_f32 v[142:143], v[28:29], v[138:139] op_sel_hi:[1,0]
	v_add_f32_e32 v135, v135, v139
	v_mul_f32_e32 v139, v143, v143
	v_mul_f32_e32 v144, v141, v141
	v_fmac_f32_e32 v139, v142, v142
	v_fmac_f32_e32 v144, v140, v140
	v_add_f32_e32 v139, v139, v144
	v_add_f32_e32 v135, v139, v135
	v_cvt_pk_bf16_f32 v142, v142, v143
	v_cvt_pk_bf16_f32 v143, v140, v141
	v_pk_mul_f32 v[140:141], v[22:23], v[138:139] op_sel_hi:[1,0]
	v_pk_mul_f32 v[138:139], v[20:21], v[138:139] op_sel_hi:[1,0]
	v_mov_b32_e32 v184, v142
	v_mov_b32_e32 v185, v143
	v_mul_f32_e32 v142, v139, v139
	v_mul_f32_e32 v143, v141, v141
	v_fmac_f32_e32 v142, v138, v138
	v_fmac_f32_e32 v143, v140, v140
	v_add_f32_e32 v142, v142, v143
	v_add_f32_e32 v135, v142, v135
	v_cvt_pk_bf16_f32 v138, v138, v139
	v_cvt_pk_bf16_f32 v139, v140, v141
	v_mov_b32_e32 v186, v138
	v_mov_b32_e32 v187, v139
	v_bfe_u32 v188, v252, 4, 1
	v_mul_u32_u24_e32 v188, 24, v188
	v_mov_b32_e32 v189, 0
	v_lshl_add_u64 v[182:183], v[136:137], 0, v[188:189]
	v_permlane16_swap_b32_e32 v184, v186
	v_permlane16_swap_b32_e32 v185, v187
	global_store_dwordx4 v[182:183], v[184:187], off offset:256
	s_nop 1
	ds_bpermute_b32 v136, v133, v135
	s_waitcnt lgkmcnt(0)
	v_add_f32_e32 v135, v135, v136
	ds_bpermute_b32 v136, v134, v135
	s_and_saveexec_b64 s[0:1], vcc
	s_cbranch_execz .LBB0_298
	s_waitcnt lgkmcnt(0)
	v_add_f32_e32 v135, v135, v136
	ds_write_b32 v131, v135 offset:640
.LBB0_298:
	s_or_b64 exec, exec, s[0:1]
	s_waitcnt lgkmcnt(0)
	v_add_u32_e32 v136, 0xb0, v130
	ds_read_b32 v130, v132 offset:704
	v_ashrrev_i32_e32 v137, 31, v136
	v_lshlrev_b64 v[136:137], 9, v[136:137]
	v_lshl_add_u64 v[128:129], v[128:129], 0, v[136:137]
	s_waitcnt lgkmcnt(0)
	v_pk_mul_f32 v[138:139], v[8:9], v[130:131] op_sel_hi:[1,0]
	v_pk_mul_f32 v[136:137], v[10:11], v[130:131] op_sel_hi:[1,0]
	v_mul_f32_e32 v132, v139, v139
	v_fmac_f32_e32 v132, v138, v138
	v_mul_f32_e32 v135, v137, v137
	v_cvt_pk_bf16_f32 v138, v138, v139
	v_cvt_pk_bf16_f32 v139, v136, v137
	v_fmac_f32_e32 v135, v136, v136
	v_mov_b32_e32 v184, v138
	v_mov_b32_e32 v185, v139
	v_pk_mul_f32 v[136:137], v[2:3], v[130:131] op_sel_hi:[1,0]
	v_pk_mul_f32 v[138:139], v[0:1], v[130:131] op_sel_hi:[1,0]
	v_add_f32_e32 v132, v132, v135
	v_mul_f32_e32 v135, v139, v139
	v_mul_f32_e32 v140, v137, v137
	v_fmac_f32_e32 v135, v138, v138
	v_fmac_f32_e32 v140, v136, v136
	v_cvt_pk_bf16_f32 v138, v138, v139
	v_cvt_pk_bf16_f32 v139, v136, v137
	v_add_f32_e32 v135, v135, v140
	v_mov_b32_e32 v186, v138
	v_mov_b32_e32 v187, v139
	v_bfe_u32 v188, v252, 4, 1
	v_mul_u32_u24_e32 v188, 24, v188
	v_mov_b32_e32 v189, 0
	v_lshl_add_u64 v[182:183], v[128:129], 0, v[188:189]
	v_permlane16_swap_b32_e32 v184, v186
	v_permlane16_swap_b32_e32 v185, v187
	global_store_dwordx4 v[182:183], v[184:187], off
	s_nop 1
	v_pk_mul_f32 v[136:137], v[14:15], v[130:131] op_sel_hi:[1,0]
	v_pk_mul_f32 v[138:139], v[12:13], v[130:131] op_sel_hi:[1,0]
	v_add_f32_e32 v132, v132, v135
	v_mul_f32_e32 v135, v139, v139
	v_mul_f32_e32 v140, v137, v137
	v_fmac_f32_e32 v135, v138, v138
	v_fmac_f32_e32 v140, v136, v136
	v_cvt_pk_bf16_f32 v138, v138, v139
	v_cvt_pk_bf16_f32 v139, v136, v137
	v_add_f32_e32 v135, v135, v140
	v_mov_b32_e32 v184, v138
	v_mov_b32_e32 v185, v139
	v_pk_mul_f32 v[136:137], v[6:7], v[130:131] op_sel_hi:[1,0]
	v_pk_mul_f32 v[138:139], v[4:5], v[130:131] op_sel_hi:[1,0]
	v_add_f32_e32 v132, v135, v132
	v_mul_f32_e32 v130, v139, v139
	v_mul_f32_e32 v135, v137, v137
	v_fmac_f32_e32 v130, v138, v138
	v_fmac_f32_e32 v135, v136, v136
	v_add_f32_e32 v130, v130, v135
	v_add_f32_e32 v130, v130, v132
	v_cvt_pk_bf16_f32 v138, v138, v139
	v_cvt_pk_bf16_f32 v139, v136, v137
	v_mov_b32_e32 v186, v138
	v_mov_b32_e32 v187, v139
	v_bfe_u32 v188, v252, 4, 1
	v_mul_u32_u24_e32 v188, 24, v188
	v_mov_b32_e32 v189, 0
	v_lshl_add_u64 v[182:183], v[128:129], 0, v[188:189]
	v_permlane16_swap_b32_e32 v184, v186
	v_permlane16_swap_b32_e32 v185, v187
	global_store_dwordx4 v[182:183], v[184:187], off offset:256
	s_nop 1
	ds_bpermute_b32 v128, v133, v130
	s_waitcnt lgkmcnt(0)
	v_add_f32_e32 v128, v130, v128
	ds_bpermute_b32 v129, v134, v128
	s_and_saveexec_b64 s[0:1], vcc
	s_cbranch_execz .LBB0_300
	s_waitcnt lgkmcnt(0)
	v_add_f32_e32 v128, v128, v129
	ds_write_b32 v131, v128 offset:704

; __device__ __forceinline__ float sigmoidf_(float x) { return __builtin_amdgcn_rcpf(1.f + __builtin_amdgcn_exp2f(x * -1.4426950408889634f)); }
; __device__ __forceinline__ u32x2 pack4(float a, float b, float c, float d) { return u32x2{cvtpk(a, b), cvtpk(c, d)}; }
; __device__ __forceinline__ u32x2 pack4(const f32x4& v) { return u32x2{cvtpk(v[0], v[1]), cvtpk(v[2], v[3])}; }
; #define SBAR() __builtin_amdgcn_sched_barrier(0)
; __global__ void __launch_bounds__(512) fwd_megakernel(Params p) {
;     ...
;         if (pn < 4) {
;           #pragma unroll
;           for (int ai = 0; ai < 2; ++ai)
;             #pragma unroll
;             for (int m = 0; m < 4; ++m) { SBAR();
;               int lrow = ai * 128 + wr * 64 + m * 16 + fr, row = brow + lrow; float rs = xl[lrow];
;               #pragma unroll
;               for (int n = 0; n < 2; ++n) {
;                 float u[4];
;                 #pragma unroll
;                 for (int j = 0; j < 4; ++j) { float val = acc[ai][0][m][n][j] * rs, gate = acc[ai][1][m][n][j] * rs; u[j] = val * sigmoidf_(gate); }
;                 *reinterpret_cast<u32x2*>(p_u0 + (long)row * CONVC + pn * 128 + wc * 32 + n * 16 + fq * 4) = pack4(u[0], u[1], u[2], u[3]);
;               }
;             }
.LBB0_304:
	s_andn2_b64 vcc, exec, s[0:1]
	s_cbranch_vccnz .LBB0_218
	v_lshl_or_b32 v131, v152, 6, v153
	v_lshl_add_u32 v130, v131, 2, s67
	ds_read_b32 v134, v130
	v_add_u32_e32 v128, s80, v131
	s_waitcnt lgkmcnt(0)
	v_ashrrev_i32_e32 v129, 31, v128
	s_lshl_b32 s0, s76, 7
	v_lshlrev_b64 v[132:133], 10, v[128:129]
	v_mul_f32_e32 v124, v124, v134
	v_mul_f32_e32 v124, 0xbfb8aa3b, v124
	v_exp_f32_e32 v124, v124
	v_mul_f32_e32 v116, v116, v134
	v_mul_f32_e32 v116, 0xbfb8aa3b, v116
	v_exp_f32_e32 v116, v116
	v_add_f32_e32 v124, 1.0, v124
	v_mul_f32_e32 v125, v125, v134
	v_rcp_f32_e32 v124, v124
	v_mul_f32_e32 v125, 0xbfb8aa3b, v125
	v_exp_f32_e32 v125, v125
	v_mul_f32_e32 v117, v117, v134
	v_mul_f32_e32 v120, v120, v134
	v_add_f32_e32 v116, 1.0, v116
	v_mul_f32_e32 v117, 0xbfb8aa3b, v117
	v_mul_f32_e32 v120, v120, v124
	v_mul_f32_e32 v124, v126, v134
	v_rcp_f32_e32 v116, v116
	v_exp_f32_e32 v117, v117
	v_mul_f32_e32 v124, 0xbfb8aa3b, v124
	v_mul_f32_e32 v126, v127, v134
	v_add_f32_e32 v125, 1.0, v125
	v_exp_f32_e32 v124, v124
	v_mul_f32_e32 v126, 0xbfb8aa3b, v126
	v_rcp_f32_e32 v125, v125
	v_exp_f32_e32 v126, v126
	v_mul_f32_e32 v112, v112, v134
	v_mul_f32_e32 v112, v112, v116
	v_add_f32_e32 v116, 1.0, v117
	v_mul_f32_e32 v117, v118, v134
	v_mul_f32_e32 v118, v119, v134
	v_mul_f32_e32 v117, 0xbfb8aa3b, v117
	v_mul_f32_e32 v118, 0xbfb8aa3b, v118
	v_mul_f32_e32 v121, v121, v134
	v_add_f32_e32 v124, 1.0, v124
	v_rcp_f32_e32 v116, v116
	v_exp_f32_e32 v117, v117
	v_exp_f32_e32 v118, v118
	v_mul_f32_e32 v121, v121, v125
	v_rcp_f32_e32 v124, v124
	v_add_f32_e32 v125, 1.0, v126
	v_rcp_f32_e32 v125, v125
	v_mul_f32_e32 v113, v113, v134
	v_mul_f32_e32 v122, v122, v134
	v_mul_f32_e32 v113, v113, v116
	v_add_f32_e32 v116, 1.0, v117
	v_add_f32_e32 v117, 1.0, v118
	v_mul_f32_e32 v124, v122, v124
	v_mul_f32_e32 v122, v123, v134
	s_ashr_i32 s1, s0, 31
	v_rcp_f32_e32 v116, v116
	v_rcp_f32_e32 v117, v117
	v_mul_f32_e32 v123, v122, v125
	v_cvt_pk_bf16_f32 v122, v120, v121
	v_lshl_add_u64 v[120:121], s[10:11], 0, v[132:133]
	s_lshl_b64 s[0:1], s[0:1], 1
	v_lshl_add_u64 v[120:121], v[120:121], 0, s[0:1]
	v_lshlrev_b32_e32 v194, 6, v151
	v_cvt_pk_bf16_f32 v123, v124, v123
	v_lshl_add_u64 v[124:125], v[120:121], 0, v[194:195]
	v_lshlrev_b32_e32 v120, 3, v150
	v_mov_b32_e32 v121, v195
	v_mul_f32_e32 v114, v114, v134
	v_mul_f32_e32 v115, v115, v134
	v_lshl_add_u64 v[124:125], v[124:125], 0, v[120:121]
	v_mul_f32_e32 v114, v114, v116
	v_mul_f32_e32 v115, v115, v117
	v_mov_b32_e32 v184, v122
	v_mov_b32_e32 v185, v123
	v_cvt_pk_bf16_f32 v112, v112, v113
	v_cvt_pk_bf16_f32 v113, v114, v115
	v_lshl_add_u64 v[114:115], s[34:35], 0, v[132:133]
	v_lshl_add_u64 v[114:115], v[114:115], 0, s[0:1]
	v_lshl_add_u64 v[114:115], v[114:115], 0, v[194:195]
	v_lshl_add_u64 v[114:115], v[114:115], 0, v[120:121]
	v_add_co_u32_e32 v114, vcc, s62, v114
	s_nop 1
	v_addc_co_u32_e32 v115, vcc, 0, v115, vcc
	v_mov_b32_e32 v186, v112
	v_mov_b32_e32 v187, v113
	v_bfe_u32 v188, v252, 4, 1
	v_mul_u32_u24_e32 v188, 24, v188
	v_mov_b32_e32 v189, 0
	v_lshl_add_u64 v[182:183], v[114:115], 0, v[188:189]
	v_permlane16_swap_b32_e32 v184, v186
	v_permlane16_swap_b32_e32 v185, v187
	global_store_dwordx4 v[182:183], v[184:187], off
	s_nop 1
	v_or_b32_e32 v112, 16, v131
	v_lshl_add_u32 v113, v112, 2, s67
	ds_read_b32 v114, v113
	v_add_u32_e32 v112, s80, v112
	v_ashrrev_i32_e32 v113, 31, v112
	v_lshlrev_b64 v[112:113], 10, v[112:113]
	s_waitcnt lgkmcnt(0)
	v_mul_f32_e32 v108, v108, v114
	v_mul_f32_e32 v108, 0xbfb8aa3b, v108
	v_exp_f32_e32 v108, v108
	v_mul_f32_e32 v100, v100, v114
	v_mul_f32_e32 v100, 0xbfb8aa3b, v100
	v_mul_f32_e32 v109, v109, v114
	v_add_f32_e32 v108, 1.0, v108
	v_exp_f32_e32 v100, v100
	v_mul_f32_e32 v109, 0xbfb8aa3b, v109
	v_rcp_f32_e32 v108, v108
	v_exp_f32_e32 v109, v109
	v_mul_f32_e32 v101, v101, v114
	v_mul_f32_e32 v104, v104, v114
	v_add_f32_e32 v100, 1.0, v100
	v_mul_f32_e32 v101, 0xbfb8aa3b, v101
	v_mul_f32_e32 v104, v104, v108
	v_mul_f32_e32 v108, v110, v114
	v_mul_f32_e32 v110, v111, v114
	v_rcp_f32_e32 v100, v100
	v_exp_f32_e32 v101, v101
	v_add_f32_e32 v109, 1.0, v109
	v_mul_f32_e32 v108, 0xbfb8aa3b, v108
	v_mul_f32_e32 v110, 0xbfb8aa3b, v110
	v_rcp_f32_e32 v109, v109
	v_exp_f32_e32 v108, v108
	v_exp_f32_e32 v110, v110
	v_mul_f32_e32 v96, v96, v114
	v_mul_f32_e32 v96, v96, v100
	v_add_f32_e32 v100, 1.0, v101
	v_mul_f32_e32 v101, v102, v114
	v_mul_f32_e32 v102, v103, v114
	v_mul_f32_e32 v105, v105, v114
	v_mul_f32_e32 v101, 0xbfb8aa3b, v101
	v_mul_f32_e32 v102, 0xbfb8aa3b, v102
	v_mul_f32_e32 v105, v105, v109
	v_add_f32_e32 v108, 1.0, v108
	v_add_f32_e32 v109, 1.0, v110
	v_rcp_f32_e32 v100, v100
	v_exp_f32_e32 v101, v101
	v_exp_f32_e32 v102, v102
	v_rcp_f32_e32 v108, v108
	v_rcp_f32_e32 v109, v109
	v_mul_f32_e32 v97, v97, v114
	v_mul_f32_e32 v106, v106, v114
	v_mul_f32_e32 v107, v107, v114
	v_mul_f32_e32 v97, v97, v100
	v_add_f32_e32 v100, 1.0, v101
	v_add_f32_e32 v101, 1.0, v102
	v_mul_f32_e32 v106, v106, v108
	v_mul_f32_e32 v107, v107, v109
	v_rcp_f32_e32 v100, v100
	v_rcp_f32_e32 v101, v101
	v_cvt_pk_bf16_f32 v104, v104, v105
	v_cvt_pk_bf16_f32 v105, v106, v107
	v_lshl_add_u64 v[106:107], s[10:11], 0, v[112:113]
	v_lshl_add_u64 v[106:107], v[106:107], 0, s[0:1]
	v_lshl_add_u64 v[106:107], v[106:107], 0, v[194:195]
	v_mul_f32_e32 v98, v98, v114
	v_mul_f32_e32 v99, v99, v114
	v_lshl_add_u64 v[106:107], v[106:107], 0, v[120:121]
	v_mul_f32_e32 v98, v98, v100
	v_mul_f32_e32 v99, v99, v101
	v_mov_b32_e32 v184, v104
	v_mov_b32_e32 v185, v105
	v_cvt_pk_bf16_f32 v96, v96, v97
	v_cvt_pk_bf16_f32 v97, v98, v99
	v_lshl_add_u64 v[98:99], s[34:35], 0, v[112:113]
	v_lshl_add_u64 v[98:99], v[98:99], 0, s[0:1]
	v_lshl_add_u64 v[98:99], v[98:99], 0, v[194:195]
	v_lshl_add_u64 v[98:99], v[98:99], 0, v[120:121]
	v_add_co_u32_e32 v98, vcc, s62, v98
	s_nop 1
	v_addc_co_u32_e32 v99, vcc, 0, v99, vcc
	v_mov_b32_e32 v186, v96
	v_mov_b32_e32 v187, v97
	v_bfe_u32 v188, v252, 4, 1
	v_mul_u32_u24_e32 v188, 24, v188
	v_mov_b32_e32 v189, 0
	v_lshl_add_u64 v[182:183], v[98:99], 0, v[188:189]
	v_permlane16_swap_b32_e32 v184, v186
	v_permlane16_swap_b32_e32 v185, v187
	global_store_dwordx4 v[182:183], v[184:187], off
	s_nop 1
	v_or_b32_e32 v96, 32, v131
	v_lshl_add_u32 v97, v96, 2, s67
	ds_read_b32 v98, v97
	v_add_u32_e32 v96, s80, v96
	v_ashrrev_i32_e32 v97, 31, v96
	v_lshlrev_b64 v[96:97], 10, v[96:97]
	s_waitcnt lgkmcnt(0)
; __device__ __forceinline__ float sigmoidf_(float x) { return __builtin_amdgcn_rcpf(1.f + __builtin_amdgcn_exp2f(x * -1.4426950408889634f)); }
; __device__ __forceinline__ u32x2 pack4(float a, float b, float c, float d) { return u32x2{cvtpk(a, b), cvtpk(c, d)}; }
; __device__ __forceinline__ u32x2 pack4(const f32x4& v) { return u32x2{cvtpk(v[0], v[1]), cvtpk(v[2], v[3])}; }
; #define SBAR() __builtin_amdgcn_sched_barrier(0)
; __global__ void __launch_bounds__(512) fwd_megakernel(Params p) {
;     ...
;           #pragma unroll
;           for (int ai = 0; ai < 2; ++ai)
;             #pragma unroll
;             for (int m = 0; m < 4; ++m) { SBAR();
;               int lrow = ai * 128 + wr * 64 + m * 16 + fr, row = brow + lrow; float rs = xl[lrow];
;               #pragma unroll
;               for (int n = 0; n < 2; ++n) {
;                 float u[4];
;                 #pragma unroll
;                 for (int j = 0; j < 4; ++j) { float val = acc[ai][0][m][n][j] * rs, gate = acc[ai][1][m][n][j] * rs; u[j] = val * sigmoidf_(gate); }
;                 *reinterpret_cast<u32x2*>(p_u0 + (long)row * CONVC + pn * 128 + wc * 32 + n * 16 + fq * 4) = pack4(u[0], u[1], u[2], u[3]);
;               }
;             }
	v_mul_f32_e32 v92, v92, v98
	v_mul_f32_e32 v92, 0xbfb8aa3b, v92
	v_exp_f32_e32 v92, v92
	v_mul_f32_e32 v84, v84, v98
	v_mul_f32_e32 v84, 0xbfb8aa3b, v84
	v_mul_f32_e32 v93, v93, v98
	v_add_f32_e32 v92, 1.0, v92
	v_exp_f32_e32 v84, v84
	v_mul_f32_e32 v93, 0xbfb8aa3b, v93
	v_rcp_f32_e32 v92, v92
	v_exp_f32_e32 v93, v93
	v_mul_f32_e32 v85, v85, v98
	v_mul_f32_e32 v88, v88, v98
	v_add_f32_e32 v84, 1.0, v84
	v_mul_f32_e32 v85, 0xbfb8aa3b, v85
	v_mul_f32_e32 v88, v88, v92
	v_mul_f32_e32 v92, v94, v98
	v_mul_f32_e32 v94, v95, v98
	v_rcp_f32_e32 v84, v84
	v_exp_f32_e32 v85, v85
	v_add_f32_e32 v93, 1.0, v93
	v_mul_f32_e32 v92, 0xbfb8aa3b, v92
	v_mul_f32_e32 v94, 0xbfb8aa3b, v94
	v_rcp_f32_e32 v93, v93
	v_exp_f32_e32 v92, v92
	v_exp_f32_e32 v94, v94
	v_mul_f32_e32 v80, v80, v98
	v_mul_f32_e32 v80, v80, v84
	v_add_f32_e32 v84, 1.0, v85
	v_mul_f32_e32 v85, v86, v98
	v_mul_f32_e32 v86, v87, v98
	v_mul_f32_e32 v89, v89, v98
	v_mul_f32_e32 v85, 0xbfb8aa3b, v85
	v_mul_f32_e32 v86, 0xbfb8aa3b, v86
	v_mul_f32_e32 v89, v89, v93
	v_add_f32_e32 v92, 1.0, v92
	v_add_f32_e32 v93, 1.0, v94
	v_rcp_f32_e32 v84, v84
	v_exp_f32_e32 v85, v85
	v_exp_f32_e32 v86, v86
	v_rcp_f32_e32 v92, v92
	v_rcp_f32_e32 v93, v93
	v_mul_f32_e32 v81, v81, v98
	v_mul_f32_e32 v90, v90, v98
	v_mul_f32_e32 v91, v91, v98
	v_mul_f32_e32 v81, v81, v84
	v_add_f32_e32 v84, 1.0, v85
	v_add_f32_e32 v85, 1.0, v86
	v_mul_f32_e32 v90, v90, v92
	v_mul_f32_e32 v91, v91, v93
	v_rcp_f32_e32 v84, v84
	v_rcp_f32_e32 v85, v85
	v_cvt_pk_bf16_f32 v88, v88, v89
	v_cvt_pk_bf16_f32 v89, v90, v91
	v_lshl_add_u64 v[90:91], s[10:11], 0, v[96:97]
	v_lshl_add_u64 v[90:91], v[90:91], 0, s[0:1]
	v_lshl_add_u64 v[90:91], v[90:91], 0, v[194:195]
	v_mul_f32_e32 v82, v82, v98
	v_mul_f32_e32 v83, v83, v98
	v_lshl_add_u64 v[90:91], v[90:91], 0, v[120:121]
	v_mul_f32_e32 v82, v82, v84
	v_mul_f32_e32 v83, v83, v85
	v_mov_b32_e32 v184, v88
	v_mov_b32_e32 v185, v89
	v_cvt_pk_bf16_f32 v80, v80, v81
	v_cvt_pk_bf16_f32 v81, v82, v83
	v_lshl_add_u64 v[82:83], s[34:35], 0, v[96:97]
	v_lshl_add_u64 v[82:83], v[82:83], 0, s[0:1]
	v_lshl_add_u64 v[82:83], v[82:83], 0, v[194:195]
	v_lshl_add_u64 v[82:83], v[82:83], 0, v[120:121]
	v_add_co_u32_e32 v82, vcc, s62, v82
	s_nop 1
	v_addc_co_u32_e32 v83, vcc, 0, v83, vcc
	v_mov_b32_e32 v186, v80
	v_mov_b32_e32 v187, v81
	v_bfe_u32 v188, v252, 4, 1
	v_mul_u32_u24_e32 v188, 24, v188
	v_mov_b32_e32 v189, 0
	v_lshl_add_u64 v[182:183], v[82:83], 0, v[188:189]
	v_permlane16_swap_b32_e32 v184, v186
	v_permlane16_swap_b32_e32 v185, v187
	global_store_dwordx4 v[182:183], v[184:187], off
	s_nop 1
	v_or_b32_e32 v80, 48, v131
	v_lshl_add_u32 v81, v80, 2, s67
	ds_read_b32 v82, v81
	v_add_u32_e32 v80, s80, v80
	v_ashrrev_i32_e32 v81, 31, v80
	v_lshlrev_b64 v[80:81], 10, v[80:81]
	s_waitcnt lgkmcnt(0)
	v_mul_f32_e32 v76, v76, v82
	v_mul_f32_e32 v76, 0xbfb8aa3b, v76
	v_exp_f32_e32 v76, v76
	v_mul_f32_e32 v68, v68, v82
	v_mul_f32_e32 v68, 0xbfb8aa3b, v68
	v_mul_f32_e32 v77, v77, v82
	v_add_f32_e32 v76, 1.0, v76
	v_exp_f32_e32 v68, v68
	v_mul_f32_e32 v77, 0xbfb8aa3b, v77
	v_rcp_f32_e32 v76, v76
	v_exp_f32_e32 v77, v77
	v_mul_f32_e32 v69, v69, v82
	v_mul_f32_e32 v72, v72, v82
	v_add_f32_e32 v68, 1.0, v68
	v_mul_f32_e32 v69, 0xbfb8aa3b, v69
	v_mul_f32_e32 v72, v72, v76
	v_mul_f32_e32 v76, v78, v82
	v_mul_f32_e32 v78, v79, v82
	v_rcp_f32_e32 v68, v68
	v_exp_f32_e32 v69, v69
	v_add_f32_e32 v77, 1.0, v77
	v_mul_f32_e32 v76, 0xbfb8aa3b, v76
	v_mul_f32_e32 v78, 0xbfb8aa3b, v78
	v_rcp_f32_e32 v77, v77
	v_exp_f32_e32 v76, v76
	v_exp_f32_e32 v78, v78
	v_mul_f32_e32 v64, v64, v82
	v_mul_f32_e32 v64, v64, v68
	v_add_f32_e32 v68, 1.0, v69
	v_mul_f32_e32 v69, v70, v82
	v_mul_f32_e32 v70, v71, v82
	v_mul_f32_e32 v73, v73, v82
	v_mul_f32_e32 v69, 0xbfb8aa3b, v69
	v_mul_f32_e32 v70, 0xbfb8aa3b, v70
	v_mul_f32_e32 v73, v73, v77
	v_add_f32_e32 v76, 1.0, v76
	v_add_f32_e32 v77, 1.0, v78
	v_rcp_f32_e32 v68, v68
	v_exp_f32_e32 v69, v69
	v_exp_f32_e32 v70, v70
	v_rcp_f32_e32 v76, v76
	v_rcp_f32_e32 v77, v77
	v_mul_f32_e32 v65, v65, v82
	v_mul_f32_e32 v74, v74, v82
	v_mul_f32_e32 v75, v75, v82
	v_mul_f32_e32 v65, v65, v68
	v_add_f32_e32 v68, 1.0, v69
	v_add_f32_e32 v69, 1.0, v70
	v_mul_f32_e32 v74, v74, v76
	v_mul_f32_e32 v75, v75, v77
	v_rcp_f32_e32 v68, v68
	v_rcp_f32_e32 v69, v69
	v_cvt_pk_bf16_f32 v72, v72, v73
	v_cvt_pk_bf16_f32 v73, v74, v75
	v_lshl_add_u64 v[74:75], s[10:11], 0, v[80:81]
	v_lshl_add_u64 v[74:75], v[74:75], 0, s[0:1]
	v_lshl_add_u64 v[74:75], v[74:75], 0, v[194:195]
	v_mul_f32_e32 v66, v66, v82
	v_mul_f32_e32 v67, v67, v82
	v_lshl_add_u64 v[74:75], v[74:75], 0, v[120:121]
	v_mul_f32_e32 v66, v66, v68
	v_mul_f32_e32 v67, v67, v69
	v_mov_b32_e32 v184, v72
	v_mov_b32_e32 v185, v73
	v_cvt_pk_bf16_f32 v64, v64, v65
	v_cvt_pk_bf16_f32 v65, v66, v67
	v_lshl_add_u64 v[66:67], s[34:35], 0, v[80:81]
	v_lshl_add_u64 v[66:67], v[66:67], 0, s[0:1]
	v_lshl_add_u64 v[66:67], v[66:67], 0, v[194:195]
	v_lshl_add_u64 v[66:67], v[66:67], 0, v[120:121]
	v_add_co_u32_e32 v66, vcc, s62, v66
	s_nop 1
	v_addc_co_u32_e32 v67, vcc, 0, v67, vcc
	v_mov_b32_e32 v186, v64
	v_mov_b32_e32 v187, v65
	v_bfe_u32 v188, v252, 4, 1
	v_mul_u32_u24_e32 v188, 24, v188
	v_mov_b32_e32 v189, 0
	v_lshl_add_u64 v[182:183], v[66:67], 0, v[188:189]
	v_permlane16_swap_b32_e32 v184, v186
	v_permlane16_swap_b32_e32 v185, v187
	global_store_dwordx4 v[182:183], v[184:187], off
	s_nop 1
	ds_read_b32 v66, v130 offset:512
	v_add_u32_e32 v64, 0x80, v128
	v_ashrrev_i32_e32 v65, 31, v64
	v_lshlrev_b64 v[64:65], 10, v[64:65]
	s_waitcnt lgkmcnt(0)
; __device__ __forceinline__ float sigmoidf_(float x) { return __builtin_amdgcn_rcpf(1.f + __builtin_amdgcn_exp2f(x * -1.4426950408889634f)); }
; __device__ __forceinline__ u32x2 pack4(float a, float b, float c, float d) { return u32x2{cvtpk(a, b), cvtpk(c, d)}; }
; __device__ __forceinline__ u32x2 pack4(const f32x4& v) { return u32x2{cvtpk(v[0], v[1]), cvtpk(v[2], v[3])}; }
; #define SBAR() __builtin_amdgcn_sched_barrier(0)
; __global__ void __launch_bounds__(512) fwd_megakernel(Params p) {
;     ...
;           #pragma unroll
;           for (int ai = 0; ai < 2; ++ai)
;             #pragma unroll
;             for (int m = 0; m < 4; ++m) { SBAR();
;               int lrow = ai * 128 + wr * 64 + m * 16 + fr, row = brow + lrow; float rs = xl[lrow];
;               #pragma unroll
;               for (int n = 0; n < 2; ++n) {
;                 float u[4];
;                 #pragma unroll
;                 for (int j = 0; j < 4; ++j) { float val = acc[ai][0][m][n][j] * rs, gate = acc[ai][1][m][n][j] * rs; u[j] = val * sigmoidf_(gate); }
;                 *reinterpret_cast<u32x2*>(p_u0 + (long)row * CONVC + pn * 128 + wc * 32 + n * 16 + fq * 4) = pack4(u[0], u[1], u[2], u[3]);
;               }
;             }
	v_mul_f32_e32 v60, v60, v66
	v_mul_f32_e32 v60, 0xbfb8aa3b, v60
	v_exp_f32_e32 v60, v60
	v_mul_f32_e32 v52, v52, v66
	v_mul_f32_e32 v52, 0xbfb8aa3b, v52
	v_mul_f32_e32 v61, v61, v66
	v_add_f32_e32 v60, 1.0, v60
	v_exp_f32_e32 v52, v52
	v_mul_f32_e32 v61, 0xbfb8aa3b, v61
	v_rcp_f32_e32 v60, v60
	v_exp_f32_e32 v61, v61
	v_mul_f32_e32 v53, v53, v66
	v_mul_f32_e32 v56, v56, v66
	v_add_f32_e32 v52, 1.0, v52
	v_mul_f32_e32 v53, 0xbfb8aa3b, v53
	v_mul_f32_e32 v56, v56, v60
	v_mul_f32_e32 v60, v62, v66
	v_mul_f32_e32 v62, v63, v66
	v_rcp_f32_e32 v52, v52
	v_exp_f32_e32 v53, v53
	v_add_f32_e32 v61, 1.0, v61
	v_mul_f32_e32 v60, 0xbfb8aa3b, v60
	v_mul_f32_e32 v62, 0xbfb8aa3b, v62
	v_rcp_f32_e32 v61, v61
	v_exp_f32_e32 v60, v60
	v_exp_f32_e32 v62, v62
	v_mul_f32_e32 v48, v48, v66
	v_mul_f32_e32 v48, v48, v52
	v_add_f32_e32 v52, 1.0, v53
	v_mul_f32_e32 v53, v54, v66
	v_mul_f32_e32 v54, v55, v66
	v_mul_f32_e32 v57, v57, v66
	v_mul_f32_e32 v53, 0xbfb8aa3b, v53
	v_mul_f32_e32 v54, 0xbfb8aa3b, v54
	v_mul_f32_e32 v57, v57, v61
	v_add_f32_e32 v60, 1.0, v60
	v_add_f32_e32 v61, 1.0, v62
	v_rcp_f32_e32 v52, v52
	v_exp_f32_e32 v53, v53
	v_exp_f32_e32 v54, v54
	v_rcp_f32_e32 v60, v60
	v_rcp_f32_e32 v61, v61
	v_mul_f32_e32 v49, v49, v66
	v_mul_f32_e32 v58, v58, v66
	v_mul_f32_e32 v59, v59, v66
	v_mul_f32_e32 v49, v49, v52
	v_add_f32_e32 v52, 1.0, v53
	v_add_f32_e32 v53, 1.0, v54
	v_mul_f32_e32 v58, v58, v60
	v_mul_f32_e32 v59, v59, v61
	v_rcp_f32_e32 v52, v52
	v_rcp_f32_e32 v53, v53
	v_cvt_pk_bf16_f32 v56, v56, v57
	v_cvt_pk_bf16_f32 v57, v58, v59
	v_lshl_add_u64 v[58:59], s[10:11], 0, v[64:65]
	v_lshl_add_u64 v[58:59], v[58:59], 0, s[0:1]
	v_lshl_add_u64 v[58:59], v[58:59], 0, v[194:195]
	v_mul_f32_e32 v50, v50, v66
	v_mul_f32_e32 v51, v51, v66
	v_lshl_add_u64 v[58:59], v[58:59], 0, v[120:121]
	v_mul_f32_e32 v50, v50, v52
	v_mul_f32_e32 v51, v51, v53
	v_mov_b32_e32 v184, v56
	v_mov_b32_e32 v185, v57
	v_cvt_pk_bf16_f32 v48, v48, v49
	v_cvt_pk_bf16_f32 v49, v50, v51
	v_lshl_add_u64 v[50:51], s[34:35], 0, v[64:65]
	v_lshl_add_u64 v[50:51], v[50:51], 0, s[0:1]
	v_lshl_add_u64 v[50:51], v[50:51], 0, v[194:195]
	v_lshl_add_u64 v[50:51], v[50:51], 0, v[120:121]
	v_add_co_u32_e32 v50, vcc, s62, v50
	s_nop 1
	v_addc_co_u32_e32 v51, vcc, 0, v51, vcc
	v_mov_b32_e32 v186, v48
	v_mov_b32_e32 v187, v49
	v_bfe_u32 v188, v252, 4, 1
	v_mul_u32_u24_e32 v188, 24, v188
	v_mov_b32_e32 v189, 0
	v_lshl_add_u64 v[182:183], v[50:51], 0, v[188:189]
	v_permlane16_swap_b32_e32 v184, v186
	v_permlane16_swap_b32_e32 v185, v187
	global_store_dwordx4 v[182:183], v[184:187], off
	s_nop 1
	ds_read_b32 v50, v130 offset:576
	v_add_u32_e32 v48, 0x90, v128
	v_ashrrev_i32_e32 v49, 31, v48
	v_lshlrev_b64 v[48:49], 10, v[48:49]
	s_waitcnt lgkmcnt(0)
	v_mul_f32_e32 v44, v44, v50
	v_mul_f32_e32 v44, 0xbfb8aa3b, v44
	v_exp_f32_e32 v44, v44
	v_mul_f32_e32 v36, v36, v50
	v_mul_f32_e32 v36, 0xbfb8aa3b, v36
	v_mul_f32_e32 v45, v45, v50
	v_add_f32_e32 v44, 1.0, v44
	v_exp_f32_e32 v36, v36
	v_mul_f32_e32 v45, 0xbfb8aa3b, v45
	v_rcp_f32_e32 v44, v44
	v_exp_f32_e32 v45, v45
	v_mul_f32_e32 v37, v37, v50
	v_mul_f32_e32 v40, v40, v50
	v_add_f32_e32 v36, 1.0, v36
	v_mul_f32_e32 v37, 0xbfb8aa3b, v37
	v_mul_f32_e32 v40, v40, v44
	v_mul_f32_e32 v44, v46, v50
	v_mul_f32_e32 v46, v47, v50
	v_rcp_f32_e32 v36, v36
	v_exp_f32_e32 v37, v37
	v_add_f32_e32 v45, 1.0, v45
	v_mul_f32_e32 v44, 0xbfb8aa3b, v44
	v_mul_f32_e32 v46, 0xbfb8aa3b, v46
	v_rcp_f32_e32 v45, v45
	v_exp_f32_e32 v44, v44
	v_exp_f32_e32 v46, v46
	v_mul_f32_e32 v32, v32, v50
	v_mul_f32_e32 v32, v32, v36
	v_add_f32_e32 v36, 1.0, v37
	v_mul_f32_e32 v37, v38, v50
	v_mul_f32_e32 v38, v39, v50
	v_mul_f32_e32 v41, v41, v50
	v_mul_f32_e32 v37, 0xbfb8aa3b, v37
	v_mul_f32_e32 v38, 0xbfb8aa3b, v38
	v_mul_f32_e32 v41, v41, v45
	v_add_f32_e32 v44, 1.0, v44
	v_add_f32_e32 v45, 1.0, v46
	v_rcp_f32_e32 v36, v36
	v_exp_f32_e32 v37, v37
	v_exp_f32_e32 v38, v38
	v_rcp_f32_e32 v44, v44
	v_rcp_f32_e32 v45, v45
	v_mul_f32_e32 v33, v33, v50
	v_mul_f32_e32 v42, v42, v50
	v_mul_f32_e32 v43, v43, v50
	v_mul_f32_e32 v33, v33, v36
	v_add_f32_e32 v36, 1.0, v37
	v_add_f32_e32 v37, 1.0, v38
	v_mul_f32_e32 v42, v42, v44
	v_mul_f32_e32 v43, v43, v45
	v_rcp_f32_e32 v36, v36
	v_rcp_f32_e32 v37, v37
	v_cvt_pk_bf16_f32 v40, v40, v41
	v_cvt_pk_bf16_f32 v41, v42, v43
	v_lshl_add_u64 v[42:43], s[10:11], 0, v[48:49]
	v_lshl_add_u64 v[42:43], v[42:43], 0, s[0:1]
	v_lshl_add_u64 v[42:43], v[42:43], 0, v[194:195]
	v_mul_f32_e32 v34, v34, v50
	v_mul_f32_e32 v35, v35, v50
	v_lshl_add_u64 v[42:43], v[42:43], 0, v[120:121]
	v_mul_f32_e32 v34, v34, v36
	v_mul_f32_e32 v35, v35, v37
	v_mov_b32_e32 v184, v40
	v_mov_b32_e32 v185, v41
	v_cvt_pk_bf16_f32 v32, v32, v33
	v_cvt_pk_bf16_f32 v33, v34, v35
	v_lshl_add_u64 v[34:35], s[34:35], 0, v[48:49]
	v_lshl_add_u64 v[34:35], v[34:35], 0, s[0:1]
	v_lshl_add_u64 v[34:35], v[34:35], 0, v[194:195]
	v_lshl_add_u64 v[34:35], v[34:35], 0, v[120:121]
	v_add_co_u32_e32 v34, vcc, s62, v34
	s_nop 1
	v_addc_co_u32_e32 v35, vcc, 0, v35, vcc
	v_mov_b32_e32 v186, v32
	v_mov_b32_e32 v187, v33
	v_bfe_u32 v188, v252, 4, 1
	v_mul_u32_u24_e32 v188, 24, v188
	v_mov_b32_e32 v189, 0
	v_lshl_add_u64 v[182:183], v[34:35], 0, v[188:189]
	v_permlane16_swap_b32_e32 v184, v186
	v_permlane16_swap_b32_e32 v185, v187
	global_store_dwordx4 v[182:183], v[184:187], off
	s_nop 1
	ds_read_b32 v34, v130 offset:640
	v_add_u32_e32 v32, 0xa0, v128
	v_ashrrev_i32_e32 v33, 31, v32
	v_lshlrev_b64 v[32:33], 10, v[32:33]
	s_waitcnt lgkmcnt(0)
; __device__ __forceinline__ float sigmoidf_(float x) { return __builtin_amdgcn_rcpf(1.f + __builtin_amdgcn_exp2f(x * -1.4426950408889634f)); }
; __device__ __forceinline__ u32x2 pack4(float a, float b, float c, float d) { return u32x2{cvtpk(a, b), cvtpk(c, d)}; }
; __device__ __forceinline__ u32x2 pack4(const f32x4& v) { return u32x2{cvtpk(v[0], v[1]), cvtpk(v[2], v[3])}; }
; #define SBAR() __builtin_amdgcn_sched_barrier(0)
; __global__ void __launch_bounds__(512) fwd_megakernel(Params p) {
;     ...
;           #pragma unroll
;           for (int ai = 0; ai < 2; ++ai)
;             #pragma unroll
;             for (int m = 0; m < 4; ++m) { SBAR();
;               int lrow = ai * 128 + wr * 64 + m * 16 + fr, row = brow + lrow; float rs = xl[lrow];
;               #pragma unroll
;               for (int n = 0; n < 2; ++n) {
;                 float u[4];
;                 #pragma unroll
;                 for (int j = 0; j < 4; ++j) { float val = acc[ai][0][m][n][j] * rs, gate = acc[ai][1][m][n][j] * rs; u[j] = val * sigmoidf_(gate); }
;                 *reinterpret_cast<u32x2*>(p_u0 + (long)row * CONVC + pn * 128 + wc * 32 + n * 16 + fq * 4) = pack4(u[0], u[1], u[2], u[3]);
;               }
;             }
	v_mul_f32_e32 v28, v28, v34
	v_mul_f32_e32 v28, 0xbfb8aa3b, v28
	v_exp_f32_e32 v28, v28
	v_mul_f32_e32 v20, v20, v34
	v_mul_f32_e32 v20, 0xbfb8aa3b, v20
	v_mul_f32_e32 v29, v29, v34
	v_add_f32_e32 v28, 1.0, v28
	v_exp_f32_e32 v20, v20
	v_mul_f32_e32 v29, 0xbfb8aa3b, v29
	v_rcp_f32_e32 v28, v28
	v_exp_f32_e32 v29, v29
	v_mul_f32_e32 v21, v21, v34
	v_mul_f32_e32 v24, v24, v34
	v_add_f32_e32 v20, 1.0, v20
	v_mul_f32_e32 v21, 0xbfb8aa3b, v21
	v_mul_f32_e32 v24, v24, v28
	v_mul_f32_e32 v28, v30, v34
	v_mul_f32_e32 v30, v31, v34
	v_rcp_f32_e32 v20, v20
	v_exp_f32_e32 v21, v21
	v_add_f32_e32 v29, 1.0, v29
	v_mul_f32_e32 v28, 0xbfb8aa3b, v28
	v_mul_f32_e32 v30, 0xbfb8aa3b, v30
	v_rcp_f32_e32 v29, v29
	v_exp_f32_e32 v28, v28
	v_exp_f32_e32 v30, v30
	v_mul_f32_e32 v16, v16, v34
	v_mul_f32_e32 v16, v16, v20
	v_add_f32_e32 v20, 1.0, v21
	v_mul_f32_e32 v21, v22, v34
	v_mul_f32_e32 v22, v23, v34
	v_mul_f32_e32 v25, v25, v34
	v_mul_f32_e32 v21, 0xbfb8aa3b, v21
	v_mul_f32_e32 v22, 0xbfb8aa3b, v22
	v_mul_f32_e32 v25, v25, v29
	v_add_f32_e32 v28, 1.0, v28
	v_add_f32_e32 v29, 1.0, v30
	v_rcp_f32_e32 v20, v20
	v_exp_f32_e32 v21, v21
	v_exp_f32_e32 v22, v22
	v_rcp_f32_e32 v28, v28
	v_rcp_f32_e32 v29, v29
	v_mul_f32_e32 v17, v17, v34
	v_mul_f32_e32 v26, v26, v34
	v_mul_f32_e32 v27, v27, v34
	v_mul_f32_e32 v17, v17, v20
	v_add_f32_e32 v20, 1.0, v21
	v_add_f32_e32 v21, 1.0, v22
	v_mul_f32_e32 v26, v26, v28
	v_mul_f32_e32 v27, v27, v29
	v_rcp_f32_e32 v20, v20
	v_rcp_f32_e32 v21, v21
	v_cvt_pk_bf16_f32 v24, v24, v25
	v_cvt_pk_bf16_f32 v25, v26, v27
	v_lshl_add_u64 v[26:27], s[10:11], 0, v[32:33]
	v_lshl_add_u64 v[26:27], v[26:27], 0, s[0:1]
	v_lshl_add_u64 v[26:27], v[26:27], 0, v[194:195]
	v_mul_f32_e32 v18, v18, v34
	v_mul_f32_e32 v19, v19, v34
	v_lshl_add_u64 v[26:27], v[26:27], 0, v[120:121]
	v_mul_f32_e32 v18, v18, v20
	v_mul_f32_e32 v19, v19, v21
	v_mov_b32_e32 v184, v24
	v_mov_b32_e32 v185, v25
	v_cvt_pk_bf16_f32 v16, v16, v17
	v_cvt_pk_bf16_f32 v17, v18, v19
	v_lshl_add_u64 v[18:19], s[34:35], 0, v[32:33]
	v_lshl_add_u64 v[18:19], v[18:19], 0, s[0:1]
	v_lshl_add_u64 v[18:19], v[18:19], 0, v[194:195]
	v_lshl_add_u64 v[18:19], v[18:19], 0, v[120:121]
	v_add_co_u32_e32 v18, vcc, s62, v18
	s_nop 1
	v_addc_co_u32_e32 v19, vcc, 0, v19, vcc
	v_mov_b32_e32 v186, v16
	v_mov_b32_e32 v187, v17
	v_bfe_u32 v188, v252, 4, 1
	v_mul_u32_u24_e32 v188, 24, v188
	v_mov_b32_e32 v189, 0
	v_lshl_add_u64 v[182:183], v[18:19], 0, v[188:189]
	v_permlane16_swap_b32_e32 v184, v186
	v_permlane16_swap_b32_e32 v185, v187
	global_store_dwordx4 v[182:183], v[184:187], off
	s_nop 1
	ds_read_b32 v18, v130 offset:704
	v_add_u32_e32 v16, 0xb0, v128
	v_ashrrev_i32_e32 v17, 31, v16
	v_lshlrev_b64 v[16:17], 10, v[16:17]
	s_waitcnt lgkmcnt(0)
	v_mul_f32_e32 v12, v12, v18
	v_mul_f32_e32 v12, 0xbfb8aa3b, v12
	v_exp_f32_e32 v12, v12
	v_mul_f32_e32 v4, v4, v18
	v_mul_f32_e32 v4, 0xbfb8aa3b, v4
	v_mul_f32_e32 v13, v13, v18
	v_add_f32_e32 v12, 1.0, v12
	v_exp_f32_e32 v4, v4
	v_mul_f32_e32 v13, 0xbfb8aa3b, v13
	v_rcp_f32_e32 v12, v12
	v_exp_f32_e32 v13, v13
	v_mul_f32_e32 v5, v5, v18
	v_mul_f32_e32 v8, v8, v18
	v_add_f32_e32 v4, 1.0, v4
	v_mul_f32_e32 v5, 0xbfb8aa3b, v5
	v_mul_f32_e32 v8, v8, v12
	v_mul_f32_e32 v12, v14, v18
	v_mul_f32_e32 v14, v15, v18
	v_rcp_f32_e32 v4, v4
	v_exp_f32_e32 v5, v5
	v_add_f32_e32 v13, 1.0, v13
	v_mul_f32_e32 v12, 0xbfb8aa3b, v12
	v_mul_f32_e32 v14, 0xbfb8aa3b, v14
	v_rcp_f32_e32 v13, v13
	v_exp_f32_e32 v12, v12
	v_exp_f32_e32 v14, v14
	v_mul_f32_e32 v0, v0, v18
	v_mul_f32_e32 v0, v0, v4
	v_add_f32_e32 v4, 1.0, v5
	v_mul_f32_e32 v5, v6, v18
	v_mul_f32_e32 v6, v7, v18
	v_mul_f32_e32 v9, v9, v18
	v_mul_f32_e32 v5, 0xbfb8aa3b, v5
	v_mul_f32_e32 v6, 0xbfb8aa3b, v6
	v_mul_f32_e32 v9, v9, v13
	v_add_f32_e32 v12, 1.0, v12
	v_add_f32_e32 v13, 1.0, v14
	v_rcp_f32_e32 v4, v4
	v_exp_f32_e32 v5, v5
	v_exp_f32_e32 v6, v6
	v_rcp_f32_e32 v12, v12
	v_rcp_f32_e32 v13, v13
	v_mul_f32_e32 v1, v1, v18
	v_mul_f32_e32 v10, v10, v18
	v_mul_f32_e32 v11, v11, v18
	v_mul_f32_e32 v1, v1, v4
	v_add_f32_e32 v4, 1.0, v5
	v_add_f32_e32 v5, 1.0, v6
	v_mul_f32_e32 v10, v10, v12
	v_mul_f32_e32 v11, v11, v13
	v_rcp_f32_e32 v4, v4
	v_rcp_f32_e32 v5, v5
	v_cvt_pk_bf16_f32 v8, v8, v9
	v_cvt_pk_bf16_f32 v9, v10, v11
	v_lshl_add_u64 v[10:11], s[10:11], 0, v[16:17]
	v_lshl_add_u64 v[10:11], v[10:11], 0, s[0:1]
	v_lshl_add_u64 v[10:11], v[10:11], 0, v[194:195]
	v_mul_f32_e32 v2, v2, v18
	v_mul_f32_e32 v3, v3, v18
	v_lshl_add_u64 v[10:11], v[10:11], 0, v[120:121]
	v_mul_f32_e32 v2, v2, v4
	v_mul_f32_e32 v3, v3, v5
	v_mov_b32_e32 v184, v8
	v_mov_b32_e32 v185, v9
	v_cvt_pk_bf16_f32 v0, v0, v1
	v_cvt_pk_bf16_f32 v1, v2, v3
	v_lshl_add_u64 v[2:3], s[34:35], 0, v[16:17]
	v_lshl_add_u64 v[2:3], v[2:3], 0, s[0:1]
	v_lshl_add_u64 v[2:3], v[2:3], 0, v[194:195]
	v_lshl_add_u64 v[2:3], v[2:3], 0, v[120:121]
	v_add_co_u32_e32 v2, vcc, 0x188a0000, v2
	s_nop 1
	v_addc_co_u32_e32 v3, vcc, 0, v3, vcc
	v_mov_b32_e32 v186, v0
	v_mov_b32_e32 v187, v1
	v_bfe_u32 v188, v252, 4, 1
	v_mul_u32_u24_e32 v188, 24, v188
	v_mov_b32_e32 v189, 0
	v_lshl_add_u64 v[182:183], v[2:3], 0, v[188:189]
	v_permlane16_swap_b32_e32 v184, v186
	v_permlane16_swap_b32_e32 v185, v187
	global_store_dwordx4 v[182:183], v[184:187], off
	s_nop 1
	s_branch .LBB0_218

;   #define WAIT_V(n) asm volatile("s_waitcnt vmcnt(" #n ")":::"memory")
;   #define BAR __builtin_amdgcn_s_barrier()
; template <class Pre, class Fin, class Epi> ...
;     ...
;   if (pf && pfE == 16)      { WAIT_V(26); BAR; WAIT_V(22); BAR; }
;   else if (pf && pfE == 32) { WAIT_V(42); BAR; WAIT_V(38); BAR; }
;   else                      { WAIT_V(10); BAR; WAIT_V(6); BAR; }
.LBB0_361:
	s_waitcnt vmcnt(24)
	s_barrier
	s_waitcnt vmcnt(20)
	s_barrier

; __device__ __forceinline__ u32x2 pack4(float a, float b, float c, float d) { return u32x2{cvtpk(a, b), cvtpk(c, d)}; }
; __device__ __forceinline__ u32x2 pack4(const f32x4& v) { return u32x2{cvtpk(v[0], v[1]), cvtpk(v[2], v[3])}; }
; #define SBAR() __builtin_amdgcn_sched_barrier(0)
; __global__ void __launch_bounds__(512) fwd_megakernel(Params p) {
;     ...
;           #pragma unroll
;           for (int ai = 0; ai < 2; ++ai)
;             #pragma unroll
;             for (int m = 0; m < 4; ++m) { SBAR();
;               int lrow = ai * 128 + wr * 64 + m * 16 + fr, row = brow + lrow; float rs = xl[lrow];
;               int b = row / LTOK, pos = row - b * LTOK; int key = pos < NMETA ? SEQ + pos : pos - NMETA;
;               long kr = (long)(b * NH + pk * 2) * KPAD + key;
;               bf16* d = (wc < 2) ? p_Kb + kr * DQK + wc * 32 + fq * 4 : p_Vb + kr * DV + (wc - 2) * 32 + fq * 4;
;               const long hstride = (wc < 2) ? (long)KPAD * DQK : (long)KPAD * DV;
;               #pragma unroll
;               for (int bj = 0; bj < 2; ++bj) {
;                 *reinterpret_cast<u32x2*>(d + bj * hstride) = pack4(acc[ai][bj][m][0] * rs);
;                 *reinterpret_cast<u32x2*>(d + bj * hstride + 16) = pack4(acc[ai][bj][m][1] * rs);
;               }
.LBB0_377:
	s_or_b64 exec, exec, s[0:1]
	v_lshrrev_b32_e32 v129, 2, v140
	v_and_b32_e32 v129, 12, v129
	v_lshlrev_b32_e32 v160, 1, v129
	v_lshl_add_u64 v[134:135], v[134:135], 0, v[160:161]
	s_waitcnt lgkmcnt(0)
	v_pk_mul_f32 v[120:121], v[120:121], v[130:131] op_sel_hi:[1,0]
	v_pk_mul_f32 v[112:113], v[112:113], v[130:131] op_sel_hi:[1,0]
	v_pk_mul_f32 v[122:123], v[122:123], v[130:131] op_sel_hi:[1,0]
	v_cvt_pk_bf16_f32 v120, v120, v121
	v_pk_mul_f32 v[114:115], v[114:115], v[130:131] op_sel_hi:[1,0]
	v_cvt_pk_bf16_f32 v121, v122, v123
	v_mov_b32_e32 v196, v120
	v_mov_b32_e32 v197, v121
	v_cvt_pk_bf16_f32 v112, v112, v113
	v_cvt_pk_bf16_f32 v113, v114, v115
	v_mov_b32_e32 v198, v112
	v_mov_b32_e32 v199, v113
	v_bfe_u32 v202, v252, 4, 1
	v_mul_u32_u24_e32 v202, 24, v202
	v_mov_b32_e32 v203, 0
	v_lshl_add_u64 v[200:201], v[134:135], 0, v[202:203]
	v_permlane16_swap_b32_e32 v196, v198
	v_permlane16_swap_b32_e32 v197, v199
	global_store_dwordx4 v[200:201], v[196:199], off
	s_nop 1
	v_pk_mul_f32 v[112:113], v[126:127], v[130:131] op_sel_hi:[1,0]
	v_pk_mul_f32 v[114:115], v[124:125], v[130:131] op_sel_hi:[1,0]
	v_pk_mul_f32 v[116:117], v[116:117], v[130:131] op_sel_hi:[1,0]
	v_cvt_pk_bf16_f32 v114, v114, v115
	v_cvt_pk_bf16_f32 v115, v112, v113
	v_lshlrev_b32_e32 v112, 1, v132
	v_mov_b32_e32 v113, v161
	v_lshl_add_u64 v[112:113], v[134:135], 0, v[112:113]
	v_mov_b32_e32 v196, v114
	v_mov_b32_e32 v197, v115
	v_pk_mul_f32 v[114:115], v[118:119], v[130:131] op_sel_hi:[1,0]
	v_cvt_pk_bf16_f32 v116, v116, v117
	s_nop 0
	v_cvt_pk_bf16_f32 v117, v114, v115
	v_mov_b32_e32 v198, v116
	v_mov_b32_e32 v199, v117
	v_bfe_u32 v202, v252, 4, 1
	v_mul_u32_u24_e32 v202, 24, v202
	v_mov_b32_e32 v203, 0
	v_lshl_add_u64 v[200:201], v[112:113], 0, v[202:203]
	v_permlane16_swap_b32_e32 v196, v198
	v_permlane16_swap_b32_e32 v197, v199
	global_store_dwordx4 v[200:201], v[196:199], off
	s_nop 1
	v_or_b32_e32 v112, 16, v139
	v_add_u32_e32 v113, s96, v112
	v_mul_hi_i32 v114, v113, s14
	v_lshrrev_b32_e32 v115, 31, v114
	v_ashrrev_i32_e32 v114, 7, v114
	v_lshl_add_u32 v112, v112, 2, 0
	v_add_u32_e32 v115, v114, v115
	v_add_u32_e32 v112, 0x20000, v112
	v_mad_i32_i24 v113, v115, s23, v113
	ds_read_b32 v112, v112
	v_cmp_gt_i32_e64 s[0:1], 16, v113
	s_nop 1
	v_cndmask_b32_e64 v114, -16, v171, s[0:1]
	v_add_u32_e32 v114, v114, v113
	v_lshl_add_u32 v113, v115, 3, s4
	v_ashrrev_i32_e32 v115, 31, v114
	v_mad_i64_i32 v[118:119], s[0:1], v113, s24, v[114:115]
	s_and_saveexec_b64 s[0:1], vcc
	s_xor_b64 s[0:1], exec, s[0:1]
	v_lshlrev_b64 v[114:115], 7, v[118:119]
	v_lshl_add_u64 v[114:115], s[34:35], 0, v[114:115]
	v_mov_b32_e32 v129, v161
	v_lshl_add_u64 v[114:115], v[114:115], 0, v[128:129]
	v_lshl_add_u64 v[116:117], v[114:115], 0, s[40:41]
	s_or_saveexec_b64 s[0:1], s[0:1]
	v_mov_b64_e32 v[114:115], 0x21000
	s_xor_b64 exec, exec, s[0:1]
	s_cbranch_execz .LBB0_381
	v_readlane_b32 s28, v254, 23
	v_readlane_b32 s29, v254, 24
	v_mov_b32_e32 v129, v161
	s_nop 0
	v_mov_b64_e32 v[114:115], s[28:29]
	v_mad_u64_u32 v[114:115], s[28:29], v118, s69, v[114:115]
	v_mov_b32_e32 v116, v115
	v_mad_u64_u32 v[116:117], s[28:29], v119, s69, v[116:117]
	v_mov_b32_e32 v115, v116
	v_lshl_add_u64 v[116:117], v[114:115], 0, v[128:129]
	v_mov_b64_e32 v[114:115], 0x31800
.LBB0_381:
	s_or_b64 exec, exec, s[0:1]
	v_lshl_add_u64 v[116:117], v[116:117], 0, v[160:161]
	s_waitcnt lgkmcnt(0)
	v_pk_mul_f32 v[104:105], v[104:105], v[112:113] op_sel_hi:[1,0]
	v_pk_mul_f32 v[96:97], v[96:97], v[112:113] op_sel_hi:[1,0]
	v_pk_mul_f32 v[106:107], v[106:107], v[112:113] op_sel_hi:[1,0]
	v_cvt_pk_bf16_f32 v104, v104, v105
	v_pk_mul_f32 v[98:99], v[98:99], v[112:113] op_sel_hi:[1,0]
	v_cvt_pk_bf16_f32 v105, v106, v107
	v_mov_b32_e32 v196, v104
	v_mov_b32_e32 v197, v105
	v_cvt_pk_bf16_f32 v96, v96, v97
	v_cvt_pk_bf16_f32 v97, v98, v99
	v_mov_b32_e32 v198, v96
	v_mov_b32_e32 v199, v97
	v_bfe_u32 v202, v252, 4, 1
	v_mul_u32_u24_e32 v202, 24, v202
	v_mov_b32_e32 v203, 0
	v_lshl_add_u64 v[200:201], v[116:117], 0, v[202:203]
	v_permlane16_swap_b32_e32 v196, v198
	v_permlane16_swap_b32_e32 v197, v199
	global_store_dwordx4 v[200:201], v[196:199], off
	s_nop 1
	v_pk_mul_f32 v[96:97], v[110:111], v[112:113] op_sel_hi:[1,0]
	v_pk_mul_f32 v[98:99], v[108:109], v[112:113] op_sel_hi:[1,0]
	v_pk_mul_f32 v[100:101], v[100:101], v[112:113] op_sel_hi:[1,0]
	v_cvt_pk_bf16_f32 v98, v98, v99
	v_cvt_pk_bf16_f32 v99, v96, v97
	v_lshlrev_b32_e32 v96, 1, v114
	v_mov_b32_e32 v97, v161
	v_lshl_add_u64 v[96:97], v[116:117], 0, v[96:97]
	v_mov_b32_e32 v196, v98
	v_mov_b32_e32 v197, v99
	v_pk_mul_f32 v[98:99], v[102:103], v[112:113] op_sel_hi:[1,0]
	v_cvt_pk_bf16_f32 v100, v100, v101
	s_nop 0
	v_cvt_pk_bf16_f32 v101, v98, v99
	v_mov_b32_e32 v198, v100
	v_mov_b32_e32 v199, v101
	v_bfe_u32 v202, v252, 4, 1
	v_mul_u32_u24_e32 v202, 24, v202
	v_mov_b32_e32 v203, 0
	v_lshl_add_u64 v[200:201], v[96:97], 0, v[202:203]
	v_permlane16_swap_b32_e32 v196, v198
	v_permlane16_swap_b32_e32 v197, v199
	global_store_dwordx4 v[200:201], v[196:199], off
	s_nop 1
	v_or_b32_e32 v96, 32, v139
	v_add_u32_e32 v97, s96, v96
	v_mul_hi_i32 v98, v97, s14
	v_lshrrev_b32_e32 v99, 31, v98
	v_ashrrev_i32_e32 v98, 7, v98
	v_lshl_add_u32 v96, v96, 2, 0
	v_add_u32_e32 v99, v98, v99
	v_add_u32_e32 v96, 0x20000, v96
	v_mad_i32_i24 v97, v99, s23, v97
	ds_read_b32 v96, v96
	v_cmp_gt_i32_e64 s[0:1], 16, v97
	s_nop 1
	v_cndmask_b32_e64 v98, -16, v171, s[0:1]
	v_add_u32_e32 v98, v98, v97
	v_lshl_add_u32 v97, v99, 3, s4
	v_ashrrev_i32_e32 v99, 31, v98
	v_mad_i64_i32 v[102:103], s[0:1], v97, s24, v[98:99]
	s_and_saveexec_b64 s[0:1], vcc
	s_xor_b64 s[0:1], exec, s[0:1]
	v_lshlrev_b64 v[98:99], 7, v[102:103]
	v_lshl_add_u64 v[98:99], s[34:35], 0, v[98:99]
	v_mov_b32_e32 v129, v161
	v_lshl_add_u64 v[98:99], v[98:99], 0, v[128:129]
	v_lshl_add_u64 v[100:101], v[98:99], 0, s[40:41]
	s_or_saveexec_b64 s[0:1], s[0:1]
	v_mov_b64_e32 v[98:99], 0x21000
	s_xor_b64 exec, exec, s[0:1]
	s_cbranch_execz .LBB0_385
	v_readlane_b32 s28, v254, 23
	v_readlane_b32 s29, v254, 24
	v_mov_b32_e32 v129, v161
	s_nop 0
	v_mov_b64_e32 v[98:99], s[28:29]
	v_mad_u64_u32 v[98:99], s[28:29], v102, s69, v[98:99]
	v_mov_b32_e32 v100, v99
	v_mad_u64_u32 v[100:101], s[28:29], v103, s69, v[100:101]
	v_mov_b32_e32 v99, v100
	v_lshl_add_u64 v[100:101], v[98:99], 0, v[128:129]
	v_mov_b64_e32 v[98:99], 0x31800
; __device__ __forceinline__ u32x2 pack4(float a, float b, float c, float d) { return u32x2{cvtpk(a, b), cvtpk(c, d)}; }
; __device__ __forceinline__ u32x2 pack4(const f32x4& v) { return u32x2{cvtpk(v[0], v[1]), cvtpk(v[2], v[3])}; }
; #define SBAR() __builtin_amdgcn_sched_barrier(0)
; __global__ void __launch_bounds__(512) fwd_megakernel(Params p) {
;     ...
;           #pragma unroll
;           for (int ai = 0; ai < 2; ++ai)
;             #pragma unroll
;             for (int m = 0; m < 4; ++m) { SBAR();
;               int lrow = ai * 128 + wr * 64 + m * 16 + fr, row = brow + lrow; float rs = xl[lrow];
;               int b = row / LTOK, pos = row - b * LTOK; int key = pos < NMETA ? SEQ + pos : pos - NMETA;
;               long kr = (long)(b * NH + pk * 2) * KPAD + key;
;               bf16* d = (wc < 2) ? p_Kb + kr * DQK + wc * 32 + fq * 4 : p_Vb + kr * DV + (wc - 2) * 32 + fq * 4;
;               const long hstride = (wc < 2) ? (long)KPAD * DQK : (long)KPAD * DV;
;               #pragma unroll
;               for (int bj = 0; bj < 2; ++bj) {
;                 *reinterpret_cast<u32x2*>(d + bj * hstride) = pack4(acc[ai][bj][m][0] * rs);
;                 *reinterpret_cast<u32x2*>(d + bj * hstride + 16) = pack4(acc[ai][bj][m][1] * rs);
;               }
.LBB0_385:
	s_or_b64 exec, exec, s[0:1]
	v_lshl_add_u64 v[100:101], v[100:101], 0, v[160:161]
	s_waitcnt lgkmcnt(0)
	v_pk_mul_f32 v[88:89], v[88:89], v[96:97] op_sel_hi:[1,0]
	v_pk_mul_f32 v[80:81], v[80:81], v[96:97] op_sel_hi:[1,0]
	v_pk_mul_f32 v[90:91], v[90:91], v[96:97] op_sel_hi:[1,0]
	v_cvt_pk_bf16_f32 v88, v88, v89
	v_pk_mul_f32 v[82:83], v[82:83], v[96:97] op_sel_hi:[1,0]
	v_cvt_pk_bf16_f32 v89, v90, v91
	v_mov_b32_e32 v196, v88
	v_mov_b32_e32 v197, v89
	v_cvt_pk_bf16_f32 v80, v80, v81
	v_cvt_pk_bf16_f32 v81, v82, v83
	v_mov_b32_e32 v198, v80
	v_mov_b32_e32 v199, v81
	v_bfe_u32 v202, v252, 4, 1
	v_mul_u32_u24_e32 v202, 24, v202
	v_mov_b32_e32 v203, 0
	v_lshl_add_u64 v[200:201], v[100:101], 0, v[202:203]
	v_permlane16_swap_b32_e32 v196, v198
	v_permlane16_swap_b32_e32 v197, v199
	global_store_dwordx4 v[200:201], v[196:199], off
	s_nop 1
	v_pk_mul_f32 v[80:81], v[94:95], v[96:97] op_sel_hi:[1,0]
	v_pk_mul_f32 v[82:83], v[92:93], v[96:97] op_sel_hi:[1,0]
	v_pk_mul_f32 v[84:85], v[84:85], v[96:97] op_sel_hi:[1,0]
	v_cvt_pk_bf16_f32 v82, v82, v83
	v_cvt_pk_bf16_f32 v83, v80, v81
	v_lshlrev_b32_e32 v80, 1, v98
	v_mov_b32_e32 v81, v161
	v_lshl_add_u64 v[80:81], v[100:101], 0, v[80:81]
	v_mov_b32_e32 v196, v82
	v_mov_b32_e32 v197, v83
	v_pk_mul_f32 v[82:83], v[86:87], v[96:97] op_sel_hi:[1,0]
	v_cvt_pk_bf16_f32 v84, v84, v85
	s_nop 0
	v_cvt_pk_bf16_f32 v85, v82, v83
	v_mov_b32_e32 v198, v84
	v_mov_b32_e32 v199, v85
	v_bfe_u32 v202, v252, 4, 1
	v_mul_u32_u24_e32 v202, 24, v202
	v_mov_b32_e32 v203, 0
	v_lshl_add_u64 v[200:201], v[80:81], 0, v[202:203]
	v_permlane16_swap_b32_e32 v196, v198
	v_permlane16_swap_b32_e32 v197, v199
	global_store_dwordx4 v[200:201], v[196:199], off
	s_nop 1
	v_or_b32_e32 v80, 48, v139
	v_add_u32_e32 v81, s96, v80
	v_mul_hi_i32 v82, v81, s14
	v_lshrrev_b32_e32 v83, 31, v82
	v_ashrrev_i32_e32 v82, 7, v82
	v_lshl_add_u32 v80, v80, 2, 0
	v_add_u32_e32 v83, v82, v83
	v_add_u32_e32 v80, 0x20000, v80
	v_mad_i32_i24 v81, v83, s23, v81
	ds_read_b32 v80, v80
	v_cmp_gt_i32_e64 s[0:1], 16, v81
	s_nop 1
	v_cndmask_b32_e64 v82, -16, v171, s[0:1]
	v_add_u32_e32 v82, v82, v81
	v_lshl_add_u32 v81, v83, 3, s4
	v_ashrrev_i32_e32 v83, 31, v82
	v_mad_i64_i32 v[86:87], s[0:1], v81, s24, v[82:83]
	s_and_saveexec_b64 s[0:1], vcc
	s_xor_b64 s[0:1], exec, s[0:1]
	v_lshlrev_b64 v[82:83], 7, v[86:87]
	v_lshl_add_u64 v[82:83], s[34:35], 0, v[82:83]
	v_mov_b32_e32 v129, v161
	v_lshl_add_u64 v[82:83], v[82:83], 0, v[128:129]
	v_lshl_add_u64 v[84:85], v[82:83], 0, s[40:41]
	s_or_saveexec_b64 s[0:1], s[0:1]
	v_mov_b64_e32 v[82:83], 0x21000
	s_xor_b64 exec, exec, s[0:1]
	s_cbranch_execz .LBB0_389
	v_readlane_b32 s28, v254, 23
	v_readlane_b32 s29, v254, 24
	v_mov_b32_e32 v129, v161
	s_nop 0
	v_mov_b64_e32 v[82:83], s[28:29]
	v_mad_u64_u32 v[82:83], s[28:29], v86, s69, v[82:83]
	v_mov_b32_e32 v84, v83
	v_mad_u64_u32 v[84:85], s[28:29], v87, s69, v[84:85]
	v_mov_b32_e32 v83, v84
	v_lshl_add_u64 v[84:85], v[82:83], 0, v[128:129]
	v_mov_b64_e32 v[82:83], 0x31800
.LBB0_389:
	s_or_b64 exec, exec, s[0:1]
	v_lshl_add_u64 v[84:85], v[84:85], 0, v[160:161]
	s_waitcnt lgkmcnt(0)
	v_pk_mul_f32 v[72:73], v[72:73], v[80:81] op_sel_hi:[1,0]
	v_pk_mul_f32 v[64:65], v[64:65], v[80:81] op_sel_hi:[1,0]
	v_pk_mul_f32 v[74:75], v[74:75], v[80:81] op_sel_hi:[1,0]
	v_cvt_pk_bf16_f32 v72, v72, v73
	v_pk_mul_f32 v[66:67], v[66:67], v[80:81] op_sel_hi:[1,0]
	v_cvt_pk_bf16_f32 v73, v74, v75
	v_mov_b32_e32 v196, v72
	v_mov_b32_e32 v197, v73
	v_cvt_pk_bf16_f32 v64, v64, v65
	v_cvt_pk_bf16_f32 v65, v66, v67
	v_mov_b32_e32 v198, v64
	v_mov_b32_e32 v199, v65
	v_bfe_u32 v202, v252, 4, 1
	v_mul_u32_u24_e32 v202, 24, v202
	v_mov_b32_e32 v203, 0
	v_lshl_add_u64 v[200:201], v[84:85], 0, v[202:203]
	v_permlane16_swap_b32_e32 v196, v198
	v_permlane16_swap_b32_e32 v197, v199
	global_store_dwordx4 v[200:201], v[196:199], off
	s_nop 1
	v_pk_mul_f32 v[64:65], v[78:79], v[80:81] op_sel_hi:[1,0]
	v_pk_mul_f32 v[66:67], v[76:77], v[80:81] op_sel_hi:[1,0]
	v_pk_mul_f32 v[68:69], v[68:69], v[80:81] op_sel_hi:[1,0]
	v_cvt_pk_bf16_f32 v66, v66, v67
	v_cvt_pk_bf16_f32 v67, v64, v65
	v_lshlrev_b32_e32 v64, 1, v82
	v_mov_b32_e32 v65, v161
	v_lshl_add_u64 v[64:65], v[84:85], 0, v[64:65]
	v_mov_b32_e32 v196, v66
	v_mov_b32_e32 v197, v67
	v_pk_mul_f32 v[66:67], v[70:71], v[80:81] op_sel_hi:[1,0]
	v_cvt_pk_bf16_f32 v68, v68, v69
	s_nop 0
	v_cvt_pk_bf16_f32 v69, v66, v67
	v_mov_b32_e32 v198, v68
	v_mov_b32_e32 v199, v69
	v_bfe_u32 v202, v252, 4, 1
	v_mul_u32_u24_e32 v202, 24, v202
	v_mov_b32_e32 v203, 0
	v_lshl_add_u64 v[200:201], v[64:65], 0, v[202:203]
	v_permlane16_swap_b32_e32 v196, v198
	v_permlane16_swap_b32_e32 v197, v199
	global_store_dwordx4 v[200:201], v[196:199], off
	s_nop 1
	v_add_u32_e32 v65, 0x80, v131
	v_mul_hi_i32 v66, v65, s14
	v_lshrrev_b32_e32 v67, 31, v66
	v_ashrrev_i32_e32 v66, 7, v66
	v_add_u32_e32 v67, v66, v67
	v_mad_i32_i24 v65, v67, s23, v65
	ds_read_b32 v64, v138 offset:512
	v_cmp_gt_i32_e64 s[0:1], 16, v65
	s_nop 1
	v_cndmask_b32_e64 v66, -16, v171, s[0:1]
	v_add_u32_e32 v66, v66, v65
	v_lshl_add_u32 v65, v67, 3, s4
	v_ashrrev_i32_e32 v67, 31, v66
	v_mad_i64_i32 v[70:71], s[0:1], v65, s24, v[66:67]
	s_and_saveexec_b64 s[0:1], vcc
	s_xor_b64 s[0:1], exec, s[0:1]
	v_lshlrev_b64 v[66:67], 7, v[70:71]
	v_lshl_add_u64 v[66:67], s[34:35], 0, v[66:67]
	v_mov_b32_e32 v129, v161
	v_lshl_add_u64 v[66:67], v[66:67], 0, v[128:129]
	v_lshl_add_u64 v[68:69], v[66:67], 0, s[40:41]
	s_or_saveexec_b64 s[0:1], s[0:1]
	v_mov_b64_e32 v[66:67], 0x21000
	s_xor_b64 exec, exec, s[0:1]
	s_cbranch_execz .LBB0_393
	v_readlane_b32 s28, v254, 23
	v_readlane_b32 s29, v254, 24
	v_mov_b32_e32 v129, v161
	s_nop 0
	v_mov_b64_e32 v[66:67], s[28:29]
	v_mad_u64_u32 v[66:67], s[28:29], v70, s69, v[66:67]
	v_mov_b32_e32 v68, v67
	v_mad_u64_u32 v[68:69], s[28:29], v71, s69, v[68:69]
	v_mov_b32_e32 v67, v68
	v_lshl_add_u64 v[68:69], v[66:67], 0, v[128:129]
	v_mov_b64_e32 v[66:67], 0x31800
; __device__ __forceinline__ u32x2 pack4(float a, float b, float c, float d) { return u32x2{cvtpk(a, b), cvtpk(c, d)}; }
; __device__ __forceinline__ u32x2 pack4(const f32x4& v) { return u32x2{cvtpk(v[0], v[1]), cvtpk(v[2], v[3])}; }
; #define SBAR() __builtin_amdgcn_sched_barrier(0)
; __global__ void __launch_bounds__(512) fwd_megakernel(Params p) {
;     ...
;           #pragma unroll
;           for (int ai = 0; ai < 2; ++ai)
;             #pragma unroll
;             for (int m = 0; m < 4; ++m) { SBAR();
;               int lrow = ai * 128 + wr * 64 + m * 16 + fr, row = brow + lrow; float rs = xl[lrow];
;               int b = row / LTOK, pos = row - b * LTOK; int key = pos < NMETA ? SEQ + pos : pos - NMETA;
;               long kr = (long)(b * NH + pk * 2) * KPAD + key;
;               bf16* d = (wc < 2) ? p_Kb + kr * DQK + wc * 32 + fq * 4 : p_Vb + kr * DV + (wc - 2) * 32 + fq * 4;
;               const long hstride = (wc < 2) ? (long)KPAD * DQK : (long)KPAD * DV;
;               #pragma unroll
;               for (int bj = 0; bj < 2; ++bj) {
;                 *reinterpret_cast<u32x2*>(d + bj * hstride) = pack4(acc[ai][bj][m][0] * rs);
;                 *reinterpret_cast<u32x2*>(d + bj * hstride + 16) = pack4(acc[ai][bj][m][1] * rs);
;               }
.LBB0_393:
	s_or_b64 exec, exec, s[0:1]
	v_lshl_add_u64 v[68:69], v[68:69], 0, v[160:161]
	s_waitcnt lgkmcnt(0)
	v_pk_mul_f32 v[60:61], v[60:61], v[64:65] op_sel_hi:[1,0]
	v_pk_mul_f32 v[52:53], v[52:53], v[64:65] op_sel_hi:[1,0]
	v_pk_mul_f32 v[62:63], v[62:63], v[64:65] op_sel_hi:[1,0]
	v_cvt_pk_bf16_f32 v60, v60, v61
	v_pk_mul_f32 v[54:55], v[54:55], v[64:65] op_sel_hi:[1,0]
	v_cvt_pk_bf16_f32 v61, v62, v63
	v_mov_b32_e32 v196, v60
	v_mov_b32_e32 v197, v61
	v_cvt_pk_bf16_f32 v52, v52, v53
	v_cvt_pk_bf16_f32 v53, v54, v55
	v_mov_b32_e32 v198, v52
	v_mov_b32_e32 v199, v53
	v_bfe_u32 v202, v252, 4, 1
	v_mul_u32_u24_e32 v202, 24, v202
	v_mov_b32_e32 v203, 0
	v_lshl_add_u64 v[200:201], v[68:69], 0, v[202:203]
	v_permlane16_swap_b32_e32 v196, v198
	v_permlane16_swap_b32_e32 v197, v199
	global_store_dwordx4 v[200:201], v[196:199], off
	s_nop 1
	v_pk_mul_f32 v[52:53], v[58:59], v[64:65] op_sel_hi:[1,0]
	v_pk_mul_f32 v[54:55], v[56:57], v[64:65] op_sel_hi:[1,0]
	v_pk_mul_f32 v[48:49], v[48:49], v[64:65] op_sel_hi:[1,0]
	v_cvt_pk_bf16_f32 v54, v54, v55
	v_cvt_pk_bf16_f32 v55, v52, v53
	v_lshlrev_b32_e32 v52, 1, v66
	v_mov_b32_e32 v53, v161
	v_lshl_add_u64 v[52:53], v[68:69], 0, v[52:53]
	v_mov_b32_e32 v196, v54
	v_mov_b32_e32 v197, v55
	v_pk_mul_f32 v[50:51], v[50:51], v[64:65] op_sel_hi:[1,0]
	v_cvt_pk_bf16_f32 v48, v48, v49
	s_nop 0
	v_cvt_pk_bf16_f32 v49, v50, v51
	v_mov_b32_e32 v198, v48
	v_mov_b32_e32 v199, v49
	v_bfe_u32 v202, v252, 4, 1
	v_mul_u32_u24_e32 v202, 24, v202
	v_mov_b32_e32 v203, 0
	v_lshl_add_u64 v[200:201], v[52:53], 0, v[202:203]
	v_permlane16_swap_b32_e32 v196, v198
	v_permlane16_swap_b32_e32 v197, v199
	global_store_dwordx4 v[200:201], v[196:199], off
	s_nop 1
	v_add_u32_e32 v49, 0x90, v131
	v_mul_hi_i32 v50, v49, s14
	v_lshrrev_b32_e32 v51, 31, v50
	v_ashrrev_i32_e32 v50, 7, v50
	v_add_u32_e32 v51, v50, v51
	v_mad_i32_i24 v49, v51, s23, v49
	ds_read_b32 v48, v138 offset:576
	v_cmp_gt_i32_e64 s[0:1], 16, v49
	s_nop 1
	v_cndmask_b32_e64 v50, -16, v171, s[0:1]
	v_add_u32_e32 v50, v50, v49
	v_lshl_add_u32 v49, v51, 3, s4
	v_ashrrev_i32_e32 v51, 31, v50
	v_mad_i64_i32 v[54:55], s[0:1], v49, s24, v[50:51]
	s_and_saveexec_b64 s[0:1], vcc
	s_xor_b64 s[0:1], exec, s[0:1]
	v_lshlrev_b64 v[50:51], 7, v[54:55]
	v_lshl_add_u64 v[50:51], s[34:35], 0, v[50:51]
	v_mov_b32_e32 v129, v161
	v_lshl_add_u64 v[50:51], v[50:51], 0, v[128:129]
	v_lshl_add_u64 v[52:53], v[50:51], 0, s[40:41]
	s_or_saveexec_b64 s[0:1], s[0:1]
	v_mov_b64_e32 v[50:51], 0x21000
	s_xor_b64 exec, exec, s[0:1]
	s_cbranch_execz .LBB0_397
	v_readlane_b32 s28, v254, 23
	v_readlane_b32 s29, v254, 24
	v_mov_b32_e32 v129, v161
	s_nop 0
	v_mov_b64_e32 v[50:51], s[28:29]
	v_mad_u64_u32 v[50:51], s[28:29], v54, s69, v[50:51]
	v_mov_b32_e32 v52, v51
	v_mad_u64_u32 v[52:53], s[28:29], v55, s69, v[52:53]
	v_mov_b32_e32 v51, v52
	v_lshl_add_u64 v[52:53], v[50:51], 0, v[128:129]
	v_mov_b64_e32 v[50:51], 0x31800
.LBB0_397:
	s_or_b64 exec, exec, s[0:1]
	v_lshl_add_u64 v[52:53], v[52:53], 0, v[160:161]
	s_waitcnt lgkmcnt(0)
	v_pk_mul_f32 v[44:45], v[44:45], v[48:49] op_sel_hi:[1,0]
	v_pk_mul_f32 v[36:37], v[36:37], v[48:49] op_sel_hi:[1,0]
	v_pk_mul_f32 v[46:47], v[46:47], v[48:49] op_sel_hi:[1,0]
	v_cvt_pk_bf16_f32 v44, v44, v45
	v_pk_mul_f32 v[38:39], v[38:39], v[48:49] op_sel_hi:[1,0]
	v_cvt_pk_bf16_f32 v45, v46, v47
	v_mov_b32_e32 v196, v44
	v_mov_b32_e32 v197, v45
	v_cvt_pk_bf16_f32 v36, v36, v37
	v_cvt_pk_bf16_f32 v37, v38, v39
	v_mov_b32_e32 v198, v36
	v_mov_b32_e32 v199, v37
	v_bfe_u32 v202, v252, 4, 1
	v_mul_u32_u24_e32 v202, 24, v202
	v_mov_b32_e32 v203, 0
	v_lshl_add_u64 v[200:201], v[52:53], 0, v[202:203]
	v_permlane16_swap_b32_e32 v196, v198
	v_permlane16_swap_b32_e32 v197, v199
	global_store_dwordx4 v[200:201], v[196:199], off
	s_nop 1
	v_pk_mul_f32 v[36:37], v[42:43], v[48:49] op_sel_hi:[1,0]
	v_pk_mul_f32 v[38:39], v[40:41], v[48:49] op_sel_hi:[1,0]
	v_pk_mul_f32 v[32:33], v[32:33], v[48:49] op_sel_hi:[1,0]
	v_cvt_pk_bf16_f32 v38, v38, v39
	v_cvt_pk_bf16_f32 v39, v36, v37
	v_lshlrev_b32_e32 v36, 1, v50
	v_mov_b32_e32 v37, v161
	v_lshl_add_u64 v[36:37], v[52:53], 0, v[36:37]
	v_mov_b32_e32 v196, v38
	v_mov_b32_e32 v197, v39
	v_pk_mul_f32 v[34:35], v[34:35], v[48:49] op_sel_hi:[1,0]
	v_cvt_pk_bf16_f32 v32, v32, v33
	s_nop 0
	v_cvt_pk_bf16_f32 v33, v34, v35
	v_mov_b32_e32 v198, v32
	v_mov_b32_e32 v199, v33
	v_bfe_u32 v202, v252, 4, 1
	v_mul_u32_u24_e32 v202, 24, v202
	v_mov_b32_e32 v203, 0
	v_lshl_add_u64 v[200:201], v[36:37], 0, v[202:203]
	v_permlane16_swap_b32_e32 v196, v198
	v_permlane16_swap_b32_e32 v197, v199
	global_store_dwordx4 v[200:201], v[196:199], off
	s_nop 1
	v_add_u32_e32 v33, 0xa0, v131
	v_mul_hi_i32 v34, v33, s14
	v_lshrrev_b32_e32 v35, 31, v34
	v_ashrrev_i32_e32 v34, 7, v34
	v_add_u32_e32 v35, v34, v35
	v_mad_i32_i24 v33, v35, s23, v33
	ds_read_b32 v32, v138 offset:640
	v_cmp_gt_i32_e64 s[0:1], 16, v33
	s_nop 1
	v_cndmask_b32_e64 v34, -16, v171, s[0:1]
	v_add_u32_e32 v34, v34, v33
	v_lshl_add_u32 v33, v35, 3, s4
	v_ashrrev_i32_e32 v35, 31, v34
	v_mad_i64_i32 v[38:39], s[0:1], v33, s24, v[34:35]
	s_and_saveexec_b64 s[0:1], vcc
	s_xor_b64 s[0:1], exec, s[0:1]
	v_lshlrev_b64 v[34:35], 7, v[38:39]
	v_lshl_add_u64 v[34:35], s[34:35], 0, v[34:35]
	v_mov_b32_e32 v129, v161
	v_lshl_add_u64 v[34:35], v[34:35], 0, v[128:129]
	v_lshl_add_u64 v[36:37], v[34:35], 0, s[40:41]
	s_or_saveexec_b64 s[0:1], s[0:1]
	v_mov_b64_e32 v[34:35], 0x21000
	s_xor_b64 exec, exec, s[0:1]
	s_cbranch_execz .LBB0_401
	v_readlane_b32 s28, v254, 23
	v_readlane_b32 s29, v254, 24
	v_mov_b32_e32 v129, v161
	s_nop 0
	v_mov_b64_e32 v[34:35], s[28:29]
	v_mad_u64_u32 v[34:35], s[28:29], v38, s69, v[34:35]
	v_mov_b32_e32 v36, v35
	v_mad_u64_u32 v[36:37], s[28:29], v39, s69, v[36:37]
	v_mov_b32_e32 v35, v36
	v_lshl_add_u64 v[36:37], v[34:35], 0, v[128:129]
	v_mov_b64_e32 v[34:35], 0x31800
; __device__ __forceinline__ u32x2 pack4(float a, float b, float c, float d) { return u32x2{cvtpk(a, b), cvtpk(c, d)}; }
; __device__ __forceinline__ u32x2 pack4(const f32x4& v) { return u32x2{cvtpk(v[0], v[1]), cvtpk(v[2], v[3])}; }
; #define SBAR() __builtin_amdgcn_sched_barrier(0)
; __global__ void __launch_bounds__(512) fwd_megakernel(Params p) {
;     ...
;           #pragma unroll
;           for (int ai = 0; ai < 2; ++ai)
;             #pragma unroll
;             for (int m = 0; m < 4; ++m) { SBAR();
;               int lrow = ai * 128 + wr * 64 + m * 16 + fr, row = brow + lrow; float rs = xl[lrow];
;               int b = row / LTOK, pos = row - b * LTOK; int key = pos < NMETA ? SEQ + pos : pos - NMETA;
;               long kr = (long)(b * NH + pk * 2) * KPAD + key;
;               bf16* d = (wc < 2) ? p_Kb + kr * DQK + wc * 32 + fq * 4 : p_Vb + kr * DV + (wc - 2) * 32 + fq * 4;
;               const long hstride = (wc < 2) ? (long)KPAD * DQK : (long)KPAD * DV;
;               #pragma unroll
;               for (int bj = 0; bj < 2; ++bj) {
;                 *reinterpret_cast<u32x2*>(d + bj * hstride) = pack4(acc[ai][bj][m][0] * rs);
;                 *reinterpret_cast<u32x2*>(d + bj * hstride + 16) = pack4(acc[ai][bj][m][1] * rs);
;               }
.LBB0_401:
	s_or_b64 exec, exec, s[0:1]
	v_lshl_add_u64 v[36:37], v[36:37], 0, v[160:161]
	s_waitcnt lgkmcnt(0)
	v_pk_mul_f32 v[28:29], v[28:29], v[32:33] op_sel_hi:[1,0]
	v_pk_mul_f32 v[20:21], v[20:21], v[32:33] op_sel_hi:[1,0]
	v_pk_mul_f32 v[30:31], v[30:31], v[32:33] op_sel_hi:[1,0]
	v_cvt_pk_bf16_f32 v28, v28, v29
	v_pk_mul_f32 v[22:23], v[22:23], v[32:33] op_sel_hi:[1,0]
	v_cvt_pk_bf16_f32 v29, v30, v31
	v_mov_b32_e32 v196, v28
	v_mov_b32_e32 v197, v29
	v_cvt_pk_bf16_f32 v20, v20, v21
	v_cvt_pk_bf16_f32 v21, v22, v23
	v_mov_b32_e32 v198, v20
	v_mov_b32_e32 v199, v21
	v_bfe_u32 v202, v252, 4, 1
	v_mul_u32_u24_e32 v202, 24, v202
	v_mov_b32_e32 v203, 0
	v_lshl_add_u64 v[200:201], v[36:37], 0, v[202:203]
	v_permlane16_swap_b32_e32 v196, v198
	v_permlane16_swap_b32_e32 v197, v199
	global_store_dwordx4 v[200:201], v[196:199], off
	s_nop 1
	v_pk_mul_f32 v[20:21], v[26:27], v[32:33] op_sel_hi:[1,0]
	v_pk_mul_f32 v[22:23], v[24:25], v[32:33] op_sel_hi:[1,0]
	v_pk_mul_f32 v[16:17], v[16:17], v[32:33] op_sel_hi:[1,0]
	v_cvt_pk_bf16_f32 v22, v22, v23
	v_cvt_pk_bf16_f32 v23, v20, v21
	v_lshlrev_b32_e32 v20, 1, v34
	v_mov_b32_e32 v21, v161
	v_lshl_add_u64 v[20:21], v[36:37], 0, v[20:21]
	v_mov_b32_e32 v196, v22
	v_mov_b32_e32 v197, v23
	v_pk_mul_f32 v[18:19], v[18:19], v[32:33] op_sel_hi:[1,0]
	v_cvt_pk_bf16_f32 v16, v16, v17
	s_nop 0
	v_cvt_pk_bf16_f32 v17, v18, v19
	v_mov_b32_e32 v198, v16
	v_mov_b32_e32 v199, v17
	v_bfe_u32 v202, v252, 4, 1
	v_mul_u32_u24_e32 v202, 24, v202
	v_mov_b32_e32 v203, 0
	v_lshl_add_u64 v[200:201], v[20:21], 0, v[202:203]
	v_permlane16_swap_b32_e32 v196, v198
	v_permlane16_swap_b32_e32 v197, v199
	global_store_dwordx4 v[200:201], v[196:199], off
	s_nop 1
	v_add_u32_e32 v17, 0xb0, v131
	v_mul_hi_i32 v18, v17, s14
	v_lshrrev_b32_e32 v19, 31, v18
	v_ashrrev_i32_e32 v18, 7, v18
	v_add_u32_e32 v19, v18, v19
	v_mad_i32_i24 v17, v19, s23, v17
	ds_read_b32 v16, v138 offset:704
	v_cmp_gt_i32_e64 s[0:1], 16, v17
	s_nop 1
	v_cndmask_b32_e64 v18, -16, v171, s[0:1]
	v_add_u32_e32 v18, v18, v17
	v_lshl_add_u32 v17, v19, 3, s4
	v_ashrrev_i32_e32 v19, 31, v18
	v_mad_i64_i32 v[22:23], s[0:1], v17, s24, v[18:19]
	s_and_saveexec_b64 s[0:1], vcc
	s_xor_b64 s[0:1], exec, s[0:1]
	v_lshlrev_b64 v[18:19], 7, v[22:23]
	v_lshl_add_u64 v[18:19], s[34:35], 0, v[18:19]
	v_mov_b32_e32 v129, v161
	v_lshl_add_u64 v[18:19], v[18:19], 0, v[128:129]
	v_lshl_add_u64 v[20:21], v[18:19], 0, s[40:41]
	s_or_saveexec_b64 s[0:1], s[0:1]
	v_mov_b64_e32 v[18:19], 0x21000
	s_xor_b64 exec, exec, s[0:1]
	s_cbranch_execz .LBB0_405
	v_readlane_b32 s4, v254, 23
	v_readlane_b32 s5, v254, 24
	v_mov_b32_e32 v129, v161
	s_nop 0
	v_mov_b64_e32 v[18:19], s[4:5]
	v_mad_u64_u32 v[18:19], s[4:5], v22, s69, v[18:19]
	v_mov_b32_e32 v20, v19
	v_mad_u64_u32 v[20:21], s[4:5], v23, s69, v[20:21]
	v_mov_b32_e32 v19, v20
	v_lshl_add_u64 v[20:21], v[18:19], 0, v[128:129]
	v_mov_b64_e32 v[18:19], 0x31800
.LBB0_405:
	s_or_b64 exec, exec, s[0:1]
	v_lshl_add_u64 v[20:21], v[20:21], 0, v[160:161]
	s_waitcnt lgkmcnt(0)
	v_pk_mul_f32 v[12:13], v[12:13], v[16:17] op_sel_hi:[1,0]
	v_pk_mul_f32 v[4:5], v[4:5], v[16:17] op_sel_hi:[1,0]
	v_pk_mul_f32 v[14:15], v[14:15], v[16:17] op_sel_hi:[1,0]
	v_cvt_pk_bf16_f32 v12, v12, v13
	v_pk_mul_f32 v[6:7], v[6:7], v[16:17] op_sel_hi:[1,0]
	v_cvt_pk_bf16_f32 v13, v14, v15
	v_mov_b32_e32 v196, v12
	v_mov_b32_e32 v197, v13
	v_cvt_pk_bf16_f32 v4, v4, v5
	v_cvt_pk_bf16_f32 v5, v6, v7
	v_lshlrev_b32_e32 v160, 1, v18
	v_mov_b32_e32 v198, v4
	v_mov_b32_e32 v199, v5
	v_bfe_u32 v202, v252, 4, 1
	v_mul_u32_u24_e32 v202, 24, v202
	v_mov_b32_e32 v203, 0
	v_lshl_add_u64 v[200:201], v[20:21], 0, v[202:203]
	v_permlane16_swap_b32_e32 v196, v198
	v_permlane16_swap_b32_e32 v197, v199
	global_store_dwordx4 v[200:201], v[196:199], off
	s_nop 1
	v_pk_mul_f32 v[4:5], v[10:11], v[16:17] op_sel_hi:[1,0]
	v_pk_mul_f32 v[6:7], v[8:9], v[16:17] op_sel_hi:[1,0]
	v_lshl_add_u64 v[10:11], v[20:21], 0, v[160:161]
	v_pk_mul_f32 v[0:1], v[0:1], v[16:17] op_sel_hi:[1,0]
	s_mov_b64 s[0:1], 0
	v_cvt_pk_bf16_f32 v6, v6, v7
	v_cvt_pk_bf16_f32 v7, v4, v5
	global_store_dwordx2 v[10:11], v[6:7], off
	v_pk_mul_f32 v[2:3], v[2:3], v[16:17] op_sel_hi:[1,0]
	v_cvt_pk_bf16_f32 v0, v0, v1
	s_nop 0
	v_cvt_pk_bf16_f32 v1, v2, v3

; #define p_rope W_(float2, OFF_ROPE)
; __device__ __forceinline__ u32x2 pack4(float a, float b, float c, float d) { return u32x2{cvtpk(a, b), cvtpk(c, d)}; }
; __device__ __forceinline__ u32x2 pack4(const f32x4& v) { return u32x2{cvtpk(v[0], v[1]), cvtpk(v[2], v[3])}; }
; #define SBAR() __builtin_amdgcn_sched_barrier(0)
; __global__ void __launch_bounds__(512) fwd_megakernel(Params p) {
;     ...
;           for (int ai = 0; ai < 2; ++ai) { SBAR();
;             f32x4 csa[4], csb[4];
;             if (rope0 || rope1) {
;               #pragma unroll
;               for (int m = 0; m < 4; ++m) {
;                 int pos = (brow + ai * 128 + wr * 64 + m * 16 + fr) % LTOK;
;                 csa[m] = *reinterpret_cast<const f32x4*>(p_rope + pos * 16 + fq * 4); csb[m] = *reinterpret_cast<const f32x4*>(p_rope + pos * 16 + fq * 4 + 2);
;               }
;             } else {
;               #pragma unroll
;               for (int m = 0; m < 4; ++m) { csa[m] = f32x4{1.f, 0.f, 1.f, 0.f}; csb[m] = csa[m]; }
;             }
;             SBAR();
;             #pragma unroll
;             for (int m = 0; m < 4; ++m) {
;               int lrow = ai * 128 + wr * 64 + m * 16 + fr, row = brow + lrow; float rs = xl[lrow];
;               const float cs_c[4] = {csa[m][0], csa[m][2], csb[m][0], csb[m][2]}, cs_s[4] = {csa[m][1], csa[m][3], csb[m][1], csb[m][3]};
;               #pragma unroll
;               for (int bj = 0; bj < 2; ++bj) {
;                 const int c0 = pn * 256 + bj * 128 + wc * 32; const bool isrope = bj ? rope1 : rope0;
;                 f32x4 x1 = acc[ai][bj][m][0] * rs, x2 = acc[ai][bj][m][1] * rs;
;                 if (isrope) {
;                   #pragma unroll
;                   for (int j = 0; j < 4; ++j) { float a1 = x1[j], a2 = x2[j]; x1[j] = a1 * cs_c[j] - a2 * cs_s[j]; x2[j] = a2 * cs_c[j] + a1 * cs_s[j]; }
;                 }
;                 bf16* qd = p_q + (long)row * 768 + c0 + fq * 4;
;                 *reinterpret_cast<u32x2*>(qd) = pack4(x1); *reinterpret_cast<u32x2*>(qd + 16) = pack4(x2);
;               }
.LBB0_434:
	s_or_b64 exec, exec, s[2:3]
	v_mov_b64_e32 v[144:145], s[34:35]
	v_mad_i64_i32 v[144:145], s[2:3], v172, s15, v[144:145]
	v_ashrrev_i32_e32 v163, 31, v162
	v_lshl_add_u64 v[144:145], v[162:163], 1, v[144:145]
	v_lshlrev_b32_e32 v160, 1, v160
	v_lshl_add_u64 v[144:145], v[144:145], 0, v[160:161]
	v_cvt_pk_bf16_f32 v148, v148, v149
	v_cvt_pk_bf16_f32 v149, v150, v151
	v_mov_b32_e32 v167, v166
	v_mov_b32_e32 v196, v148
	v_mov_b32_e32 v197, v149
	v_cvt_pk_bf16_f32 v148, v168, v169
	v_cvt_pk_bf16_f32 v149, v146, v147
	v_mov_b32_e32 v146, v166
	v_mov_b32_e32 v147, v166
	v_pk_mul_f32 v[134:135], v[134:135], v[146:147]
	v_pk_mul_f32 v[132:133], v[132:133], v[166:167]
	v_pk_mul_f32 v[130:131], v[130:131], v[146:147]
	v_pk_mul_f32 v[128:129], v[128:129], v[166:167]
	v_mov_b32_e32 v198, v148
	v_mov_b32_e32 v199, v149
	v_bfe_u32 v202, v252, 4, 1
	v_mul_u32_u24_e32 v202, 24, v202
	v_mov_b32_e32 v203, 0
	v_lshl_add_u64 v[200:201], v[144:145], 0, v[202:203]
	v_permlane16_swap_b32_e32 v196, v198
	v_permlane16_swap_b32_e32 v197, v199
	global_store_dwordx4 v[200:201], v[196:199], off
	s_nop 1
	s_and_saveexec_b64 s[2:3], s[4:5]
	s_cbranch_execz .LBB0_436
	s_waitcnt vmcnt(0)
	v_mov_b32_e32 v146, v152
	v_mul_f32_e32 v150, v156, v134
	v_mul_f32_e32 v152, v157, v130
	v_mul_f32_e32 v156, v156, v130
	v_mov_b32_e32 v130, v135
	v_mov_b32_e32 v147, v154
	v_mov_b32_e32 v154, v153
	v_mul_f32_e32 v166, v157, v134
	v_pk_mul_f32 v[168:169], v[158:159], v[130:131]
	v_mov_b32_e32 v134, v131
	v_pk_mul_f32 v[148:149], v[154:155], v[128:129]
	v_mov_b32_e32 v151, v168
	v_mov_b32_e32 v153, v169
	v_pk_mul_f32 v[130:131], v[158:159], v[134:135]
	v_pk_mul_f32 v[128:129], v[146:147], v[128:129]
	v_pk_fma_f32 v[146:147], v[146:147], v[132:133], v[148:149] neg_lo:[0,0,1] neg_hi:[0,0,1]
	v_pk_add_f32 v[148:149], v[150:151], v[152:153] neg_lo:[0,1] neg_hi:[0,1]
	v_mov_b32_e32 v167, v131
	v_mov_b32_e32 v157, v130
	v_pk_fma_f32 v[128:129], v[154:155], v[132:133], v[128:129]
	v_pk_add_f32 v[130:131], v[166:167], v[156:157]
	v_mov_b32_e32 v132, v146
	v_mov_b32_e32 v133, v147
	v_mov_b32_e32 v134, v148
	v_mov_b32_e32 v135, v149
.LBB0_436:
	s_or_b64 exec, exec, s[2:3]
	v_cvt_pk_bf16_f32 v132, v132, v133
	v_cvt_pk_bf16_f32 v133, v134, v135
	v_mov_b32_e32 v196, v132
	v_mov_b32_e32 v197, v133
	v_or_b32_e32 v132, 16, v174
	v_cvt_pk_bf16_f32 v134, v128, v129
	v_lshl_add_u32 v128, v132, 2, 0
	v_add_u32_e32 v128, 0x20000, v128
	v_cvt_pk_bf16_f32 v135, v130, v131
	ds_read_b32 v128, v128
	v_mov_b32_e32 v198, v134
	v_mov_b32_e32 v199, v135
	v_bfe_u32 v202, v252, 4, 1
	v_mul_u32_u24_e32 v202, 24, v202
	v_mov_b32_e32 v203, 0
	v_lshl_add_u64 v[200:201], v[144:145], 0, v[202:203]
	v_permlane16_swap_b32_e32 v196, v198
	v_permlane16_swap_b32_e32 v197, v199
	global_store_dwordx4 v[200:201], v[196:199], off offset:256
	s_nop 1
	s_waitcnt lgkmcnt(0)
	v_pk_mul_f32 v[126:127], v[126:127], v[128:129] op_sel_hi:[1,0]
	v_pk_mul_f32 v[124:125], v[124:125], v[128:129] op_sel_hi:[1,0]
	v_pk_mul_f32 v[122:123], v[122:123], v[128:129] op_sel_hi:[1,0]
	v_pk_mul_f32 v[130:131], v[120:121], v[128:129] op_sel_hi:[1,0]
	s_and_saveexec_b64 s[2:3], s[6:7]
	s_cbranch_execz .LBB0_438
	s_waitcnt vmcnt(0)
	v_mul_f32_e32 v148, v141, v122
	v_mul_f32_e32 v150, v140, v122
	v_mov_b32_e32 v122, v127
	v_mov_b32_e32 v134, v137
	v_mov_b32_e32 v135, v139
	v_mul_f32_e32 v146, v140, v126
	v_mul_f32_e32 v152, v141, v126
	v_pk_mul_f32 v[154:155], v[142:143], v[122:123]
	v_mov_b32_e32 v126, v123
	v_mov_b32_e32 v120, v136
	v_mov_b32_e32 v121, v138
	v_pk_mul_f32 v[144:145], v[134:135], v[130:131]
	v_mov_b32_e32 v147, v154
	v_mov_b32_e32 v149, v155
	v_pk_mul_f32 v[122:123], v[142:143], v[126:127]
	v_pk_mul_f32 v[130:131], v[120:121], v[130:131]
	v_pk_fma_f32 v[120:121], v[120:121], v[124:125], v[144:145] neg_lo:[0,0,1] neg_hi:[0,0,1]
	v_pk_add_f32 v[144:145], v[146:147], v[148:149] neg_lo:[0,1] neg_hi:[0,1]
	v_mov_b32_e32 v153, v123
	v_mov_b32_e32 v151, v122
	v_pk_fma_f32 v[130:131], v[134:135], v[124:125], v[130:131]
	v_pk_add_f32 v[122:123], v[152:153], v[150:151]
	v_mov_b32_e32 v124, v120
	v_mov_b32_e32 v125, v121
	v_mov_b32_e32 v126, v144
	v_mov_b32_e32 v127, v145
.LBB0_438:
	s_or_b64 exec, exec, s[2:3]
	v_add_u32_e32 v132, s96, v132
	v_mov_b64_e32 v[120:121], s[34:35]
	v_mad_i64_i32 v[120:121], s[2:3], v132, s15, v[120:121]
	v_lshl_add_u64 v[120:121], v[162:163], 1, v[120:121]
	v_lshl_add_u64 v[120:121], v[120:121], 0, v[160:161]
	v_cvt_pk_bf16_f32 v124, v124, v125
	v_cvt_pk_bf16_f32 v125, v126, v127
	v_mov_b32_e32 v129, v128
	v_mov_b32_e32 v196, v124
	v_mov_b32_e32 v197, v125
	v_cvt_pk_bf16_f32 v124, v130, v131
	v_cvt_pk_bf16_f32 v125, v122, v123
	v_mov_b32_e32 v122, v128
	v_mov_b32_e32 v123, v128
	v_pk_mul_f32 v[110:111], v[110:111], v[122:123]
	v_pk_mul_f32 v[108:109], v[108:109], v[128:129]
	v_pk_mul_f32 v[106:107], v[106:107], v[122:123]
	v_pk_mul_f32 v[104:105], v[104:105], v[128:129]
	v_mov_b32_e32 v198, v124
	v_mov_b32_e32 v199, v125
	v_bfe_u32 v202, v252, 4, 1
	v_mul_u32_u24_e32 v202, 24, v202
	v_mov_b32_e32 v203, 0
	v_lshl_add_u64 v[200:201], v[120:121], 0, v[202:203]
	v_permlane16_swap_b32_e32 v196, v198
	v_permlane16_swap_b32_e32 v197, v199
	global_store_dwordx4 v[200:201], v[196:199], off
	s_nop 1
	s_and_saveexec_b64 s[2:3], s[4:5]
	s_cbranch_execz .LBB0_440
	s_waitcnt vmcnt(0)
	v_mul_f32_e32 v128, v141, v106
	v_mul_f32_e32 v130, v140, v106
	v_mov_b32_e32 v106, v111
	v_mov_b32_e32 v123, v138
	v_mov_b32_e32 v138, v137
	v_mul_f32_e32 v126, v140, v110
	v_mul_f32_e32 v132, v141, v110
	v_pk_mul_f32 v[134:135], v[142:143], v[106:107]
	v_mov_b32_e32 v110, v107
	v_mov_b32_e32 v122, v136
	v_pk_mul_f32 v[124:125], v[138:139], v[104:105]
	v_mov_b32_e32 v127, v134
	v_mov_b32_e32 v129, v135
	v_pk_mul_f32 v[106:107], v[142:143], v[110:111]
	v_pk_mul_f32 v[104:105], v[122:123], v[104:105]
	v_pk_fma_f32 v[122:123], v[122:123], v[108:109], v[124:125] neg_lo:[0,0,1] neg_hi:[0,0,1]
	v_pk_add_f32 v[124:125], v[126:127], v[128:129] neg_lo:[0,1] neg_hi:[0,1]
	v_mov_b32_e32 v133, v107
	v_mov_b32_e32 v131, v106
	v_pk_fma_f32 v[104:105], v[138:139], v[108:109], v[104:105]
	v_pk_add_f32 v[106:107], v[132:133], v[130:131]
	v_mov_b32_e32 v108, v122
	v_mov_b32_e32 v109, v123
	v_mov_b32_e32 v110, v124
	v_mov_b32_e32 v111, v125
; #define p_rope W_(float2, OFF_ROPE)
; __device__ __forceinline__ u32x2 pack4(float a, float b, float c, float d) { return u32x2{cvtpk(a, b), cvtpk(c, d)}; }
; __device__ __forceinline__ u32x2 pack4(const f32x4& v) { return u32x2{cvtpk(v[0], v[1]), cvtpk(v[2], v[3])}; }
; #define SBAR() __builtin_amdgcn_sched_barrier(0)
; __global__ void __launch_bounds__(512) fwd_megakernel(Params p) {
;     ...
;           for (int ai = 0; ai < 2; ++ai) { SBAR();
;             f32x4 csa[4], csb[4];
;             if (rope0 || rope1) {
;               #pragma unroll
;               for (int m = 0; m < 4; ++m) {
;                 int pos = (brow + ai * 128 + wr * 64 + m * 16 + fr) % LTOK;
;                 csa[m] = *reinterpret_cast<const f32x4*>(p_rope + pos * 16 + fq * 4); csb[m] = *reinterpret_cast<const f32x4*>(p_rope + pos * 16 + fq * 4 + 2);
;               }
;             } else {
;               #pragma unroll
;               for (int m = 0; m < 4; ++m) { csa[m] = f32x4{1.f, 0.f, 1.f, 0.f}; csb[m] = csa[m]; }
;             }
;             SBAR();
;             #pragma unroll
;             for (int m = 0; m < 4; ++m) {
;               int lrow = ai * 128 + wr * 64 + m * 16 + fr, row = brow + lrow; float rs = xl[lrow];
;               const float cs_c[4] = {csa[m][0], csa[m][2], csb[m][0], csb[m][2]}, cs_s[4] = {csa[m][1], csa[m][3], csb[m][1], csb[m][3]};
;               #pragma unroll
;               for (int bj = 0; bj < 2; ++bj) {
;                 const int c0 = pn * 256 + bj * 128 + wc * 32; const bool isrope = bj ? rope1 : rope0;
;                 f32x4 x1 = acc[ai][bj][m][0] * rs, x2 = acc[ai][bj][m][1] * rs;
;                 if (isrope) {
;                   #pragma unroll
;                   for (int j = 0; j < 4; ++j) { float a1 = x1[j], a2 = x2[j]; x1[j] = a1 * cs_c[j] - a2 * cs_s[j]; x2[j] = a2 * cs_c[j] + a1 * cs_s[j]; }
;                 }
;                 bf16* qd = p_q + (long)row * 768 + c0 + fq * 4;
;                 *reinterpret_cast<u32x2*>(qd) = pack4(x1); *reinterpret_cast<u32x2*>(qd + 16) = pack4(x2);
;               }
.LBB0_440:
	s_or_b64 exec, exec, s[2:3]
	v_cvt_pk_bf16_f32 v108, v108, v109
	v_cvt_pk_bf16_f32 v109, v110, v111
	v_mov_b32_e32 v196, v108
	v_mov_b32_e32 v197, v109
	v_or_b32_e32 v108, 32, v174
	v_cvt_pk_bf16_f32 v110, v104, v105
	v_lshl_add_u32 v104, v108, 2, 0
	v_add_u32_e32 v104, 0x20000, v104
	v_cvt_pk_bf16_f32 v111, v106, v107
	ds_read_b32 v104, v104
	v_mov_b32_e32 v198, v110
	v_mov_b32_e32 v199, v111
	v_bfe_u32 v202, v252, 4, 1
	v_mul_u32_u24_e32 v202, 24, v202
	v_mov_b32_e32 v203, 0
	v_lshl_add_u64 v[200:201], v[120:121], 0, v[202:203]
	v_permlane16_swap_b32_e32 v196, v198
	v_permlane16_swap_b32_e32 v197, v199
	global_store_dwordx4 v[200:201], v[196:199], off offset:256
	s_nop 1
	s_waitcnt lgkmcnt(0)
	v_pk_mul_f32 v[98:99], v[98:99], v[104:105] op_sel_hi:[1,0]
	v_pk_mul_f32 v[96:97], v[96:97], v[104:105] op_sel_hi:[1,0]
	v_pk_mul_f32 v[94:95], v[94:95], v[104:105] op_sel_hi:[1,0]
	v_pk_mul_f32 v[106:107], v[92:93], v[104:105] op_sel_hi:[1,0]
	s_and_saveexec_b64 s[2:3], s[6:7]
	s_cbranch_execz .LBB0_442
	s_waitcnt vmcnt(0)
	v_mul_f32_e32 v124, v117, v94
	v_mul_f32_e32 v126, v116, v94
	v_mov_b32_e32 v94, v99
	v_mov_b32_e32 v110, v113
	v_mov_b32_e32 v111, v115
	v_mul_f32_e32 v122, v116, v98
	v_mul_f32_e32 v128, v117, v98
	v_pk_mul_f32 v[130:131], v[118:119], v[94:95]
	v_mov_b32_e32 v98, v95
	v_mov_b32_e32 v92, v112
	v_mov_b32_e32 v93, v114
	v_pk_mul_f32 v[120:121], v[110:111], v[106:107]
	v_mov_b32_e32 v123, v130
	v_mov_b32_e32 v125, v131
	v_pk_mul_f32 v[94:95], v[118:119], v[98:99]
	v_pk_mul_f32 v[106:107], v[92:93], v[106:107]
	v_pk_fma_f32 v[92:93], v[92:93], v[96:97], v[120:121] neg_lo:[0,0,1] neg_hi:[0,0,1]
	v_pk_add_f32 v[120:121], v[122:123], v[124:125] neg_lo:[0,1] neg_hi:[0,1]
	v_mov_b32_e32 v129, v95
	v_mov_b32_e32 v127, v94
	v_pk_fma_f32 v[106:107], v[110:111], v[96:97], v[106:107]
	v_pk_add_f32 v[94:95], v[128:129], v[126:127]
	v_mov_b32_e32 v96, v92
	v_mov_b32_e32 v97, v93
	v_mov_b32_e32 v98, v120
	v_mov_b32_e32 v99, v121
.LBB0_442:
	s_or_b64 exec, exec, s[2:3]
	v_add_u32_e32 v108, s96, v108
	v_mov_b64_e32 v[92:93], s[34:35]
	v_mad_i64_i32 v[92:93], s[2:3], v108, s15, v[92:93]
	v_lshl_add_u64 v[92:93], v[162:163], 1, v[92:93]
	v_lshl_add_u64 v[92:93], v[92:93], 0, v[160:161]
	v_cvt_pk_bf16_f32 v96, v96, v97
	v_cvt_pk_bf16_f32 v97, v98, v99
	v_mov_b32_e32 v105, v104
	v_mov_b32_e32 v196, v96
	v_mov_b32_e32 v197, v97
	v_cvt_pk_bf16_f32 v96, v106, v107
	v_cvt_pk_bf16_f32 v97, v94, v95
	v_mov_b32_e32 v94, v104
	v_mov_b32_e32 v95, v104
	v_pk_mul_f32 v[86:87], v[86:87], v[94:95]
	v_pk_mul_f32 v[84:85], v[84:85], v[104:105]
	v_pk_mul_f32 v[82:83], v[82:83], v[94:95]
	v_pk_mul_f32 v[80:81], v[80:81], v[104:105]
	v_mov_b32_e32 v198, v96
	v_mov_b32_e32 v199, v97
	v_bfe_u32 v202, v252, 4, 1
	v_mul_u32_u24_e32 v202, 24, v202
	v_mov_b32_e32 v203, 0
	v_lshl_add_u64 v[200:201], v[92:93], 0, v[202:203]
	v_permlane16_swap_b32_e32 v196, v198
	v_permlane16_swap_b32_e32 v197, v199
	global_store_dwordx4 v[200:201], v[196:199], off
	s_nop 1
	s_and_saveexec_b64 s[2:3], s[4:5]
	s_cbranch_execz .LBB0_444
	s_waitcnt vmcnt(0)
	v_mul_f32_e32 v104, v117, v82
	v_mul_f32_e32 v106, v116, v82
	v_mov_b32_e32 v82, v87
	v_mov_b32_e32 v95, v114
	v_mov_b32_e32 v114, v113
	v_mul_f32_e32 v98, v116, v86
	v_mul_f32_e32 v108, v117, v86
	v_pk_mul_f32 v[110:111], v[118:119], v[82:83]
	v_mov_b32_e32 v86, v83
	v_mov_b32_e32 v94, v112
	v_pk_mul_f32 v[96:97], v[114:115], v[80:81]
	v_mov_b32_e32 v99, v110
	v_mov_b32_e32 v105, v111
	v_pk_mul_f32 v[82:83], v[118:119], v[86:87]
	v_pk_mul_f32 v[80:81], v[94:95], v[80:81]
	v_pk_fma_f32 v[94:95], v[94:95], v[84:85], v[96:97] neg_lo:[0,0,1] neg_hi:[0,0,1]
	v_pk_add_f32 v[96:97], v[98:99], v[104:105] neg_lo:[0,1] neg_hi:[0,1]
	v_mov_b32_e32 v109, v83
	v_mov_b32_e32 v107, v82
	v_pk_fma_f32 v[80:81], v[114:115], v[84:85], v[80:81]
	v_pk_add_f32 v[82:83], v[108:109], v[106:107]
	v_mov_b32_e32 v84, v94
	v_mov_b32_e32 v85, v95
	v_mov_b32_e32 v86, v96
	v_mov_b32_e32 v87, v97
.LBB0_444:
	s_or_b64 exec, exec, s[2:3]
	v_cvt_pk_bf16_f32 v84, v84, v85
	v_cvt_pk_bf16_f32 v85, v86, v87
	v_mov_b32_e32 v196, v84
	v_mov_b32_e32 v197, v85
	v_or_b32_e32 v84, 48, v174
	v_cvt_pk_bf16_f32 v86, v80, v81
	v_lshl_add_u32 v80, v84, 2, 0
	v_add_u32_e32 v80, 0x20000, v80
	v_cvt_pk_bf16_f32 v87, v82, v83
	ds_read_b32 v80, v80
	v_mov_b32_e32 v198, v86
	v_mov_b32_e32 v199, v87
	v_bfe_u32 v202, v252, 4, 1
	v_mul_u32_u24_e32 v202, 24, v202
	v_mov_b32_e32 v203, 0
	v_lshl_add_u64 v[200:201], v[92:93], 0, v[202:203]
	v_permlane16_swap_b32_e32 v196, v198
	v_permlane16_swap_b32_e32 v197, v199
	global_store_dwordx4 v[200:201], v[196:199], off offset:256
	s_nop 1
	s_waitcnt lgkmcnt(0)
	v_pk_mul_f32 v[78:79], v[78:79], v[80:81] op_sel_hi:[1,0]
	v_pk_mul_f32 v[76:77], v[76:77], v[80:81] op_sel_hi:[1,0]
	v_pk_mul_f32 v[74:75], v[74:75], v[80:81] op_sel_hi:[1,0]
	v_pk_mul_f32 v[82:83], v[72:73], v[80:81] op_sel_hi:[1,0]
	s_and_saveexec_b64 s[2:3], s[6:7]
	s_cbranch_execz .LBB0_446
	s_waitcnt vmcnt(0)
	v_mul_f32_e32 v96, v101, v74
	v_mul_f32_e32 v98, v100, v74
	v_mov_b32_e32 v74, v79
	v_mov_b32_e32 v86, v89
	v_mov_b32_e32 v87, v91
	v_mul_f32_e32 v94, v100, v78
	v_mul_f32_e32 v104, v101, v78
	v_pk_mul_f32 v[106:107], v[102:103], v[74:75]
	v_mov_b32_e32 v78, v75
	v_mov_b32_e32 v72, v88
	v_mov_b32_e32 v73, v90
	v_pk_mul_f32 v[92:93], v[86:87], v[82:83]
	v_mov_b32_e32 v95, v106
	v_mov_b32_e32 v97, v107
	v_pk_mul_f32 v[74:75], v[102:103], v[78:79]
	v_pk_mul_f32 v[82:83], v[72:73], v[82:83]
	v_pk_fma_f32 v[72:73], v[72:73], v[76:77], v[92:93] neg_lo:[0,0,1] neg_hi:[0,0,1]
	v_pk_add_f32 v[92:93], v[94:95], v[96:97] neg_lo:[0,1] neg_hi:[0,1]
	v_mov_b32_e32 v105, v75
	v_mov_b32_e32 v99, v74
	v_pk_fma_f32 v[82:83], v[86:87], v[76:77], v[82:83]
	v_pk_add_f32 v[74:75], v[104:105], v[98:99]
	v_mov_b32_e32 v76, v72
	v_mov_b32_e32 v77, v73
	v_mov_b32_e32 v78, v92
	v_mov_b32_e32 v79, v93
; #define p_rope W_(float2, OFF_ROPE)
; __device__ __forceinline__ u32x2 pack4(float a, float b, float c, float d) { return u32x2{cvtpk(a, b), cvtpk(c, d)}; }
; __device__ __forceinline__ u32x2 pack4(const f32x4& v) { return u32x2{cvtpk(v[0], v[1]), cvtpk(v[2], v[3])}; }
; #define SBAR() __builtin_amdgcn_sched_barrier(0)
; __global__ void __launch_bounds__(512) fwd_megakernel(Params p) {
;     ...
;           for (int ai = 0; ai < 2; ++ai) { SBAR();
;             f32x4 csa[4], csb[4];
;             if (rope0 || rope1) {
;               #pragma unroll
;               for (int m = 0; m < 4; ++m) {
;                 int pos = (brow + ai * 128 + wr * 64 + m * 16 + fr) % LTOK;
;                 csa[m] = *reinterpret_cast<const f32x4*>(p_rope + pos * 16 + fq * 4); csb[m] = *reinterpret_cast<const f32x4*>(p_rope + pos * 16 + fq * 4 + 2);
;               }
;             } else {
;               #pragma unroll
;               for (int m = 0; m < 4; ++m) { csa[m] = f32x4{1.f, 0.f, 1.f, 0.f}; csb[m] = csa[m]; }
;             }
;             SBAR();
;             #pragma unroll
;             for (int m = 0; m < 4; ++m) {
;               int lrow = ai * 128 + wr * 64 + m * 16 + fr, row = brow + lrow; float rs = xl[lrow];
;               const float cs_c[4] = {csa[m][0], csa[m][2], csb[m][0], csb[m][2]}, cs_s[4] = {csa[m][1], csa[m][3], csb[m][1], csb[m][3]};
;               #pragma unroll
;               for (int bj = 0; bj < 2; ++bj) {
;                 const int c0 = pn * 256 + bj * 128 + wc * 32; const bool isrope = bj ? rope1 : rope0;
;                 f32x4 x1 = acc[ai][bj][m][0] * rs, x2 = acc[ai][bj][m][1] * rs;
;                 if (isrope) {
;                   #pragma unroll
;                   for (int j = 0; j < 4; ++j) { float a1 = x1[j], a2 = x2[j]; x1[j] = a1 * cs_c[j] - a2 * cs_s[j]; x2[j] = a2 * cs_c[j] + a1 * cs_s[j]; }
;                 }
;                 bf16* qd = p_q + (long)row * 768 + c0 + fq * 4;
;                 *reinterpret_cast<u32x2*>(qd) = pack4(x1); *reinterpret_cast<u32x2*>(qd + 16) = pack4(x2);
;               }
.LBB0_446:
	s_or_b64 exec, exec, s[2:3]
	v_add_u32_e32 v84, s96, v84
	v_mov_b64_e32 v[72:73], s[34:35]
	v_mad_i64_i32 v[72:73], s[2:3], v84, s15, v[72:73]
	v_lshl_add_u64 v[72:73], v[162:163], 1, v[72:73]
	v_lshl_add_u64 v[72:73], v[72:73], 0, v[160:161]
	v_cvt_pk_bf16_f32 v76, v76, v77
	v_cvt_pk_bf16_f32 v77, v78, v79
	v_mov_b32_e32 v81, v80
	v_mov_b32_e32 v196, v76
	v_mov_b32_e32 v197, v77
	v_cvt_pk_bf16_f32 v76, v82, v83
	v_cvt_pk_bf16_f32 v77, v74, v75
	v_mov_b32_e32 v74, v80
	v_mov_b32_e32 v75, v80
	v_pk_mul_f32 v[70:71], v[70:71], v[74:75]
	v_pk_mul_f32 v[68:69], v[68:69], v[80:81]
	v_pk_mul_f32 v[66:67], v[66:67], v[74:75]
	v_pk_mul_f32 v[64:65], v[64:65], v[80:81]
	v_mov_b32_e32 v198, v76
	v_mov_b32_e32 v199, v77
	v_bfe_u32 v202, v252, 4, 1
	v_mul_u32_u24_e32 v202, 24, v202
	v_mov_b32_e32 v203, 0
	v_lshl_add_u64 v[200:201], v[72:73], 0, v[202:203]
	v_permlane16_swap_b32_e32 v196, v198
	v_permlane16_swap_b32_e32 v197, v199
	global_store_dwordx4 v[200:201], v[196:199], off
	s_nop 1
	s_and_saveexec_b64 s[2:3], s[4:5]
	s_cbranch_execz .LBB0_448
	s_waitcnt vmcnt(0)
	v_mul_f32_e32 v80, v101, v66
	v_mul_f32_e32 v82, v100, v66
	v_mov_b32_e32 v66, v71
	v_mov_b32_e32 v75, v90
	v_mov_b32_e32 v90, v89
	v_mul_f32_e32 v78, v100, v70
	v_mul_f32_e32 v84, v101, v70
	v_pk_mul_f32 v[86:87], v[102:103], v[66:67]
	v_mov_b32_e32 v70, v67
	v_mov_b32_e32 v74, v88
	v_pk_mul_f32 v[76:77], v[90:91], v[64:65]
	v_mov_b32_e32 v79, v86
	v_mov_b32_e32 v81, v87
	v_pk_mul_f32 v[66:67], v[102:103], v[70:71]
	v_pk_mul_f32 v[64:65], v[74:75], v[64:65]
	v_pk_fma_f32 v[74:75], v[74:75], v[68:69], v[76:77] neg_lo:[0,0,1] neg_hi:[0,0,1]
	v_pk_add_f32 v[76:77], v[78:79], v[80:81] neg_lo:[0,1] neg_hi:[0,1]
	v_mov_b32_e32 v85, v67
	v_mov_b32_e32 v83, v66
	v_pk_fma_f32 v[64:65], v[90:91], v[68:69], v[64:65]
	v_pk_add_f32 v[66:67], v[84:85], v[82:83]
	v_mov_b32_e32 v68, v74
	v_mov_b32_e32 v69, v75
	v_mov_b32_e32 v70, v76
	v_mov_b32_e32 v71, v77
.LBB0_448:
	s_or_b64 exec, exec, s[2:3]
	v_cvt_pk_bf16_f32 v68, v68, v69
	v_cvt_pk_bf16_f32 v69, v70, v71
	v_mov_b32_e32 v196, v68
	v_mov_b32_e32 v197, v69
	v_cvt_pk_bf16_f32 v64, v64, v65
	v_cvt_pk_bf16_f32 v65, v66, v67
	v_mov_b32_e32 v198, v64
	v_mov_b32_e32 v199, v65
	v_bfe_u32 v202, v252, 4, 1
	v_mul_u32_u24_e32 v202, 24, v202
	v_mov_b32_e32 v203, 0
	v_lshl_add_u64 v[200:201], v[72:73], 0, v[202:203]
	v_permlane16_swap_b32_e32 v196, v198
	v_permlane16_swap_b32_e32 v197, v199
	global_store_dwordx4 v[200:201], v[196:199], off offset:256
	s_nop 1
	s_waitcnt vmcnt(0)
	v_add_u32_e32 v100, 0x80, v172
	v_mov_b32_e32 v65, 0
	v_mov_b32_e32 v64, 1.0
	v_mov_b32_e32 v66, 1.0
	v_mov_b32_e32 v67, 0
	v_mov_b32_e32 v72, 1.0
	v_mov_b32_e32 v73, 0
	v_mov_b32_e32 v74, 1.0
	v_mov_b32_e32 v75, 0
	v_mov_b32_e32 v80, 1.0
	v_mov_b32_e32 v81, 0
	v_mov_b32_e32 v82, 1.0
	v_mov_b32_e32 v83, 0
	v_mov_b32_e32 v88, 1.0
	v_mov_b32_e32 v89, 0
	v_mov_b32_e32 v90, 1.0
	v_mov_b32_e32 v91, 0
	v_mov_b32_e32 v68, 1.0
	v_mov_b32_e32 v69, 0
	v_mov_b32_e32 v70, 1.0
	v_mov_b32_e32 v71, 0
	v_mov_b32_e32 v76, 1.0
	v_mov_b32_e32 v77, 0
	v_mov_b32_e32 v78, 1.0
	v_mov_b32_e32 v79, 0
	v_mov_b32_e32 v84, 1.0
	v_mov_b32_e32 v85, 0
	v_mov_b32_e32 v86, 1.0
	v_mov_b32_e32 v87, 0
	v_mov_b32_e32 v92, 1.0
	v_mov_b32_e32 v93, 0
	v_mov_b32_e32 v94, 1.0
	v_mov_b32_e32 v95, 0
	s_and_saveexec_b64 s[2:3], s[0:1]
	s_cbranch_execz .LBB0_450
	v_mul_hi_i32 v68, v100, s14
	v_lshrrev_b32_e32 v69, 31, v68
	v_ashrrev_i32_e32 v68, 7, v68
	v_add_u32_e32 v68, v68, v69
	v_mul_lo_u32 v68, v68, s77
	v_sub_u32_e32 v68, v100, v68
	v_readlane_b32 s0, v254, 29
	v_lshlrev_b32_e32 v68, 4, v68
	v_mov_b32_e32 v165, v161
	v_readlane_b32 s1, v254, 30
	v_ashrrev_i32_e32 v69, 31, v68
	v_lshl_add_u64 v[66:67], s[34:35], 0, v[164:165]
	v_lshl_add_u64 v[64:65], s[0:1], 0, v[164:165]
	v_lshlrev_b64 v[68:69], 3, v[68:69]
	v_lshl_add_u64 v[70:71], v[64:65], 0, v[68:69]
	v_lshl_add_u64 v[68:69], v[66:67], 0, v[68:69]
	s_mov_b32 s0, 0x2ec82000
	v_add_co_u32_e32 v68, vcc, s0, v68
	s_nop 1
	v_addc_co_u32_e32 v69, vcc, 0, v69, vcc
	global_load_dwordx4 v[88:91], v[70:71], off
	global_load_dwordx4 v[92:95], v[68:69], off offset:1040
	v_or_b32_e32 v68, 16, v100
	v_mul_hi_i32 v69, v68, s14
	v_lshrrev_b32_e32 v70, 31, v69
	v_ashrrev_i32_e32 v69, 7, v69
	v_add_u32_e32 v69, v69, v70
	v_mul_lo_u32 v69, v69, s77
	v_sub_u32_e32 v68, v68, v69
	v_lshlrev_b32_e32 v68, 4, v68
	v_ashrrev_i32_e32 v69, 31, v68
	v_lshlrev_b64 v[68:69], 3, v[68:69]
	v_lshl_add_u64 v[70:71], v[64:65], 0, v[68:69]
	v_lshl_add_u64 v[68:69], v[66:67], 0, v[68:69]
	v_add_co_u32_e32 v68, vcc, s0, v68
	s_nop 1
	v_addc_co_u32_e32 v69, vcc, 0, v69, vcc
	global_load_dwordx4 v[80:83], v[70:71], off
	global_load_dwordx4 v[84:87], v[68:69], off offset:1040
	v_or_b32_e32 v68, 32, v100
	v_mul_hi_i32 v69, v68, s14
	v_lshrrev_b32_e32 v70, 31, v69
	v_ashrrev_i32_e32 v69, 7, v69
	v_add_u32_e32 v69, v69, v70
	v_mul_lo_u32 v69, v69, s77
	v_sub_u32_e32 v68, v68, v69
	v_lshlrev_b32_e32 v68, 4, v68
	v_ashrrev_i32_e32 v69, 31, v68
	v_lshlrev_b64 v[68:69], 3, v[68:69]
	v_lshl_add_u64 v[70:71], v[64:65], 0, v[68:69]
	v_lshl_add_u64 v[68:69], v[66:67], 0, v[68:69]
	v_add_co_u32_e32 v68, vcc, s0, v68
	s_nop 1
	v_addc_co_u32_e32 v69, vcc, 0, v69, vcc
	global_load_dwordx4 v[72:75], v[70:71], off
	global_load_dwordx4 v[76:79], v[68:69], off offset:1040
	v_or_b32_e32 v68, 48, v100
	v_mul_hi_i32 v69, v68, s14
	v_lshrrev_b32_e32 v70, 31, v69
	v_ashrrev_i32_e32 v69, 7, v69
	v_add_u32_e32 v69, v69, v70
	v_mul_lo_u32 v69, v69, s77
	v_sub_u32_e32 v68, v68, v69
	v_lshlrev_b32_e32 v68, 4, v68
	v_ashrrev_i32_e32 v69, 31, v68
	v_lshlrev_b64 v[68:69], 3, v[68:69]
	v_lshl_add_u64 v[66:67], v[66:67], 0, v[68:69]
	v_lshl_add_u64 v[64:65], v[64:65], 0, v[68:69]
	v_add_co_u32_e32 v68, vcc, s0, v66
	s_nop 1
	v_addc_co_u32_e32 v69, vcc, 0, v67, vcc
	global_load_dwordx4 v[64:67], v[64:65], off
	s_nop 0
	global_load_dwordx4 v[68:71], v[68:69], off offset:1040

; #define p_rope W_(float2, OFF_ROPE)
; __device__ __forceinline__ u32x2 pack4(float a, float b, float c, float d) { return u32x2{cvtpk(a, b), cvtpk(c, d)}; }
; __device__ __forceinline__ u32x2 pack4(const f32x4& v) { return u32x2{cvtpk(v[0], v[1]), cvtpk(v[2], v[3])}; }
; #define SBAR() __builtin_amdgcn_sched_barrier(0)
; __global__ void __launch_bounds__(512) fwd_megakernel(Params p) {
;     ...
;           for (int ai = 0; ai < 2; ++ai) { SBAR();
;             f32x4 csa[4], csb[4];
;             if (rope0 || rope1) {
;               #pragma unroll
;               for (int m = 0; m < 4; ++m) {
;                 int pos = (brow + ai * 128 + wr * 64 + m * 16 + fr) % LTOK;
;                 csa[m] = *reinterpret_cast<const f32x4*>(p_rope + pos * 16 + fq * 4); csb[m] = *reinterpret_cast<const f32x4*>(p_rope + pos * 16 + fq * 4 + 2);
;               }
;             } else {
;               #pragma unroll
;               for (int m = 0; m < 4; ++m) { csa[m] = f32x4{1.f, 0.f, 1.f, 0.f}; csb[m] = csa[m]; }
;             }
;             SBAR();
;             #pragma unroll
;             for (int m = 0; m < 4; ++m) {
;               int lrow = ai * 128 + wr * 64 + m * 16 + fr, row = brow + lrow; float rs = xl[lrow];
;               const float cs_c[4] = {csa[m][0], csa[m][2], csb[m][0], csb[m][2]}, cs_s[4] = {csa[m][1], csa[m][3], csb[m][1], csb[m][3]};
;               #pragma unroll
;               for (int bj = 0; bj < 2; ++bj) {
;                 const int c0 = pn * 256 + bj * 128 + wc * 32; const bool isrope = bj ? rope1 : rope0;
;                 f32x4 x1 = acc[ai][bj][m][0] * rs, x2 = acc[ai][bj][m][1] * rs;
;                 if (isrope) {
;                   #pragma unroll
;                   for (int j = 0; j < 4; ++j) { float a1 = x1[j], a2 = x2[j]; x1[j] = a1 * cs_c[j] - a2 * cs_s[j]; x2[j] = a2 * cs_c[j] + a1 * cs_s[j]; }
;                 }
;                 bf16* qd = p_q + (long)row * 768 + c0 + fq * 4;
;                 *reinterpret_cast<u32x2*>(qd) = pack4(x1); *reinterpret_cast<u32x2*>(qd + 16) = pack4(x2);
;               }
.LBB0_452:
	s_or_b64 exec, exec, s[0:1]
	v_mov_b64_e32 v[56:57], s[34:35]
	v_mad_i64_i32 v[56:57], s[0:1], v100, s15, v[56:57]
	v_lshl_add_u64 v[56:57], v[162:163], 1, v[56:57]
	v_lshl_add_u64 v[56:57], v[56:57], 0, v[160:161]
	v_cvt_pk_bf16_f32 v60, v60, v61
	v_cvt_pk_bf16_f32 v61, v62, v63
	v_mov_b32_e32 v97, v96
	v_mov_b32_e32 v196, v60
	v_mov_b32_e32 v197, v61
	v_cvt_pk_bf16_f32 v60, v98, v99
	v_cvt_pk_bf16_f32 v61, v58, v59
	v_mov_b32_e32 v58, v96
	v_mov_b32_e32 v59, v96
	v_pk_mul_f32 v[54:55], v[54:55], v[58:59]
	v_pk_mul_f32 v[52:53], v[52:53], v[96:97]
	v_pk_mul_f32 v[50:51], v[50:51], v[58:59]
	v_pk_mul_f32 v[48:49], v[48:49], v[96:97]
	v_mov_b32_e32 v198, v60
	v_mov_b32_e32 v199, v61
	v_bfe_u32 v202, v252, 4, 1
	v_mul_u32_u24_e32 v202, 24, v202
	v_mov_b32_e32 v203, 0
	v_lshl_add_u64 v[200:201], v[56:57], 0, v[202:203]
	v_permlane16_swap_b32_e32 v196, v198
	v_permlane16_swap_b32_e32 v197, v199
	global_store_dwordx4 v[200:201], v[196:199], off
	s_nop 1
	s_and_saveexec_b64 s[0:1], s[4:5]
	s_cbranch_execz .LBB0_454
	s_waitcnt vmcnt(8)
	v_mov_b32_e32 v58, v88
	s_waitcnt vmcnt(7)
	v_mul_f32_e32 v62, v92, v54
	v_mul_f32_e32 v88, v93, v50
	v_mul_f32_e32 v92, v92, v50
	v_mov_b32_e32 v50, v55
	v_mov_b32_e32 v59, v90
	v_mov_b32_e32 v90, v89
	v_mul_f32_e32 v96, v93, v54
	v_pk_mul_f32 v[98:99], v[94:95], v[50:51]
	v_mov_b32_e32 v54, v51
	v_pk_mul_f32 v[60:61], v[90:91], v[48:49]
	v_mov_b32_e32 v63, v98
	v_mov_b32_e32 v89, v99
	v_pk_mul_f32 v[50:51], v[94:95], v[54:55]
	v_pk_mul_f32 v[48:49], v[58:59], v[48:49]
	v_pk_fma_f32 v[58:59], v[58:59], v[52:53], v[60:61] neg_lo:[0,0,1] neg_hi:[0,0,1]
	v_pk_add_f32 v[60:61], v[62:63], v[88:89] neg_lo:[0,1] neg_hi:[0,1]
	v_mov_b32_e32 v97, v51
	v_mov_b32_e32 v93, v50
	v_pk_fma_f32 v[48:49], v[90:91], v[52:53], v[48:49]
	v_pk_add_f32 v[50:51], v[96:97], v[92:93]
	v_mov_b32_e32 v52, v58
	v_mov_b32_e32 v53, v59
	v_mov_b32_e32 v54, v60
	v_mov_b32_e32 v55, v61
.LBB0_454:
	s_or_b64 exec, exec, s[0:1]
	v_cvt_pk_bf16_f32 v52, v52, v53
	v_cvt_pk_bf16_f32 v53, v54, v55
	v_mov_b32_e32 v196, v52
	v_mov_b32_e32 v197, v53
	v_cvt_pk_bf16_f32 v52, v48, v49
	v_cvt_pk_bf16_f32 v53, v50, v51
	ds_read_b32 v48, v173 offset:576
	v_mov_b32_e32 v198, v52
	v_mov_b32_e32 v199, v53
	v_bfe_u32 v202, v252, 4, 1
	v_mul_u32_u24_e32 v202, 24, v202
	v_mov_b32_e32 v203, 0
	v_lshl_add_u64 v[200:201], v[56:57], 0, v[202:203]
	v_permlane16_swap_b32_e32 v196, v198
	v_permlane16_swap_b32_e32 v197, v199
	global_store_dwordx4 v[200:201], v[196:199], off offset:256
	s_nop 1
	s_waitcnt lgkmcnt(0)
	v_pk_mul_f32 v[46:47], v[46:47], v[48:49] op_sel_hi:[1,0]
	v_pk_mul_f32 v[44:45], v[44:45], v[48:49] op_sel_hi:[1,0]
	v_pk_mul_f32 v[42:43], v[42:43], v[48:49] op_sel_hi:[1,0]
	v_pk_mul_f32 v[50:51], v[40:41], v[48:49] op_sel_hi:[1,0]
	s_and_saveexec_b64 s[0:1], s[6:7]
	s_cbranch_execz .LBB0_456
	s_waitcnt vmcnt(6)
	v_mul_f32_e32 v58, v85, v42
	v_mul_f32_e32 v60, v84, v42
	v_mov_b32_e32 v42, v47
	v_mov_b32_e32 v52, v81
	v_mov_b32_e32 v53, v83
	v_mul_f32_e32 v56, v84, v46
	v_mul_f32_e32 v62, v85, v46
	v_pk_mul_f32 v[88:89], v[86:87], v[42:43]
	v_mov_b32_e32 v46, v43
	v_mov_b32_e32 v40, v80
	v_mov_b32_e32 v41, v82
	v_pk_mul_f32 v[54:55], v[52:53], v[50:51]
	v_mov_b32_e32 v57, v88
	v_mov_b32_e32 v59, v89
	v_pk_mul_f32 v[42:43], v[86:87], v[46:47]
	v_pk_mul_f32 v[50:51], v[40:41], v[50:51]
	v_pk_fma_f32 v[40:41], v[40:41], v[44:45], v[54:55] neg_lo:[0,0,1] neg_hi:[0,0,1]
	v_pk_add_f32 v[54:55], v[56:57], v[58:59] neg_lo:[0,1] neg_hi:[0,1]
	v_mov_b32_e32 v63, v43
	v_mov_b32_e32 v61, v42
	v_pk_fma_f32 v[50:51], v[52:53], v[44:45], v[50:51]
	v_pk_add_f32 v[42:43], v[62:63], v[60:61]
	v_mov_b32_e32 v44, v40
	v_mov_b32_e32 v45, v41
	v_mov_b32_e32 v46, v54
	v_mov_b32_e32 v47, v55
.LBB0_456:
	s_or_b64 exec, exec, s[0:1]
	v_add_u32_e32 v52, 0x90, v172
	v_mov_b64_e32 v[40:41], s[34:35]
	v_mad_i64_i32 v[40:41], s[0:1], v52, s15, v[40:41]
	v_lshl_add_u64 v[40:41], v[162:163], 1, v[40:41]
	v_lshl_add_u64 v[40:41], v[40:41], 0, v[160:161]
	v_cvt_pk_bf16_f32 v44, v44, v45
	v_cvt_pk_bf16_f32 v45, v46, v47
	v_mov_b32_e32 v49, v48
	v_mov_b32_e32 v196, v44
	v_mov_b32_e32 v197, v45
	v_cvt_pk_bf16_f32 v44, v50, v51
	v_cvt_pk_bf16_f32 v45, v42, v43
	v_mov_b32_e32 v42, v48
	v_mov_b32_e32 v43, v48
	v_pk_mul_f32 v[38:39], v[38:39], v[42:43]
	v_pk_mul_f32 v[36:37], v[36:37], v[48:49]
	v_pk_mul_f32 v[34:35], v[34:35], v[42:43]
	v_pk_mul_f32 v[32:33], v[32:33], v[48:49]
	v_mov_b32_e32 v198, v44
	v_mov_b32_e32 v199, v45
	v_bfe_u32 v202, v252, 4, 1
	v_mul_u32_u24_e32 v202, 24, v202
	v_mov_b32_e32 v203, 0
	v_lshl_add_u64 v[200:201], v[40:41], 0, v[202:203]
	v_permlane16_swap_b32_e32 v196, v198
	v_permlane16_swap_b32_e32 v197, v199
	global_store_dwordx4 v[200:201], v[196:199], off
	s_nop 1
	s_and_saveexec_b64 s[0:1], s[4:5]
	s_cbranch_execz .LBB0_458
	s_waitcnt vmcnt(7)
	v_mul_f32_e32 v48, v85, v34
	v_mul_f32_e32 v50, v84, v34
	v_mov_b32_e32 v34, v39
	v_mov_b32_e32 v43, v82
	v_mov_b32_e32 v82, v81
	v_mul_f32_e32 v46, v84, v38
	v_mul_f32_e32 v52, v85, v38
	v_pk_mul_f32 v[54:55], v[86:87], v[34:35]
	v_mov_b32_e32 v38, v35
	v_mov_b32_e32 v42, v80
	v_pk_mul_f32 v[44:45], v[82:83], v[32:33]
	v_mov_b32_e32 v47, v54
	v_mov_b32_e32 v49, v55
	v_pk_mul_f32 v[34:35], v[86:87], v[38:39]
	v_pk_mul_f32 v[32:33], v[42:43], v[32:33]
	v_pk_fma_f32 v[42:43], v[42:43], v[36:37], v[44:45] neg_lo:[0,0,1] neg_hi:[0,0,1]
	v_pk_add_f32 v[44:45], v[46:47], v[48:49] neg_lo:[0,1] neg_hi:[0,1]
	v_mov_b32_e32 v53, v35
	v_mov_b32_e32 v51, v34
	v_pk_fma_f32 v[32:33], v[82:83], v[36:37], v[32:33]
	v_pk_add_f32 v[34:35], v[52:53], v[50:51]
	v_mov_b32_e32 v36, v42
	v_mov_b32_e32 v37, v43
	v_mov_b32_e32 v38, v44
	v_mov_b32_e32 v39, v45
; #define p_rope W_(float2, OFF_ROPE)
; __device__ __forceinline__ u32x2 pack4(float a, float b, float c, float d) { return u32x2{cvtpk(a, b), cvtpk(c, d)}; }
; __device__ __forceinline__ u32x2 pack4(const f32x4& v) { return u32x2{cvtpk(v[0], v[1]), cvtpk(v[2], v[3])}; }
; #define SBAR() __builtin_amdgcn_sched_barrier(0)
; __global__ void __launch_bounds__(512) fwd_megakernel(Params p) {
;     ...
;           for (int ai = 0; ai < 2; ++ai) { SBAR();
;             f32x4 csa[4], csb[4];
;             if (rope0 || rope1) {
;               #pragma unroll
;               for (int m = 0; m < 4; ++m) {
;                 int pos = (brow + ai * 128 + wr * 64 + m * 16 + fr) % LTOK;
;                 csa[m] = *reinterpret_cast<const f32x4*>(p_rope + pos * 16 + fq * 4); csb[m] = *reinterpret_cast<const f32x4*>(p_rope + pos * 16 + fq * 4 + 2);
;               }
;             } else {
;               #pragma unroll
;               for (int m = 0; m < 4; ++m) { csa[m] = f32x4{1.f, 0.f, 1.f, 0.f}; csb[m] = csa[m]; }
;             }
;             SBAR();
;             #pragma unroll
;             for (int m = 0; m < 4; ++m) {
;               int lrow = ai * 128 + wr * 64 + m * 16 + fr, row = brow + lrow; float rs = xl[lrow];
;               const float cs_c[4] = {csa[m][0], csa[m][2], csb[m][0], csb[m][2]}, cs_s[4] = {csa[m][1], csa[m][3], csb[m][1], csb[m][3]};
;               #pragma unroll
;               for (int bj = 0; bj < 2; ++bj) {
;                 const int c0 = pn * 256 + bj * 128 + wc * 32; const bool isrope = bj ? rope1 : rope0;
;                 f32x4 x1 = acc[ai][bj][m][0] * rs, x2 = acc[ai][bj][m][1] * rs;
;                 if (isrope) {
;                   #pragma unroll
;                   for (int j = 0; j < 4; ++j) { float a1 = x1[j], a2 = x2[j]; x1[j] = a1 * cs_c[j] - a2 * cs_s[j]; x2[j] = a2 * cs_c[j] + a1 * cs_s[j]; }
;                 }
;                 bf16* qd = p_q + (long)row * 768 + c0 + fq * 4;
;                 *reinterpret_cast<u32x2*>(qd) = pack4(x1); *reinterpret_cast<u32x2*>(qd + 16) = pack4(x2);
;               }
.LBB0_458:
	s_or_b64 exec, exec, s[0:1]
	v_cvt_pk_bf16_f32 v36, v36, v37
	v_cvt_pk_bf16_f32 v37, v38, v39
	v_mov_b32_e32 v196, v36
	v_mov_b32_e32 v197, v37
	v_cvt_pk_bf16_f32 v36, v32, v33
	v_cvt_pk_bf16_f32 v37, v34, v35
	ds_read_b32 v32, v173 offset:640
	v_mov_b32_e32 v198, v36
	v_mov_b32_e32 v199, v37
	v_bfe_u32 v202, v252, 4, 1
	v_mul_u32_u24_e32 v202, 24, v202
	v_mov_b32_e32 v203, 0
	v_lshl_add_u64 v[200:201], v[40:41], 0, v[202:203]
	v_permlane16_swap_b32_e32 v196, v198
	v_permlane16_swap_b32_e32 v197, v199
	global_store_dwordx4 v[200:201], v[196:199], off offset:256
	s_nop 1
	s_waitcnt lgkmcnt(0)
	v_pk_mul_f32 v[30:31], v[30:31], v[32:33] op_sel_hi:[1,0]
	v_pk_mul_f32 v[28:29], v[28:29], v[32:33] op_sel_hi:[1,0]
	v_pk_mul_f32 v[26:27], v[26:27], v[32:33] op_sel_hi:[1,0]
	v_pk_mul_f32 v[34:35], v[24:25], v[32:33] op_sel_hi:[1,0]
	s_and_saveexec_b64 s[0:1], s[6:7]
	s_cbranch_execz .LBB0_460
	s_waitcnt vmcnt(6)
	v_mul_f32_e32 v42, v77, v26
	v_mul_f32_e32 v44, v76, v26
	v_mov_b32_e32 v26, v31
	v_mov_b32_e32 v36, v73
	v_mov_b32_e32 v37, v75
	v_mul_f32_e32 v40, v76, v30
	v_mul_f32_e32 v46, v77, v30
	v_pk_mul_f32 v[48:49], v[78:79], v[26:27]
	v_mov_b32_e32 v30, v27
	v_mov_b32_e32 v24, v72
	v_mov_b32_e32 v25, v74
	v_pk_mul_f32 v[38:39], v[36:37], v[34:35]
	v_mov_b32_e32 v41, v48
	v_mov_b32_e32 v43, v49
	v_pk_mul_f32 v[26:27], v[78:79], v[30:31]
	v_pk_mul_f32 v[34:35], v[24:25], v[34:35]
	v_pk_fma_f32 v[24:25], v[24:25], v[28:29], v[38:39] neg_lo:[0,0,1] neg_hi:[0,0,1]
	v_pk_add_f32 v[38:39], v[40:41], v[42:43] neg_lo:[0,1] neg_hi:[0,1]
	v_mov_b32_e32 v47, v27
	v_mov_b32_e32 v45, v26
	v_pk_fma_f32 v[34:35], v[36:37], v[28:29], v[34:35]
	v_pk_add_f32 v[26:27], v[46:47], v[44:45]
	v_mov_b32_e32 v28, v24
	v_mov_b32_e32 v29, v25
	v_mov_b32_e32 v30, v38
	v_mov_b32_e32 v31, v39
.LBB0_460:
	s_or_b64 exec, exec, s[0:1]
	v_add_u32_e32 v36, 0xa0, v172
	v_mov_b64_e32 v[24:25], s[34:35]
	v_mad_i64_i32 v[24:25], s[0:1], v36, s15, v[24:25]
	v_lshl_add_u64 v[24:25], v[162:163], 1, v[24:25]
	v_lshl_add_u64 v[24:25], v[24:25], 0, v[160:161]
	v_cvt_pk_bf16_f32 v28, v28, v29
	v_cvt_pk_bf16_f32 v29, v30, v31
	v_mov_b32_e32 v33, v32
	v_mov_b32_e32 v196, v28
	v_mov_b32_e32 v197, v29
	v_cvt_pk_bf16_f32 v28, v34, v35
	v_cvt_pk_bf16_f32 v29, v26, v27
	v_mov_b32_e32 v26, v32
	v_mov_b32_e32 v27, v32
	v_pk_mul_f32 v[22:23], v[22:23], v[26:27]
	v_pk_mul_f32 v[20:21], v[20:21], v[32:33]
	v_pk_mul_f32 v[18:19], v[18:19], v[26:27]
	v_pk_mul_f32 v[16:17], v[16:17], v[32:33]
	v_mov_b32_e32 v198, v28
	v_mov_b32_e32 v199, v29
	v_bfe_u32 v202, v252, 4, 1
	v_mul_u32_u24_e32 v202, 24, v202
	v_mov_b32_e32 v203, 0
	v_lshl_add_u64 v[200:201], v[24:25], 0, v[202:203]
	v_permlane16_swap_b32_e32 v196, v198
	v_permlane16_swap_b32_e32 v197, v199
	global_store_dwordx4 v[200:201], v[196:199], off
	s_nop 1
	s_and_saveexec_b64 s[0:1], s[4:5]
	s_cbranch_execz .LBB0_462
	s_waitcnt vmcnt(7)
	v_mul_f32_e32 v32, v77, v18
	v_mul_f32_e32 v34, v76, v18
	v_mov_b32_e32 v18, v23
	v_mov_b32_e32 v27, v74
	v_mov_b32_e32 v74, v73
	v_mul_f32_e32 v30, v76, v22
	v_mul_f32_e32 v36, v77, v22
	v_pk_mul_f32 v[38:39], v[78:79], v[18:19]
	v_mov_b32_e32 v22, v19
	v_mov_b32_e32 v26, v72
	v_pk_mul_f32 v[28:29], v[74:75], v[16:17]
	v_mov_b32_e32 v31, v38
	v_mov_b32_e32 v33, v39
	v_pk_mul_f32 v[18:19], v[78:79], v[22:23]
	v_pk_mul_f32 v[16:17], v[26:27], v[16:17]
	v_pk_fma_f32 v[26:27], v[26:27], v[20:21], v[28:29] neg_lo:[0,0,1] neg_hi:[0,0,1]
	v_pk_add_f32 v[28:29], v[30:31], v[32:33] neg_lo:[0,1] neg_hi:[0,1]
	v_mov_b32_e32 v37, v19
	v_mov_b32_e32 v35, v18
	v_pk_fma_f32 v[16:17], v[74:75], v[20:21], v[16:17]
	v_pk_add_f32 v[18:19], v[36:37], v[34:35]
	v_mov_b32_e32 v20, v26
	v_mov_b32_e32 v21, v27
	v_mov_b32_e32 v22, v28
	v_mov_b32_e32 v23, v29
; #define p_rope W_(float2, OFF_ROPE)
; __device__ __forceinline__ u32x2 pack4(float a, float b, float c, float d) { return u32x2{cvtpk(a, b), cvtpk(c, d)}; }
; __device__ __forceinline__ u32x2 pack4(const f32x4& v) { return u32x2{cvtpk(v[0], v[1]), cvtpk(v[2], v[3])}; }
; #define SBAR() __builtin_amdgcn_sched_barrier(0)
; __global__ void __launch_bounds__(512) fwd_megakernel(Params p) {
;     ...
;           for (int ai = 0; ai < 2; ++ai) { SBAR();
;             f32x4 csa[4], csb[4];
;             if (rope0 || rope1) {
;               #pragma unroll
;               for (int m = 0; m < 4; ++m) {
;                 int pos = (brow + ai * 128 + wr * 64 + m * 16 + fr) % LTOK;
;                 csa[m] = *reinterpret_cast<const f32x4*>(p_rope + pos * 16 + fq * 4); csb[m] = *reinterpret_cast<const f32x4*>(p_rope + pos * 16 + fq * 4 + 2);
;               }
;             } else {
;               #pragma unroll
;               for (int m = 0; m < 4; ++m) { csa[m] = f32x4{1.f, 0.f, 1.f, 0.f}; csb[m] = csa[m]; }
;             }
;             SBAR();
;             #pragma unroll
;             for (int m = 0; m < 4; ++m) {
;               int lrow = ai * 128 + wr * 64 + m * 16 + fr, row = brow + lrow; float rs = xl[lrow];
;               const float cs_c[4] = {csa[m][0], csa[m][2], csb[m][0], csb[m][2]}, cs_s[4] = {csa[m][1], csa[m][3], csb[m][1], csb[m][3]};
;               #pragma unroll
;               for (int bj = 0; bj < 2; ++bj) {
;                 const int c0 = pn * 256 + bj * 128 + wc * 32; const bool isrope = bj ? rope1 : rope0;
;                 f32x4 x1 = acc[ai][bj][m][0] * rs, x2 = acc[ai][bj][m][1] * rs;
;                 if (isrope) {
;                   #pragma unroll
;                   for (int j = 0; j < 4; ++j) { float a1 = x1[j], a2 = x2[j]; x1[j] = a1 * cs_c[j] - a2 * cs_s[j]; x2[j] = a2 * cs_c[j] + a1 * cs_s[j]; }
;                 }
;                 bf16* qd = p_q + (long)row * 768 + c0 + fq * 4;
;                 *reinterpret_cast<u32x2*>(qd) = pack4(x1); *reinterpret_cast<u32x2*>(qd + 16) = pack4(x2);
;               }
.LBB0_462:
	s_or_b64 exec, exec, s[0:1]
	v_cvt_pk_bf16_f32 v20, v20, v21
	v_cvt_pk_bf16_f32 v21, v22, v23
	v_mov_b32_e32 v196, v20
	v_mov_b32_e32 v197, v21
	v_cvt_pk_bf16_f32 v20, v16, v17
	v_cvt_pk_bf16_f32 v21, v18, v19
	ds_read_b32 v16, v173 offset:704
	v_mov_b32_e32 v198, v20
	v_mov_b32_e32 v199, v21
	v_bfe_u32 v202, v252, 4, 1
	v_mul_u32_u24_e32 v202, 24, v202
	v_mov_b32_e32 v203, 0
	v_lshl_add_u64 v[200:201], v[24:25], 0, v[202:203]
	v_permlane16_swap_b32_e32 v196, v198
	v_permlane16_swap_b32_e32 v197, v199
	global_store_dwordx4 v[200:201], v[196:199], off offset:256
	s_nop 1
	s_waitcnt lgkmcnt(0)
	v_pk_mul_f32 v[14:15], v[14:15], v[16:17] op_sel_hi:[1,0]
	v_pk_mul_f32 v[12:13], v[12:13], v[16:17] op_sel_hi:[1,0]
	v_pk_mul_f32 v[10:11], v[10:11], v[16:17] op_sel_hi:[1,0]
	v_pk_mul_f32 v[18:19], v[8:9], v[16:17] op_sel_hi:[1,0]
	s_and_saveexec_b64 s[0:1], s[6:7]
	s_cbranch_execz .LBB0_464
	s_waitcnt vmcnt(6)
	v_mul_f32_e32 v26, v69, v10
	v_mul_f32_e32 v28, v68, v10
	v_mov_b32_e32 v10, v15
	v_mov_b32_e32 v20, v65
	v_mov_b32_e32 v21, v67
	v_mul_f32_e32 v24, v68, v14
	v_mul_f32_e32 v30, v69, v14
	v_pk_mul_f32 v[32:33], v[70:71], v[10:11]
	v_mov_b32_e32 v14, v11
	v_mov_b32_e32 v8, v64
	v_mov_b32_e32 v9, v66
	v_pk_mul_f32 v[22:23], v[20:21], v[18:19]
	v_mov_b32_e32 v25, v32
	v_mov_b32_e32 v27, v33
	v_pk_mul_f32 v[10:11], v[70:71], v[14:15]
	v_pk_mul_f32 v[18:19], v[8:9], v[18:19]
	v_pk_fma_f32 v[8:9], v[8:9], v[12:13], v[22:23] neg_lo:[0,0,1] neg_hi:[0,0,1]
	v_pk_add_f32 v[22:23], v[24:25], v[26:27] neg_lo:[0,1] neg_hi:[0,1]
	v_mov_b32_e32 v31, v11
	v_mov_b32_e32 v29, v10
	v_pk_fma_f32 v[18:19], v[20:21], v[12:13], v[18:19]
	v_pk_add_f32 v[10:11], v[30:31], v[28:29]
	v_mov_b32_e32 v12, v8
	v_mov_b32_e32 v13, v9
	v_mov_b32_e32 v14, v22
	v_mov_b32_e32 v15, v23
.LBB0_464:
	s_or_b64 exec, exec, s[0:1]
	v_add_u32_e32 v20, 0xb0, v172
	v_mov_b64_e32 v[8:9], s[34:35]
	v_mad_i64_i32 v[8:9], s[0:1], v20, s15, v[8:9]
	v_lshl_add_u64 v[8:9], v[162:163], 1, v[8:9]
	v_lshl_add_u64 v[8:9], v[8:9], 0, v[160:161]
	v_cvt_pk_bf16_f32 v12, v12, v13
	v_cvt_pk_bf16_f32 v13, v14, v15
	v_mov_b32_e32 v17, v16
	v_mov_b32_e32 v196, v12
	v_mov_b32_e32 v197, v13
	v_cvt_pk_bf16_f32 v12, v18, v19
	v_cvt_pk_bf16_f32 v13, v10, v11
	v_mov_b32_e32 v10, v16
	v_mov_b32_e32 v11, v16
	v_pk_mul_f32 v[6:7], v[6:7], v[10:11]
	v_pk_mul_f32 v[4:5], v[4:5], v[16:17]
	v_pk_mul_f32 v[2:3], v[2:3], v[10:11]
	v_pk_mul_f32 v[0:1], v[0:1], v[16:17]
	v_mov_b32_e32 v198, v12
	v_mov_b32_e32 v199, v13
	v_bfe_u32 v202, v252, 4, 1
	v_mul_u32_u24_e32 v202, 24, v202
	v_mov_b32_e32 v203, 0
	v_lshl_add_u64 v[200:201], v[8:9], 0, v[202:203]
	v_permlane16_swap_b32_e32 v196, v198
	v_permlane16_swap_b32_e32 v197, v199
	global_store_dwordx4 v[200:201], v[196:199], off
	s_nop 1
	s_and_saveexec_b64 s[0:1], s[4:5]
	s_cbranch_execz .LBB0_347
	s_waitcnt vmcnt(7)
	v_mul_f32_e32 v16, v69, v2
	v_mul_f32_e32 v18, v68, v2
	v_mov_b32_e32 v2, v7
	v_mov_b32_e32 v11, v66
	v_mov_b32_e32 v66, v65
	v_mul_f32_e32 v14, v68, v6
	v_mul_f32_e32 v20, v69, v6
	v_pk_mul_f32 v[22:23], v[70:71], v[2:3]
	v_mov_b32_e32 v6, v3
	v_mov_b32_e32 v10, v64
	v_pk_mul_f32 v[12:13], v[66:67], v[0:1]
	v_mov_b32_e32 v15, v22
	v_mov_b32_e32 v17, v23
	v_pk_mul_f32 v[2:3], v[70:71], v[6:7]
	v_pk_mul_f32 v[0:1], v[10:11], v[0:1]
	v_pk_fma_f32 v[10:11], v[10:11], v[4:5], v[12:13] neg_lo:[0,0,1] neg_hi:[0,0,1]
	v_pk_add_f32 v[12:13], v[14:15], v[16:17] neg_lo:[0,1] neg_hi:[0,1]
	v_mov_b32_e32 v21, v3
	v_mov_b32_e32 v19, v2
	v_pk_fma_f32 v[0:1], v[66:67], v[4:5], v[0:1]
	v_pk_add_f32 v[2:3], v[20:21], v[18:19]
	v_mov_b32_e32 v4, v10
	v_mov_b32_e32 v5, v11
	v_mov_b32_e32 v6, v12
	v_mov_b32_e32 v7, v13
	s_branch .LBB0_347
